# MFMA issue order within each 8-group changed to snake (one operand changes per step) in all GEMM K-loops: energy experiment
# baseline (speedup 1.0000x reference)
.LBB0_184:
	ds_read_b128 v[140:143], v147
	ds_read_b128 v[150:153], v147 offset:1024
	ds_read_b128 v[154:157], v147 offset:2048
	ds_read_b128 v[158:161], v147 offset:3072
	ds_read_b128 v[162:165], v148
	ds_read_b128 v[166:169], v148 offset:1024
	ds_read_b128 v[170:173], v148 offset:2048
	ds_read_b128 v[174:177], v148 offset:3072
	s_add_u32 s18, s44, 0xfffc0080
	s_addc_u32 s19, s45, -1
	s_cmp_eq_u32 s70, 12
	s_cselect_b32 s49, s13, s19
	s_cselect_b32 s48, s66, s18
	s_cselect_b32 s47, s11, s69
	s_cselect_b32 s46, s67, s68
	v_lshl_add_u64 v[178:179], s[44:45], 0, v[132:133]
	s_add_i32 m0, s37, 0xc000
	ds_read_b128 v[184:187], v149
	ds_read_b128 v[188:191], v149 offset:1024
	ds_read_b128 v[192:195], v149 offset:2048
	ds_read_b128 v[196:199], v149 offset:3072
	ds_read_b128 v[200:203], v149 offset:4096
	ds_read_b128 v[204:207], v149 offset:5120
	ds_read_b128 v[208:211], v149 offset:6144
	ds_read_b128 v[212:215], v149 offset:7168
	global_load_lds_dwordx4 v[178:179], off
	v_lshl_add_u64 v[178:179], s[44:45], 0, v[134:135]
	s_add_i32 m0, s37, 0xe000
	s_nop 0
	global_load_lds_dwordx4 v[178:179], off
	s_waitcnt vmcnt(8)
	s_waitcnt lgkmcnt(0)
	s_barrier
	s_setprio 1
	s_waitcnt lgkmcnt(0)
	v_mfma_f32_16x16x32_bf16 v[124:127], v[140:143], v[184:187], v[124:127]
	v_mfma_f32_16x16x32_bf16 v[120:123], v[154:157], v[184:187], v[120:123]
	v_mfma_f32_16x16x32_bf16 v[104:107], v[154:157], v[192:195], v[104:107]
	v_mfma_f32_16x16x32_bf16 v[108:111], v[140:143], v[192:195], v[108:111]
	v_mfma_f32_16x16x32_bf16 v[92:95], v[140:143], v[200:203], v[92:95]
	v_mfma_f32_16x16x32_bf16 v[88:91], v[154:157], v[200:203], v[88:91]
	v_mfma_f32_16x16x32_bf16 v[72:75], v[154:157], v[208:211], v[72:75]
	v_mfma_f32_16x16x32_bf16 v[76:79], v[140:143], v[208:211], v[76:79]
	v_mfma_f32_16x16x32_bf16 v[124:127], v[150:153], v[188:191], v[124:127]
	v_mfma_f32_16x16x32_bf16 v[120:123], v[158:161], v[188:191], v[120:123]
	v_mfma_f32_16x16x32_bf16 v[104:107], v[158:161], v[196:199], v[104:107]
	v_mfma_f32_16x16x32_bf16 v[108:111], v[150:153], v[196:199], v[108:111]
	v_mfma_f32_16x16x32_bf16 v[92:95], v[150:153], v[204:207], v[92:95]
	v_mfma_f32_16x16x32_bf16 v[88:91], v[158:161], v[204:207], v[88:91]
	v_mfma_f32_16x16x32_bf16 v[72:75], v[158:161], v[212:215], v[72:75]
	v_mfma_f32_16x16x32_bf16 v[76:79], v[150:153], v[212:215], v[76:79]
	s_setprio 0
	s_setprio 1
	v_mfma_f32_16x16x32_bf16 v[116:119], v[162:165], v[184:187], v[116:119]
	v_mfma_f32_16x16x32_bf16 v[112:115], v[170:173], v[184:187], v[112:115]
	v_mfma_f32_16x16x32_bf16 v[96:99], v[170:173], v[192:195], v[96:99]
	v_mfma_f32_16x16x32_bf16 v[100:103], v[162:165], v[192:195], v[100:103]
	v_mfma_f32_16x16x32_bf16 v[84:87], v[162:165], v[200:203], v[84:87]
	v_mfma_f32_16x16x32_bf16 v[80:83], v[170:173], v[200:203], v[80:83]
	v_mfma_f32_16x16x32_bf16 v[64:67], v[170:173], v[208:211], v[64:67]
	v_mfma_f32_16x16x32_bf16 v[68:71], v[162:165], v[208:211], v[68:71]
	v_mfma_f32_16x16x32_bf16 v[116:119], v[166:169], v[188:191], v[116:119]
	v_mfma_f32_16x16x32_bf16 v[112:115], v[174:177], v[188:191], v[112:115]
	v_mfma_f32_16x16x32_bf16 v[96:99], v[174:177], v[196:199], v[96:99]
	v_mfma_f32_16x16x32_bf16 v[100:103], v[166:169], v[196:199], v[100:103]
	v_mfma_f32_16x16x32_bf16 v[84:87], v[166:169], v[204:207], v[84:87]
	v_mfma_f32_16x16x32_bf16 v[80:83], v[174:177], v[204:207], v[80:83]
	v_mfma_f32_16x16x32_bf16 v[64:67], v[174:177], v[212:215], v[64:67]
	v_mfma_f32_16x16x32_bf16 v[68:71], v[166:169], v[212:215], v[68:71]
	s_setprio 0
	s_barrier
	s_add_i32 s18, s62, s54
	v_lshl_add_u64 v[178:179], s[46:47], 0, v[130:131]
	s_mov_b32 m0, s18
	ds_read_b128 v[184:187], v149 offset:16384
	ds_read_b128 v[188:191], v149 offset:17408
	ds_read_b128 v[192:195], v149 offset:18432
	ds_read_b128 v[196:199], v149 offset:19456
	ds_read_b128 v[200:203], v149 offset:20480
	ds_read_b128 v[204:207], v149 offset:21504
	ds_read_b128 v[208:211], v149 offset:22528
	ds_read_b128 v[212:215], v149 offset:23552
	global_load_lds_dwordx4 v[178:179], off
	s_add_i32 m0, s18, 0x2000
	s_add_u32 s72, s46, 0x40000
	v_lshl_add_u64 v[216:217], s[46:47], 0, v[128:129]
	s_addc_u32 s73, s47, 0
	s_add_i32 s18, s63, s54
	global_load_lds_dwordx4 v[216:217], off
	v_lshl_add_u64 v[218:219], s[72:73], 0, v[130:131]
	s_mov_b32 m0, s18
	v_lshl_add_u64 v[220:221], s[48:49], 0, v[128:129]
	global_load_lds_dwordx4 v[218:219], off
	v_lshl_add_u64 v[218:219], s[72:73], 0, v[128:129]
	s_add_i32 m0, s18, 0x2000
	s_nop 0
	global_load_lds_dwordx4 v[218:219], off
	v_lshl_add_u64 v[218:219], s[48:49], 0, v[130:131]
	s_mov_b32 m0, s37
	s_nop 0
	global_load_lds_dwordx4 v[218:219], off
	s_mov_b32 m0, s56
	s_nop 0
	global_load_lds_dwordx4 v[220:221], off
	s_waitcnt vmcnt(8)
	s_waitcnt lgkmcnt(0)
	s_barrier
	s_setprio 1
	s_waitcnt lgkmcnt(0)
	v_mfma_f32_16x16x32_bf16 v[60:63], v[140:143], v[184:187], v[60:63]
	v_mfma_f32_16x16x32_bf16 v[56:59], v[154:157], v[184:187], v[56:59]
	v_mfma_f32_16x16x32_bf16 v[40:43], v[154:157], v[192:195], v[40:43]
	v_mfma_f32_16x16x32_bf16 v[44:47], v[140:143], v[192:195], v[44:47]
	v_mfma_f32_16x16x32_bf16 v[28:31], v[140:143], v[200:203], v[28:31]
	v_mfma_f32_16x16x32_bf16 v[24:27], v[154:157], v[200:203], v[24:27]
	v_mfma_f32_16x16x32_bf16 v[8:11], v[154:157], v[208:211], v[8:11]
	v_mfma_f32_16x16x32_bf16 v[12:15], v[140:143], v[208:211], v[12:15]
	v_mfma_f32_16x16x32_bf16 v[60:63], v[150:153], v[188:191], v[60:63]
	v_mfma_f32_16x16x32_bf16 v[56:59], v[158:161], v[188:191], v[56:59]
	v_mfma_f32_16x16x32_bf16 v[40:43], v[158:161], v[196:199], v[40:43]
	v_mfma_f32_16x16x32_bf16 v[44:47], v[150:153], v[196:199], v[44:47]
	v_mfma_f32_16x16x32_bf16 v[28:31], v[150:153], v[204:207], v[28:31]
	v_mfma_f32_16x16x32_bf16 v[24:27], v[158:161], v[204:207], v[24:27]
	v_mfma_f32_16x16x32_bf16 v[8:11], v[158:161], v[212:215], v[8:11]
	v_mfma_f32_16x16x32_bf16 v[12:15], v[150:153], v[212:215], v[12:15]
	s_setprio 0
	s_setprio 1
	v_mfma_f32_16x16x32_bf16 v[52:55], v[162:165], v[184:187], v[52:55]
	v_mfma_f32_16x16x32_bf16 v[48:51], v[170:173], v[184:187], v[48:51]
	v_mfma_f32_16x16x32_bf16 v[32:35], v[170:173], v[192:195], v[32:35]
	v_mfma_f32_16x16x32_bf16 v[36:39], v[162:165], v[192:195], v[36:39]
	v_mfma_f32_16x16x32_bf16 v[20:23], v[162:165], v[200:203], v[20:23]
	v_mfma_f32_16x16x32_bf16 v[16:19], v[170:173], v[200:203], v[16:19]
	v_mfma_f32_16x16x32_bf16 v[0:3], v[170:173], v[208:211], v[0:3]
	v_mfma_f32_16x16x32_bf16 v[4:7], v[162:165], v[208:211], v[4:7]
	v_mfma_f32_16x16x32_bf16 v[52:55], v[166:169], v[188:191], v[52:55]
	v_mfma_f32_16x16x32_bf16 v[48:51], v[174:177], v[188:191], v[48:51]
	v_mfma_f32_16x16x32_bf16 v[32:35], v[174:177], v[196:199], v[32:35]
	v_mfma_f32_16x16x32_bf16 v[36:39], v[166:169], v[196:199], v[36:39]
	v_mfma_f32_16x16x32_bf16 v[20:23], v[166:169], v[204:207], v[20:23]
	v_mfma_f32_16x16x32_bf16 v[16:19], v[174:177], v[204:207], v[16:19]
	v_mfma_f32_16x16x32_bf16 v[0:3], v[174:177], v[212:215], v[0:3]
	v_mfma_f32_16x16x32_bf16 v[4:7], v[166:169], v[212:215], v[4:7]
	s_setprio 0
	s_barrier
	s_add_i32 s18, 0, 0x18000
	s_add_i32 s19, 0, 0x1c000
	v_add_u32_e32 v158, s18, v145
	v_add_u32_e32 v174, s19, v145
	ds_read_b128 v[140:143], v158
	ds_read_b128 v[150:153], v158 offset:1024
	ds_read_b128 v[154:157], v158 offset:2048
	ds_read_b128 v[158:161], v158 offset:3072
	ds_read_b128 v[162:165], v174
	ds_read_b128 v[166:169], v174 offset:1024
	ds_read_b128 v[170:173], v174 offset:2048
	ds_read_b128 v[174:177], v174 offset:3072
	s_add_u32 s48, s48, 0x40000
	s_addc_u32 s49, s49, 0
	s_mov_b32 m0, s57
	v_lshl_add_u64 v[222:223], s[48:49], 0, v[130:131]
	ds_read_b128 v[184:187], v149 offset:32768
	ds_read_b128 v[188:191], v149 offset:33792
	ds_read_b128 v[192:195], v149 offset:34816
	ds_read_b128 v[196:199], v149 offset:35840
	ds_read_b128 v[200:203], v149 offset:36864
	ds_read_b128 v[204:207], v149 offset:37888
	ds_read_b128 v[208:211], v149 offset:38912
	ds_read_b128 v[212:215], v149 offset:39936
	global_load_lds_dwordx4 v[222:223], off
	v_lshl_add_u64 v[222:223], s[48:49], 0, v[128:129]
	s_mov_b32 m0, s58
	s_nop 0
	global_load_lds_dwordx4 v[222:223], off
	s_waitcnt vmcnt(8)
	s_waitcnt lgkmcnt(0)
	s_barrier
	s_setprio 1
	s_waitcnt lgkmcnt(0)
	v_mfma_f32_16x16x32_bf16 v[124:127], v[140:143], v[184:187], v[124:127]
	v_mfma_f32_16x16x32_bf16 v[120:123], v[154:157], v[184:187], v[120:123]
	v_mfma_f32_16x16x32_bf16 v[104:107], v[154:157], v[192:195], v[104:107]
	v_mfma_f32_16x16x32_bf16 v[108:111], v[140:143], v[192:195], v[108:111]
	v_mfma_f32_16x16x32_bf16 v[92:95], v[140:143], v[200:203], v[92:95]
	v_mfma_f32_16x16x32_bf16 v[88:91], v[154:157], v[200:203], v[88:91]
	v_mfma_f32_16x16x32_bf16 v[72:75], v[154:157], v[208:211], v[72:75]
	v_mfma_f32_16x16x32_bf16 v[76:79], v[140:143], v[208:211], v[76:79]
	v_mfma_f32_16x16x32_bf16 v[124:127], v[150:153], v[188:191], v[124:127]
	v_mfma_f32_16x16x32_bf16 v[120:123], v[158:161], v[188:191], v[120:123]
	v_mfma_f32_16x16x32_bf16 v[104:107], v[158:161], v[196:199], v[104:107]
	v_mfma_f32_16x16x32_bf16 v[108:111], v[150:153], v[196:199], v[108:111]
	v_mfma_f32_16x16x32_bf16 v[92:95], v[150:153], v[204:207], v[92:95]
	v_mfma_f32_16x16x32_bf16 v[88:91], v[158:161], v[204:207], v[88:91]
	v_mfma_f32_16x16x32_bf16 v[72:75], v[158:161], v[212:215], v[72:75]
	v_mfma_f32_16x16x32_bf16 v[76:79], v[150:153], v[212:215], v[76:79]
	s_setprio 0
	s_setprio 1
	v_mfma_f32_16x16x32_bf16 v[116:119], v[162:165], v[184:187], v[116:119]
	v_mfma_f32_16x16x32_bf16 v[112:115], v[170:173], v[184:187], v[112:115]
	v_mfma_f32_16x16x32_bf16 v[96:99], v[170:173], v[192:195], v[96:99]
	v_mfma_f32_16x16x32_bf16 v[100:103], v[162:165], v[192:195], v[100:103]
	v_mfma_f32_16x16x32_bf16 v[84:87], v[162:165], v[200:203], v[84:87]
	v_mfma_f32_16x16x32_bf16 v[80:83], v[170:173], v[200:203], v[80:83]
	v_mfma_f32_16x16x32_bf16 v[64:67], v[170:173], v[208:211], v[64:67]
	v_mfma_f32_16x16x32_bf16 v[68:71], v[162:165], v[208:211], v[68:71]
	v_mfma_f32_16x16x32_bf16 v[116:119], v[166:169], v[188:191], v[116:119]
	v_mfma_f32_16x16x32_bf16 v[112:115], v[174:177], v[188:191], v[112:115]
	v_mfma_f32_16x16x32_bf16 v[96:99], v[174:177], v[196:199], v[96:99]
	v_mfma_f32_16x16x32_bf16 v[100:103], v[166:169], v[196:199], v[100:103]
	v_mfma_f32_16x16x32_bf16 v[84:87], v[166:169], v[204:207], v[84:87]
	v_mfma_f32_16x16x32_bf16 v[80:83], v[174:177], v[204:207], v[80:83]
	v_mfma_f32_16x16x32_bf16 v[64:67], v[174:177], v[212:215], v[64:67]
	v_mfma_f32_16x16x32_bf16 v[68:71], v[166:169], v[212:215], v[68:71]
	s_setprio 0
	s_barrier
	s_add_i32 s18, s18, s54
	v_lshl_add_u64 v[178:179], v[178:179], 0, s[6:7]
	s_mov_b32 m0, s18
	ds_read_b128 v[184:187], v149 offset:49152
	ds_read_b128 v[188:191], v149 offset:50176
	ds_read_b128 v[192:195], v149 offset:51200
	ds_read_b128 v[196:199], v149 offset:52224
	ds_read_b128 v[200:203], v149 offset:53248
	ds_read_b128 v[204:207], v149 offset:54272
	ds_read_b128 v[208:211], v149 offset:55296
	ds_read_b128 v[212:215], v149 offset:56320
	global_load_lds_dwordx4 v[178:179], off
	s_add_i32 m0, s18, 0x2000
	s_add_u32 s46, s46, 0x40080
	v_lshl_add_u64 v[178:179], v[216:217], 0, s[6:7]
	s_addc_u32 s47, s47, 0
	s_add_i32 s18, s19, s54
	global_load_lds_dwordx4 v[178:179], off
	v_lshl_add_u64 v[178:179], s[46:47], 0, v[130:131]
	s_mov_b32 m0, s18
	s_nop 0
	global_load_lds_dwordx4 v[178:179], off
	v_lshl_add_u64 v[178:179], s[46:47], 0, v[128:129]
	s_add_i32 m0, s18, 0x2000
	s_nop 0
	global_load_lds_dwordx4 v[178:179], off
	v_lshl_add_u64 v[178:179], v[218:219], 0, s[6:7]
	s_mov_b32 m0, s60
	s_nop 0
	global_load_lds_dwordx4 v[178:179], off
	v_lshl_add_u64 v[178:179], v[220:221], 0, s[6:7]
	s_mov_b32 m0, s61
	s_nop 0
	global_load_lds_dwordx4 v[178:179], off
	s_waitcnt vmcnt(8)
	s_waitcnt lgkmcnt(0)
	s_barrier
	s_setprio 1
	s_waitcnt lgkmcnt(0)
	v_mfma_f32_16x16x32_bf16 v[60:63], v[140:143], v[184:187], v[60:63]
	v_mfma_f32_16x16x32_bf16 v[56:59], v[154:157], v[184:187], v[56:59]
	v_mfma_f32_16x16x32_bf16 v[40:43], v[154:157], v[192:195], v[40:43]
	v_mfma_f32_16x16x32_bf16 v[44:47], v[140:143], v[192:195], v[44:47]
	v_mfma_f32_16x16x32_bf16 v[28:31], v[140:143], v[200:203], v[28:31]
	v_mfma_f32_16x16x32_bf16 v[24:27], v[154:157], v[200:203], v[24:27]
	v_mfma_f32_16x16x32_bf16 v[8:11], v[154:157], v[208:211], v[8:11]
	v_mfma_f32_16x16x32_bf16 v[12:15], v[140:143], v[208:211], v[12:15]
	v_mfma_f32_16x16x32_bf16 v[60:63], v[150:153], v[188:191], v[60:63]
	v_mfma_f32_16x16x32_bf16 v[56:59], v[158:161], v[188:191], v[56:59]
	v_mfma_f32_16x16x32_bf16 v[40:43], v[158:161], v[196:199], v[40:43]
	v_mfma_f32_16x16x32_bf16 v[44:47], v[150:153], v[196:199], v[44:47]
	v_mfma_f32_16x16x32_bf16 v[28:31], v[150:153], v[204:207], v[28:31]
	v_mfma_f32_16x16x32_bf16 v[24:27], v[158:161], v[204:207], v[24:27]
	v_mfma_f32_16x16x32_bf16 v[8:11], v[158:161], v[212:215], v[8:11]
	v_mfma_f32_16x16x32_bf16 v[12:15], v[150:153], v[212:215], v[12:15]
	s_setprio 0
	s_setprio 1
	v_mfma_f32_16x16x32_bf16 v[52:55], v[162:165], v[184:187], v[52:55]
	v_mfma_f32_16x16x32_bf16 v[48:51], v[170:173], v[184:187], v[48:51]
	v_mfma_f32_16x16x32_bf16 v[32:35], v[170:173], v[192:195], v[32:35]
	v_mfma_f32_16x16x32_bf16 v[36:39], v[162:165], v[192:195], v[36:39]
	v_mfma_f32_16x16x32_bf16 v[20:23], v[162:165], v[200:203], v[20:23]
	v_mfma_f32_16x16x32_bf16 v[16:19], v[170:173], v[200:203], v[16:19]
	v_mfma_f32_16x16x32_bf16 v[0:3], v[170:173], v[208:211], v[0:3]
	v_mfma_f32_16x16x32_bf16 v[4:7], v[162:165], v[208:211], v[4:7]
	v_mfma_f32_16x16x32_bf16 v[52:55], v[166:169], v[188:191], v[52:55]
	v_mfma_f32_16x16x32_bf16 v[48:51], v[174:177], v[188:191], v[48:51]
	v_mfma_f32_16x16x32_bf16 v[32:35], v[174:177], v[196:199], v[32:35]
	v_mfma_f32_16x16x32_bf16 v[36:39], v[166:169], v[196:199], v[36:39]
	v_mfma_f32_16x16x32_bf16 v[20:23], v[166:169], v[204:207], v[20:23]
	v_mfma_f32_16x16x32_bf16 v[16:19], v[174:177], v[204:207], v[16:19]
	v_mfma_f32_16x16x32_bf16 v[0:3], v[174:177], v[212:215], v[0:3]
	v_mfma_f32_16x16x32_bf16 v[4:7], v[166:169], v[212:215], v[4:7]
	s_setprio 0
	s_barrier
	s_add_i32 s70, s70, 2
	s_add_u32 s44, s44, 0x100
	s_addc_u32 s45, s45, 0
	s_add_u32 s68, s68, 0x100
	s_addc_u32 s69, s69, 0
	s_cmp_gt_u32 s70, 13
	s_cbranch_scc0 .LBB0_184
	s_and_b64 vcc, exec, s[8:9]
	s_cbranch_vccz .LBB0_187
	s_barrier

.LBB0_264:
	ds_read_b128 v[152:155], v149
	ds_read_b128 v[156:159], v149 offset:1024
	ds_read_b128 v[160:163], v149 offset:2048
	ds_read_b128 v[164:167], v149 offset:3072
	ds_read_b128 v[168:171], v150
	ds_read_b128 v[172:175], v150 offset:1024
	ds_read_b128 v[176:179], v150 offset:2048
	ds_read_b128 v[184:187], v150 offset:3072
	s_add_u32 s54, s52, 0x100
	s_addc_u32 s55, s53, 0
	s_cmp_eq_u32 s86, 40
	s_cselect_b32 s59, s7, s55
	s_cselect_b32 s58, s6, s54
	s_cselect_b32 s57, s49, s85
	s_cselect_b32 s56, s48, s84
	v_lshl_add_u64 v[144:145], s[52:53], 0, v[136:137]
	s_add_i32 m0, s63, 0xc000
	ds_read_b128 v[188:191], v151
	ds_read_b128 v[192:195], v151 offset:1024
	ds_read_b128 v[196:199], v151 offset:2048
	ds_read_b128 v[200:203], v151 offset:3072
	ds_read_b128 v[204:207], v151 offset:4096
	ds_read_b128 v[208:211], v151 offset:5120
	ds_read_b128 v[212:215], v151 offset:6144
	ds_read_b128 v[216:219], v151 offset:7168
	global_load_lds_dwordx4 v[144:145], off
	v_lshl_add_u64 v[144:145], s[52:53], 0, v[138:139]
	s_add_i32 m0, s63, 0xe000
	s_nop 0
	global_load_lds_dwordx4 v[144:145], off
	s_waitcnt vmcnt(8)
	s_waitcnt lgkmcnt(0)
	s_barrier
	s_setprio 1
	s_waitcnt lgkmcnt(0)
	v_mfma_f32_16x16x32_bf16 v[124:127], v[152:155], v[188:191], v[124:127]
	v_mfma_f32_16x16x32_bf16 v[120:123], v[160:163], v[188:191], v[120:123]
	v_mfma_f32_16x16x32_bf16 v[108:111], v[160:163], v[196:199], v[108:111]
	v_mfma_f32_16x16x32_bf16 v[116:119], v[152:155], v[196:199], v[116:119]
	v_mfma_f32_16x16x32_bf16 v[100:103], v[152:155], v[204:207], v[100:103]
	v_mfma_f32_16x16x32_bf16 v[92:95], v[160:163], v[204:207], v[92:95]
	v_mfma_f32_16x16x32_bf16 v[76:79], v[160:163], v[212:215], v[76:79]
	v_mfma_f32_16x16x32_bf16 v[84:87], v[152:155], v[212:215], v[84:87]
	v_mfma_f32_16x16x32_bf16 v[124:127], v[156:159], v[192:195], v[124:127]
	v_mfma_f32_16x16x32_bf16 v[120:123], v[164:167], v[192:195], v[120:123]
	v_mfma_f32_16x16x32_bf16 v[108:111], v[164:167], v[200:203], v[108:111]
	v_mfma_f32_16x16x32_bf16 v[116:119], v[156:159], v[200:203], v[116:119]
	v_mfma_f32_16x16x32_bf16 v[100:103], v[156:159], v[208:211], v[100:103]
	v_mfma_f32_16x16x32_bf16 v[92:95], v[164:167], v[208:211], v[92:95]
	v_mfma_f32_16x16x32_bf16 v[76:79], v[164:167], v[216:219], v[76:79]
	v_mfma_f32_16x16x32_bf16 v[84:87], v[156:159], v[216:219], v[84:87]
	s_setprio 0
	s_setprio 1
	v_mfma_f32_16x16x32_bf16 v[112:115], v[168:171], v[188:191], v[112:115]
	v_mfma_f32_16x16x32_bf16 v[104:107], v[176:179], v[188:191], v[104:107]
	v_mfma_f32_16x16x32_bf16 v[88:91], v[176:179], v[196:199], v[88:91]
	v_mfma_f32_16x16x32_bf16 v[96:99], v[168:171], v[196:199], v[96:99]
	v_mfma_f32_16x16x32_bf16 v[80:83], v[168:171], v[204:207], v[80:83]
	v_mfma_f32_16x16x32_bf16 v[72:75], v[176:179], v[204:207], v[72:75]
	v_mfma_f32_16x16x32_bf16 v[64:67], v[176:179], v[212:215], v[64:67]
	v_mfma_f32_16x16x32_bf16 v[68:71], v[168:171], v[212:215], v[68:71]
	v_mfma_f32_16x16x32_bf16 v[112:115], v[172:175], v[192:195], v[112:115]
	v_mfma_f32_16x16x32_bf16 v[104:107], v[184:187], v[192:195], v[104:107]
	v_mfma_f32_16x16x32_bf16 v[88:91], v[184:187], v[200:203], v[88:91]
	v_mfma_f32_16x16x32_bf16 v[96:99], v[172:175], v[200:203], v[96:99]
	v_mfma_f32_16x16x32_bf16 v[80:83], v[172:175], v[208:211], v[80:83]
	v_mfma_f32_16x16x32_bf16 v[72:75], v[184:187], v[208:211], v[72:75]
	v_mfma_f32_16x16x32_bf16 v[64:67], v[184:187], v[216:219], v[64:67]
	v_mfma_f32_16x16x32_bf16 v[68:71], v[172:175], v[216:219], v[68:71]
	s_setprio 0
	s_barrier
	s_add_i32 s18, s70, s62
	v_lshl_add_u64 v[144:145], s[56:57], 0, v[130:131]
	s_mov_b32 m0, s18
	ds_read_b128 v[188:191], v151 offset:16384
	ds_read_b128 v[192:195], v151 offset:17408
	ds_read_b128 v[196:199], v151 offset:18432
	ds_read_b128 v[200:203], v151 offset:19456
	ds_read_b128 v[204:207], v151 offset:20480
	ds_read_b128 v[208:211], v151 offset:21504
	ds_read_b128 v[212:215], v151 offset:22528
	ds_read_b128 v[216:219], v151 offset:23552
	global_load_lds_dwordx4 v[144:145], off
	s_add_i32 m0, s18, 0x2000
	s_add_u32 s52, s56, 0xb0000
	v_lshl_add_u64 v[220:221], s[56:57], 0, v[134:135]
	s_addc_u32 s53, s57, 0
	s_add_i32 s18, s71, s62
	global_load_lds_dwordx4 v[220:221], off
	v_lshl_add_u64 v[222:223], s[52:53], 0, v[130:131]
	s_mov_b32 m0, s18
	v_lshl_add_u64 v[224:225], s[58:59], 0, v[132:133]
	global_load_lds_dwordx4 v[222:223], off
	v_lshl_add_u64 v[222:223], s[52:53], 0, v[134:135]
	s_add_i32 m0, s18, 0x2000
	s_nop 0
	global_load_lds_dwordx4 v[222:223], off
	v_lshl_add_u64 v[222:223], s[58:59], 0, v[128:129]
	s_mov_b32 m0, s63
	s_nop 0
	global_load_lds_dwordx4 v[222:223], off
	s_mov_b32 m0, s64
	s_nop 0
	global_load_lds_dwordx4 v[224:225], off
	s_waitcnt vmcnt(8)
	s_waitcnt lgkmcnt(0)
	s_barrier
	s_setprio 1
	s_waitcnt lgkmcnt(0)
	v_mfma_f32_16x16x32_bf16 v[60:63], v[152:155], v[188:191], v[60:63]
	v_mfma_f32_16x16x32_bf16 v[56:59], v[160:163], v[188:191], v[56:59]
	v_mfma_f32_16x16x32_bf16 v[44:47], v[160:163], v[196:199], v[44:47]
	v_mfma_f32_16x16x32_bf16 v[52:55], v[152:155], v[196:199], v[52:55]
	v_mfma_f32_16x16x32_bf16 v[36:39], v[152:155], v[204:207], v[36:39]
	v_mfma_f32_16x16x32_bf16 v[28:31], v[160:163], v[204:207], v[28:31]
	v_mfma_f32_16x16x32_bf16 v[12:15], v[160:163], v[212:215], v[12:15]
	v_mfma_f32_16x16x32_bf16 v[20:23], v[152:155], v[212:215], v[20:23]
	v_mfma_f32_16x16x32_bf16 v[60:63], v[156:159], v[192:195], v[60:63]
	v_mfma_f32_16x16x32_bf16 v[56:59], v[164:167], v[192:195], v[56:59]
	v_mfma_f32_16x16x32_bf16 v[44:47], v[164:167], v[200:203], v[44:47]
	v_mfma_f32_16x16x32_bf16 v[52:55], v[156:159], v[200:203], v[52:55]
	v_mfma_f32_16x16x32_bf16 v[36:39], v[156:159], v[208:211], v[36:39]
	v_mfma_f32_16x16x32_bf16 v[28:31], v[164:167], v[208:211], v[28:31]
	v_mfma_f32_16x16x32_bf16 v[12:15], v[164:167], v[216:219], v[12:15]
	v_mfma_f32_16x16x32_bf16 v[20:23], v[156:159], v[216:219], v[20:23]
	s_setprio 0
	s_setprio 1
	v_mfma_f32_16x16x32_bf16 v[48:51], v[168:171], v[188:191], v[48:51]
	v_mfma_f32_16x16x32_bf16 v[40:43], v[176:179], v[188:191], v[40:43]
	v_mfma_f32_16x16x32_bf16 v[24:27], v[176:179], v[196:199], v[24:27]
	v_mfma_f32_16x16x32_bf16 v[32:35], v[168:171], v[196:199], v[32:35]
	v_mfma_f32_16x16x32_bf16 v[16:19], v[168:171], v[204:207], v[16:19]
	v_mfma_f32_16x16x32_bf16 v[8:11], v[176:179], v[204:207], v[8:11]
	v_mfma_f32_16x16x32_bf16 v[0:3], v[176:179], v[212:215], v[0:3]
	v_mfma_f32_16x16x32_bf16 v[4:7], v[168:171], v[212:215], v[4:7]
	v_mfma_f32_16x16x32_bf16 v[48:51], v[172:175], v[192:195], v[48:51]
	v_mfma_f32_16x16x32_bf16 v[40:43], v[184:187], v[192:195], v[40:43]
	v_mfma_f32_16x16x32_bf16 v[24:27], v[184:187], v[200:203], v[24:27]
	v_mfma_f32_16x16x32_bf16 v[32:35], v[172:175], v[200:203], v[32:35]
	v_mfma_f32_16x16x32_bf16 v[16:19], v[172:175], v[208:211], v[16:19]
	v_mfma_f32_16x16x32_bf16 v[8:11], v[184:187], v[208:211], v[8:11]
	v_mfma_f32_16x16x32_bf16 v[0:3], v[184:187], v[216:219], v[0:3]
	v_mfma_f32_16x16x32_bf16 v[4:7], v[172:175], v[216:219], v[4:7]
	s_setprio 0
	s_barrier
	s_add_i32 s18, 0, 0x18000
	s_add_i32 s19, 0, 0x1c000
	v_add_u32_e32 v164, s18, v147
	v_add_u32_e32 v181, s19, v147
	ds_read_b128 v[152:155], v164
	ds_read_b128 v[156:159], v164 offset:1024
	ds_read_b128 v[160:163], v164 offset:2048
	ds_read_b128 v[164:167], v164 offset:3072
	ds_read_b128 v[168:171], v181
	ds_read_b128 v[172:175], v181 offset:1024
	ds_read_b128 v[176:179], v181 offset:2048
	ds_read_b128 v[184:187], v181 offset:3072
	s_add_u32 s52, s58, 0xb0000
	s_addc_u32 s53, s59, 0
	s_mov_b32 m0, s65
	v_lshl_add_u64 v[226:227], s[52:53], 0, v[128:129]
	ds_read_b128 v[188:191], v151 offset:32768
	ds_read_b128 v[192:195], v151 offset:33792
	ds_read_b128 v[196:199], v151 offset:34816
	ds_read_b128 v[200:203], v151 offset:35840
	ds_read_b128 v[204:207], v151 offset:36864
	ds_read_b128 v[208:211], v151 offset:37888
	ds_read_b128 v[212:215], v151 offset:38912
	ds_read_b128 v[216:219], v151 offset:39936
	global_load_lds_dwordx4 v[226:227], off
	v_lshl_add_u64 v[226:227], s[52:53], 0, v[132:133]
	s_mov_b32 m0, s66
	s_nop 0
	global_load_lds_dwordx4 v[226:227], off
	s_waitcnt vmcnt(8)
	s_waitcnt lgkmcnt(0)
	s_barrier
	s_setprio 1
	s_waitcnt lgkmcnt(0)
	v_mfma_f32_16x16x32_bf16 v[124:127], v[152:155], v[188:191], v[124:127]
	v_mfma_f32_16x16x32_bf16 v[120:123], v[160:163], v[188:191], v[120:123]
	v_mfma_f32_16x16x32_bf16 v[108:111], v[160:163], v[196:199], v[108:111]
	v_mfma_f32_16x16x32_bf16 v[116:119], v[152:155], v[196:199], v[116:119]
	v_mfma_f32_16x16x32_bf16 v[100:103], v[152:155], v[204:207], v[100:103]
	v_mfma_f32_16x16x32_bf16 v[92:95], v[160:163], v[204:207], v[92:95]
	v_mfma_f32_16x16x32_bf16 v[76:79], v[160:163], v[212:215], v[76:79]
	v_mfma_f32_16x16x32_bf16 v[84:87], v[152:155], v[212:215], v[84:87]
	v_mfma_f32_16x16x32_bf16 v[124:127], v[156:159], v[192:195], v[124:127]
	v_mfma_f32_16x16x32_bf16 v[120:123], v[164:167], v[192:195], v[120:123]
	v_mfma_f32_16x16x32_bf16 v[108:111], v[164:167], v[200:203], v[108:111]
	v_mfma_f32_16x16x32_bf16 v[116:119], v[156:159], v[200:203], v[116:119]
	v_mfma_f32_16x16x32_bf16 v[100:103], v[156:159], v[208:211], v[100:103]
	v_mfma_f32_16x16x32_bf16 v[92:95], v[164:167], v[208:211], v[92:95]
	v_mfma_f32_16x16x32_bf16 v[76:79], v[164:167], v[216:219], v[76:79]
	v_mfma_f32_16x16x32_bf16 v[84:87], v[156:159], v[216:219], v[84:87]
	s_setprio 0
	s_setprio 1
	v_mfma_f32_16x16x32_bf16 v[112:115], v[168:171], v[188:191], v[112:115]
	v_mfma_f32_16x16x32_bf16 v[104:107], v[176:179], v[188:191], v[104:107]
	v_mfma_f32_16x16x32_bf16 v[88:91], v[176:179], v[196:199], v[88:91]
	v_mfma_f32_16x16x32_bf16 v[96:99], v[168:171], v[196:199], v[96:99]
	v_mfma_f32_16x16x32_bf16 v[80:83], v[168:171], v[204:207], v[80:83]
	v_mfma_f32_16x16x32_bf16 v[72:75], v[176:179], v[204:207], v[72:75]
	v_mfma_f32_16x16x32_bf16 v[64:67], v[176:179], v[212:215], v[64:67]
	v_mfma_f32_16x16x32_bf16 v[68:71], v[168:171], v[212:215], v[68:71]
	v_mfma_f32_16x16x32_bf16 v[112:115], v[172:175], v[192:195], v[112:115]
	v_mfma_f32_16x16x32_bf16 v[104:107], v[184:187], v[192:195], v[104:107]
	v_mfma_f32_16x16x32_bf16 v[88:91], v[184:187], v[200:203], v[88:91]
	v_mfma_f32_16x16x32_bf16 v[96:99], v[172:175], v[200:203], v[96:99]
	v_mfma_f32_16x16x32_bf16 v[80:83], v[172:175], v[208:211], v[80:83]
	v_mfma_f32_16x16x32_bf16 v[72:75], v[184:187], v[208:211], v[72:75]
	v_mfma_f32_16x16x32_bf16 v[64:67], v[184:187], v[216:219], v[64:67]
	v_mfma_f32_16x16x32_bf16 v[68:71], v[172:175], v[216:219], v[68:71]
	s_setprio 0
	s_barrier
	s_add_i32 s18, s18, s62
	v_lshl_add_u64 v[144:145], v[144:145], 0, s[8:9]
	s_mov_b32 m0, s18
	ds_read_b128 v[188:191], v151 offset:49152
	ds_read_b128 v[192:195], v151 offset:50176
	ds_read_b128 v[196:199], v151 offset:51200
	ds_read_b128 v[200:203], v151 offset:52224
	ds_read_b128 v[204:207], v151 offset:53248
	ds_read_b128 v[208:211], v151 offset:54272
	ds_read_b128 v[212:215], v151 offset:55296
	ds_read_b128 v[216:219], v151 offset:56320
	global_load_lds_dwordx4 v[144:145], off
	s_add_i32 m0, s18, 0x2000
	s_add_u32 s52, s56, 0xb0080
	v_lshl_add_u64 v[144:145], v[220:221], 0, s[8:9]
	s_addc_u32 s53, s57, 0
	s_add_i32 s18, s19, s62
	global_load_lds_dwordx4 v[144:145], off
	v_lshl_add_u64 v[144:145], s[52:53], 0, v[130:131]
	s_mov_b32 m0, s18
	s_nop 0
	global_load_lds_dwordx4 v[144:145], off
	v_lshl_add_u64 v[144:145], s[52:53], 0, v[134:135]
	s_add_i32 m0, s18, 0x2000
	s_nop 0
	global_load_lds_dwordx4 v[144:145], off
	v_lshl_add_u64 v[144:145], v[222:223], 0, s[8:9]
	s_mov_b32 m0, s68
	s_nop 0
	global_load_lds_dwordx4 v[144:145], off
	v_lshl_add_u64 v[144:145], v[224:225], 0, s[8:9]
	s_mov_b32 m0, s69
	s_nop 0
	global_load_lds_dwordx4 v[144:145], off
	s_waitcnt vmcnt(8)
	s_waitcnt lgkmcnt(0)
	s_barrier
	s_setprio 1
	s_waitcnt lgkmcnt(0)
	v_mfma_f32_16x16x32_bf16 v[60:63], v[152:155], v[188:191], v[60:63]
	v_mfma_f32_16x16x32_bf16 v[56:59], v[160:163], v[188:191], v[56:59]
	v_mfma_f32_16x16x32_bf16 v[44:47], v[160:163], v[196:199], v[44:47]
	v_mfma_f32_16x16x32_bf16 v[52:55], v[152:155], v[196:199], v[52:55]
	v_mfma_f32_16x16x32_bf16 v[36:39], v[152:155], v[204:207], v[36:39]
	v_mfma_f32_16x16x32_bf16 v[28:31], v[160:163], v[204:207], v[28:31]
	v_mfma_f32_16x16x32_bf16 v[12:15], v[160:163], v[212:215], v[12:15]
	v_mfma_f32_16x16x32_bf16 v[20:23], v[152:155], v[212:215], v[20:23]
	v_mfma_f32_16x16x32_bf16 v[60:63], v[156:159], v[192:195], v[60:63]
	v_mfma_f32_16x16x32_bf16 v[56:59], v[164:167], v[192:195], v[56:59]
	v_mfma_f32_16x16x32_bf16 v[44:47], v[164:167], v[200:203], v[44:47]
	v_mfma_f32_16x16x32_bf16 v[52:55], v[156:159], v[200:203], v[52:55]
	v_mfma_f32_16x16x32_bf16 v[36:39], v[156:159], v[208:211], v[36:39]
	v_mfma_f32_16x16x32_bf16 v[28:31], v[164:167], v[208:211], v[28:31]
	v_mfma_f32_16x16x32_bf16 v[12:15], v[164:167], v[216:219], v[12:15]
	v_mfma_f32_16x16x32_bf16 v[20:23], v[156:159], v[216:219], v[20:23]
	s_setprio 0
	s_setprio 1
	v_mfma_f32_16x16x32_bf16 v[48:51], v[168:171], v[188:191], v[48:51]
	v_mfma_f32_16x16x32_bf16 v[40:43], v[176:179], v[188:191], v[40:43]
	v_mfma_f32_16x16x32_bf16 v[24:27], v[176:179], v[196:199], v[24:27]
	v_mfma_f32_16x16x32_bf16 v[32:35], v[168:171], v[196:199], v[32:35]
	v_mfma_f32_16x16x32_bf16 v[16:19], v[168:171], v[204:207], v[16:19]
	v_mfma_f32_16x16x32_bf16 v[8:11], v[176:179], v[204:207], v[8:11]
	v_mfma_f32_16x16x32_bf16 v[0:3], v[176:179], v[212:215], v[0:3]
	v_mfma_f32_16x16x32_bf16 v[4:7], v[168:171], v[212:215], v[4:7]
	v_mfma_f32_16x16x32_bf16 v[48:51], v[172:175], v[192:195], v[48:51]
	v_mfma_f32_16x16x32_bf16 v[40:43], v[184:187], v[192:195], v[40:43]
	v_mfma_f32_16x16x32_bf16 v[24:27], v[184:187], v[200:203], v[24:27]
	v_mfma_f32_16x16x32_bf16 v[32:35], v[172:175], v[200:203], v[32:35]
	v_mfma_f32_16x16x32_bf16 v[16:19], v[172:175], v[208:211], v[16:19]
	v_mfma_f32_16x16x32_bf16 v[8:11], v[184:187], v[208:211], v[8:11]
	v_mfma_f32_16x16x32_bf16 v[0:3], v[184:187], v[216:219], v[0:3]
	v_mfma_f32_16x16x32_bf16 v[4:7], v[172:175], v[216:219], v[4:7]
	s_setprio 0
	s_barrier
	s_add_i32 s86, s86, 2
	s_add_u32 s84, s84, 0x100
	s_addc_u32 s85, s85, 0
	s_cmp_gt_u32 s86, 41
	s_mov_b64 s[52:53], s[54:55]
	s_cbranch_scc0 .LBB0_264
	s_and_b64 vcc, exec, s[10:11]
	s_cbranch_vccz .LBB0_267
	s_barrier

.LBB0_387:
	ds_read_b128 v[152:155], v148
	ds_read_b128 v[156:159], v148 offset:1024
	ds_read_b128 v[160:163], v148 offset:2048
	ds_read_b128 v[164:167], v148 offset:3072
	ds_read_b128 v[168:171], v149
	ds_read_b128 v[172:175], v149 offset:1024
	ds_read_b128 v[176:179], v149 offset:2048
	ds_read_b128 v[184:187], v149 offset:3072
	s_add_u32 s18, s58, 0xfffc0080
	s_addc_u32 s19, s59, -1
	s_cmp_eq_u32 s86, 12
	s_cselect_b32 s63, s49, s19
	s_cselect_b32 s62, s82, s18
	s_cselect_b32 s61, s47, s85
	s_cselect_b32 s60, s83, s84
	v_lshl_add_u64 v[220:221], s[58:59], 0, v[138:139]
	s_add_i32 m0, s68, 0xc000
	ds_read_b128 v[188:191], v150
	ds_read_b128 v[192:195], v150 offset:1024
	ds_read_b128 v[196:199], v150 offset:2048
	ds_read_b128 v[200:203], v150 offset:3072
	ds_read_b128 v[204:207], v150 offset:4096
	ds_read_b128 v[208:211], v150 offset:5120
	ds_read_b128 v[212:215], v150 offset:6144
	ds_read_b128 v[216:219], v150 offset:7168
	global_load_lds_dwordx4 v[220:221], off
	v_lshl_add_u64 v[220:221], s[58:59], 0, v[140:141]
	s_add_i32 m0, s68, 0xe000
	s_nop 0
	global_load_lds_dwordx4 v[220:221], off
	s_waitcnt vmcnt(8)
	s_waitcnt lgkmcnt(0)
	s_barrier
	s_setprio 1
	s_waitcnt lgkmcnt(0)
	v_mfma_f32_16x16x32_bf16 v[124:127], v[152:155], v[188:191], v[124:127]
	v_mfma_f32_16x16x32_bf16 v[120:123], v[160:163], v[188:191], v[120:123]
	v_mfma_f32_16x16x32_bf16 v[112:115], v[160:163], v[196:199], v[112:115]
	v_mfma_f32_16x16x32_bf16 v[116:119], v[152:155], v[196:199], v[116:119]
	v_mfma_f32_16x16x32_bf16 v[108:111], v[152:155], v[204:207], v[108:111]
	v_mfma_f32_16x16x32_bf16 v[104:107], v[160:163], v[204:207], v[104:107]
	v_mfma_f32_16x16x32_bf16 v[96:99], v[160:163], v[212:215], v[96:99]
	v_mfma_f32_16x16x32_bf16 v[100:103], v[152:155], v[212:215], v[100:103]
	v_mfma_f32_16x16x32_bf16 v[124:127], v[156:159], v[192:195], v[124:127]
	v_mfma_f32_16x16x32_bf16 v[120:123], v[164:167], v[192:195], v[120:123]
	v_mfma_f32_16x16x32_bf16 v[112:115], v[164:167], v[200:203], v[112:115]
	v_mfma_f32_16x16x32_bf16 v[116:119], v[156:159], v[200:203], v[116:119]
	v_mfma_f32_16x16x32_bf16 v[108:111], v[156:159], v[208:211], v[108:111]
	v_mfma_f32_16x16x32_bf16 v[104:107], v[164:167], v[208:211], v[104:107]
	v_mfma_f32_16x16x32_bf16 v[96:99], v[164:167], v[216:219], v[96:99]
	v_mfma_f32_16x16x32_bf16 v[100:103], v[156:159], v[216:219], v[100:103]
	s_setprio 0
	s_setprio 1
	v_mfma_f32_16x16x32_bf16 v[68:71], v[168:171], v[188:191], v[68:71]
	v_mfma_f32_16x16x32_bf16 v[64:67], v[176:179], v[188:191], v[64:67]
	v_mfma_f32_16x16x32_bf16 v[48:51], v[176:179], v[196:199], v[48:51]
	v_mfma_f32_16x16x32_bf16 v[52:55], v[168:171], v[196:199], v[52:55]
	v_mfma_f32_16x16x32_bf16 v[44:47], v[168:171], v[204:207], v[44:47]
	v_mfma_f32_16x16x32_bf16 v[40:43], v[176:179], v[204:207], v[40:43]
	v_mfma_f32_16x16x32_bf16 v[32:35], v[176:179], v[212:215], v[32:35]
	v_mfma_f32_16x16x32_bf16 v[36:39], v[168:171], v[212:215], v[36:39]
	v_mfma_f32_16x16x32_bf16 v[68:71], v[172:175], v[192:195], v[68:71]
	v_mfma_f32_16x16x32_bf16 v[64:67], v[184:187], v[192:195], v[64:67]
	v_mfma_f32_16x16x32_bf16 v[48:51], v[184:187], v[200:203], v[48:51]
	v_mfma_f32_16x16x32_bf16 v[52:55], v[172:175], v[200:203], v[52:55]
	v_mfma_f32_16x16x32_bf16 v[44:47], v[172:175], v[208:211], v[44:47]
	v_mfma_f32_16x16x32_bf16 v[40:43], v[184:187], v[208:211], v[40:43]
	v_mfma_f32_16x16x32_bf16 v[32:35], v[184:187], v[216:219], v[32:35]
	v_mfma_f32_16x16x32_bf16 v[36:39], v[172:175], v[216:219], v[36:39]
	s_setprio 0
	s_barrier
	s_add_i32 s18, s76, s66
	v_lshl_add_u64 v[220:221], s[60:61], 0, v[132:133]
	s_mov_b32 m0, s18
	ds_read_b128 v[188:191], v150 offset:16384
	ds_read_b128 v[192:195], v150 offset:17408
	ds_read_b128 v[196:199], v150 offset:18432
	ds_read_b128 v[200:203], v150 offset:19456
	ds_read_b128 v[204:207], v150 offset:20480
	ds_read_b128 v[208:211], v150 offset:21504
	ds_read_b128 v[212:215], v150 offset:22528
	ds_read_b128 v[216:219], v150 offset:23552
	global_load_lds_dwordx4 v[220:221], off
	s_add_i32 m0, s18, 0x2000
	s_add_u32 s88, s60, 0x40000
	v_lshl_add_u64 v[222:223], s[60:61], 0, v[128:129]
	s_addc_u32 s89, s61, 0
	s_add_i32 s18, s77, s66
	global_load_lds_dwordx4 v[222:223], off
	v_lshl_add_u64 v[224:225], s[88:89], 0, v[132:133]
	s_mov_b32 m0, s18
	v_lshl_add_u64 v[226:227], s[62:63], 0, v[130:131]
	global_load_lds_dwordx4 v[224:225], off
	v_lshl_add_u64 v[224:225], s[88:89], 0, v[128:129]
	s_add_i32 m0, s18, 0x2000
	s_nop 0
	global_load_lds_dwordx4 v[224:225], off
	v_lshl_add_u64 v[224:225], s[62:63], 0, v[134:135]
	s_mov_b32 m0, s68
	s_nop 0
	global_load_lds_dwordx4 v[224:225], off
	s_mov_b32 m0, s69
	s_nop 0
	global_load_lds_dwordx4 v[226:227], off
	s_waitcnt vmcnt(8)
	s_waitcnt lgkmcnt(0)
	s_barrier
	s_setprio 1
	s_waitcnt lgkmcnt(0)
	v_mfma_f32_16x16x32_bf16 v[92:95], v[152:155], v[188:191], v[92:95]
	v_mfma_f32_16x16x32_bf16 v[88:91], v[160:163], v[188:191], v[88:91]
	v_mfma_f32_16x16x32_bf16 v[80:83], v[160:163], v[196:199], v[80:83]
	v_mfma_f32_16x16x32_bf16 v[84:87], v[152:155], v[196:199], v[84:87]
	v_mfma_f32_16x16x32_bf16 v[76:79], v[152:155], v[204:207], v[76:79]
	v_mfma_f32_16x16x32_bf16 v[72:75], v[160:163], v[204:207], v[72:75]
	v_mfma_f32_16x16x32_bf16 v[56:59], v[160:163], v[212:215], v[56:59]
	v_mfma_f32_16x16x32_bf16 v[60:63], v[152:155], v[212:215], v[60:63]
	v_mfma_f32_16x16x32_bf16 v[92:95], v[156:159], v[192:195], v[92:95]
	v_mfma_f32_16x16x32_bf16 v[88:91], v[164:167], v[192:195], v[88:91]
	v_mfma_f32_16x16x32_bf16 v[80:83], v[164:167], v[200:203], v[80:83]
	v_mfma_f32_16x16x32_bf16 v[84:87], v[156:159], v[200:203], v[84:87]
	v_mfma_f32_16x16x32_bf16 v[76:79], v[156:159], v[208:211], v[76:79]
	v_mfma_f32_16x16x32_bf16 v[72:75], v[164:167], v[208:211], v[72:75]
	v_mfma_f32_16x16x32_bf16 v[56:59], v[164:167], v[216:219], v[56:59]
	v_mfma_f32_16x16x32_bf16 v[60:63], v[156:159], v[216:219], v[60:63]
	s_setprio 0
	s_setprio 1
	v_mfma_f32_16x16x32_bf16 v[28:31], v[168:171], v[188:191], v[28:31]
	v_mfma_f32_16x16x32_bf16 v[24:27], v[176:179], v[188:191], v[24:27]
	v_mfma_f32_16x16x32_bf16 v[16:19], v[176:179], v[196:199], v[16:19]
	v_mfma_f32_16x16x32_bf16 v[20:23], v[168:171], v[196:199], v[20:23]
	v_mfma_f32_16x16x32_bf16 v[12:15], v[168:171], v[204:207], v[12:15]
	v_mfma_f32_16x16x32_bf16 v[8:11], v[176:179], v[204:207], v[8:11]
	v_mfma_f32_16x16x32_bf16 v[0:3], v[176:179], v[212:215], v[0:3]
	v_mfma_f32_16x16x32_bf16 v[4:7], v[168:171], v[212:215], v[4:7]
	v_mfma_f32_16x16x32_bf16 v[28:31], v[172:175], v[192:195], v[28:31]
	v_mfma_f32_16x16x32_bf16 v[24:27], v[184:187], v[192:195], v[24:27]
	v_mfma_f32_16x16x32_bf16 v[16:19], v[184:187], v[200:203], v[16:19]
	v_mfma_f32_16x16x32_bf16 v[20:23], v[172:175], v[200:203], v[20:23]
	v_mfma_f32_16x16x32_bf16 v[12:15], v[172:175], v[208:211], v[12:15]
	v_mfma_f32_16x16x32_bf16 v[8:11], v[184:187], v[208:211], v[8:11]
	v_mfma_f32_16x16x32_bf16 v[0:3], v[184:187], v[216:219], v[0:3]
	v_mfma_f32_16x16x32_bf16 v[4:7], v[172:175], v[216:219], v[4:7]
	s_setprio 0
	s_barrier
	s_add_i32 s18, 0, 0x18000
	s_add_i32 s19, 0, 0x1c000
	v_add_u32_e32 v164, s18, v147
	v_add_u32_e32 v181, s19, v147
	ds_read_b128 v[152:155], v164
	ds_read_b128 v[156:159], v164 offset:1024
	ds_read_b128 v[160:163], v164 offset:2048
	ds_read_b128 v[164:167], v164 offset:3072
	ds_read_b128 v[168:171], v181
	ds_read_b128 v[172:175], v181 offset:1024
	ds_read_b128 v[176:179], v181 offset:2048
	ds_read_b128 v[184:187], v181 offset:3072
	s_add_u32 s62, s62, 0x40000
	s_addc_u32 s63, s63, 0
	s_mov_b32 m0, s70
	v_lshl_add_u64 v[228:229], s[62:63], 0, v[134:135]
	ds_read_b128 v[188:191], v150 offset:32768
	ds_read_b128 v[192:195], v150 offset:33792
	ds_read_b128 v[196:199], v150 offset:34816
	ds_read_b128 v[200:203], v150 offset:35840
	ds_read_b128 v[204:207], v150 offset:36864
	ds_read_b128 v[208:211], v150 offset:37888
	ds_read_b128 v[212:215], v150 offset:38912
	ds_read_b128 v[216:219], v150 offset:39936
	global_load_lds_dwordx4 v[228:229], off
	v_lshl_add_u64 v[228:229], s[62:63], 0, v[130:131]
	s_mov_b32 m0, s71
	s_nop 0
	global_load_lds_dwordx4 v[228:229], off
	s_waitcnt vmcnt(8)
	s_waitcnt lgkmcnt(0)
	s_barrier
	s_setprio 1
	s_waitcnt lgkmcnt(0)
	v_mfma_f32_16x16x32_bf16 v[124:127], v[152:155], v[188:191], v[124:127]
	v_mfma_f32_16x16x32_bf16 v[120:123], v[160:163], v[188:191], v[120:123]
	v_mfma_f32_16x16x32_bf16 v[112:115], v[160:163], v[196:199], v[112:115]
	v_mfma_f32_16x16x32_bf16 v[116:119], v[152:155], v[196:199], v[116:119]
	v_mfma_f32_16x16x32_bf16 v[108:111], v[152:155], v[204:207], v[108:111]
	v_mfma_f32_16x16x32_bf16 v[104:107], v[160:163], v[204:207], v[104:107]
	v_mfma_f32_16x16x32_bf16 v[96:99], v[160:163], v[212:215], v[96:99]
	v_mfma_f32_16x16x32_bf16 v[100:103], v[152:155], v[212:215], v[100:103]
	v_mfma_f32_16x16x32_bf16 v[124:127], v[156:159], v[192:195], v[124:127]
	v_mfma_f32_16x16x32_bf16 v[120:123], v[164:167], v[192:195], v[120:123]
	v_mfma_f32_16x16x32_bf16 v[112:115], v[164:167], v[200:203], v[112:115]
	v_mfma_f32_16x16x32_bf16 v[116:119], v[156:159], v[200:203], v[116:119]
	v_mfma_f32_16x16x32_bf16 v[108:111], v[156:159], v[208:211], v[108:111]
	v_mfma_f32_16x16x32_bf16 v[104:107], v[164:167], v[208:211], v[104:107]
	v_mfma_f32_16x16x32_bf16 v[96:99], v[164:167], v[216:219], v[96:99]
	v_mfma_f32_16x16x32_bf16 v[100:103], v[156:159], v[216:219], v[100:103]
	s_setprio 0
	s_setprio 1
	v_mfma_f32_16x16x32_bf16 v[68:71], v[168:171], v[188:191], v[68:71]
	v_mfma_f32_16x16x32_bf16 v[64:67], v[176:179], v[188:191], v[64:67]
	v_mfma_f32_16x16x32_bf16 v[48:51], v[176:179], v[196:199], v[48:51]
	v_mfma_f32_16x16x32_bf16 v[52:55], v[168:171], v[196:199], v[52:55]
	v_mfma_f32_16x16x32_bf16 v[44:47], v[168:171], v[204:207], v[44:47]
	v_mfma_f32_16x16x32_bf16 v[40:43], v[176:179], v[204:207], v[40:43]
	v_mfma_f32_16x16x32_bf16 v[32:35], v[176:179], v[212:215], v[32:35]
	v_mfma_f32_16x16x32_bf16 v[36:39], v[168:171], v[212:215], v[36:39]
	v_mfma_f32_16x16x32_bf16 v[68:71], v[172:175], v[192:195], v[68:71]
	v_mfma_f32_16x16x32_bf16 v[64:67], v[184:187], v[192:195], v[64:67]
	v_mfma_f32_16x16x32_bf16 v[48:51], v[184:187], v[200:203], v[48:51]
	v_mfma_f32_16x16x32_bf16 v[52:55], v[172:175], v[200:203], v[52:55]
	v_mfma_f32_16x16x32_bf16 v[44:47], v[172:175], v[208:211], v[44:47]
	v_mfma_f32_16x16x32_bf16 v[40:43], v[184:187], v[208:211], v[40:43]
	v_mfma_f32_16x16x32_bf16 v[32:35], v[184:187], v[216:219], v[32:35]
	v_mfma_f32_16x16x32_bf16 v[36:39], v[172:175], v[216:219], v[36:39]
	s_setprio 0
	s_barrier
	s_add_i32 s18, s18, s66
	v_lshl_add_u64 v[220:221], v[220:221], 0, s[6:7]
	s_mov_b32 m0, s18
	ds_read_b128 v[188:191], v150 offset:49152
	ds_read_b128 v[192:195], v150 offset:50176
	ds_read_b128 v[196:199], v150 offset:51200
	ds_read_b128 v[200:203], v150 offset:52224
	ds_read_b128 v[204:207], v150 offset:53248
	ds_read_b128 v[208:211], v150 offset:54272
	ds_read_b128 v[212:215], v150 offset:55296
	ds_read_b128 v[216:219], v150 offset:56320
	global_load_lds_dwordx4 v[220:221], off
	s_add_i32 m0, s18, 0x2000
	s_add_u32 s60, s60, 0x40080
	v_lshl_add_u64 v[220:221], v[222:223], 0, s[6:7]
	s_addc_u32 s61, s61, 0
	s_add_i32 s18, s19, s66
	global_load_lds_dwordx4 v[220:221], off
	v_lshl_add_u64 v[220:221], s[60:61], 0, v[132:133]
	s_mov_b32 m0, s18
	s_nop 0
	global_load_lds_dwordx4 v[220:221], off
	v_lshl_add_u64 v[220:221], s[60:61], 0, v[128:129]
	s_add_i32 m0, s18, 0x2000
	s_nop 0
	global_load_lds_dwordx4 v[220:221], off
	v_lshl_add_u64 v[220:221], v[224:225], 0, s[6:7]
	s_mov_b32 m0, s74
	s_nop 0
	global_load_lds_dwordx4 v[220:221], off
	v_lshl_add_u64 v[220:221], v[226:227], 0, s[6:7]
	s_mov_b32 m0, s75
	s_nop 0
	global_load_lds_dwordx4 v[220:221], off
	s_waitcnt vmcnt(8)
	s_waitcnt lgkmcnt(0)
	s_barrier
	s_setprio 1
	s_waitcnt lgkmcnt(0)
	v_mfma_f32_16x16x32_bf16 v[92:95], v[152:155], v[188:191], v[92:95]
	v_mfma_f32_16x16x32_bf16 v[88:91], v[160:163], v[188:191], v[88:91]
	v_mfma_f32_16x16x32_bf16 v[80:83], v[160:163], v[196:199], v[80:83]
	v_mfma_f32_16x16x32_bf16 v[84:87], v[152:155], v[196:199], v[84:87]
	v_mfma_f32_16x16x32_bf16 v[76:79], v[152:155], v[204:207], v[76:79]
	v_mfma_f32_16x16x32_bf16 v[72:75], v[160:163], v[204:207], v[72:75]
	v_mfma_f32_16x16x32_bf16 v[56:59], v[160:163], v[212:215], v[56:59]
	v_mfma_f32_16x16x32_bf16 v[60:63], v[152:155], v[212:215], v[60:63]
	v_mfma_f32_16x16x32_bf16 v[92:95], v[156:159], v[192:195], v[92:95]
	v_mfma_f32_16x16x32_bf16 v[88:91], v[164:167], v[192:195], v[88:91]
	v_mfma_f32_16x16x32_bf16 v[80:83], v[164:167], v[200:203], v[80:83]
	v_mfma_f32_16x16x32_bf16 v[84:87], v[156:159], v[200:203], v[84:87]
	v_mfma_f32_16x16x32_bf16 v[76:79], v[156:159], v[208:211], v[76:79]
	v_mfma_f32_16x16x32_bf16 v[72:75], v[164:167], v[208:211], v[72:75]
	v_mfma_f32_16x16x32_bf16 v[56:59], v[164:167], v[216:219], v[56:59]
	v_mfma_f32_16x16x32_bf16 v[60:63], v[156:159], v[216:219], v[60:63]
	s_setprio 0
	s_setprio 1
	v_mfma_f32_16x16x32_bf16 v[28:31], v[168:171], v[188:191], v[28:31]
	v_mfma_f32_16x16x32_bf16 v[24:27], v[176:179], v[188:191], v[24:27]
	v_mfma_f32_16x16x32_bf16 v[16:19], v[176:179], v[196:199], v[16:19]
	v_mfma_f32_16x16x32_bf16 v[20:23], v[168:171], v[196:199], v[20:23]
	v_mfma_f32_16x16x32_bf16 v[12:15], v[168:171], v[204:207], v[12:15]
	v_mfma_f32_16x16x32_bf16 v[8:11], v[176:179], v[204:207], v[8:11]
	v_mfma_f32_16x16x32_bf16 v[0:3], v[176:179], v[212:215], v[0:3]
	v_mfma_f32_16x16x32_bf16 v[4:7], v[168:171], v[212:215], v[4:7]
	v_mfma_f32_16x16x32_bf16 v[28:31], v[172:175], v[192:195], v[28:31]
	v_mfma_f32_16x16x32_bf16 v[24:27], v[184:187], v[192:195], v[24:27]
	v_mfma_f32_16x16x32_bf16 v[16:19], v[184:187], v[200:203], v[16:19]
	v_mfma_f32_16x16x32_bf16 v[20:23], v[172:175], v[200:203], v[20:23]
	v_mfma_f32_16x16x32_bf16 v[12:15], v[172:175], v[208:211], v[12:15]
	v_mfma_f32_16x16x32_bf16 v[8:11], v[184:187], v[208:211], v[8:11]
	v_mfma_f32_16x16x32_bf16 v[0:3], v[184:187], v[216:219], v[0:3]
	v_mfma_f32_16x16x32_bf16 v[4:7], v[172:175], v[216:219], v[4:7]
	s_setprio 0
	s_barrier
	s_add_i32 s86, s86, 2
	s_add_u32 s58, s58, 0x100
	s_addc_u32 s59, s59, 0
	s_add_u32 s84, s84, 0x100
	s_addc_u32 s85, s85, 0
	s_cmp_gt_u32 s86, 13
	s_cbranch_scc0 .LBB0_387
	s_and_b64 vcc, exec, s[8:9]
	s_cbranch_vccz .LBB0_390
	s_barrier

.LBB0_601:
	ds_read_b128 v[152:155], v149
	ds_read_b128 v[156:159], v149 offset:1024
	ds_read_b128 v[160:163], v149 offset:2048
	ds_read_b128 v[164:167], v149 offset:3072
	ds_read_b128 v[168:171], v150
	ds_read_b128 v[172:175], v150 offset:1024
	ds_read_b128 v[176:179], v150 offset:2048
	ds_read_b128 v[184:187], v150 offset:3072
	s_add_u32 s18, s58, 0xfffc0080
	s_addc_u32 s19, s59, -1
	s_cmp_eq_u32 s88, 12
	s_cselect_b32 s63, s49, s19
	s_cselect_b32 s62, s84, s18
	s_cselect_b32 s61, s47, s87
	s_cselect_b32 s60, s85, s86
	v_lshl_add_u64 v[144:145], s[58:59], 0, v[136:137]
	s_add_i32 m0, s57, 0xc000
	ds_read_b128 v[188:191], v151
	ds_read_b128 v[192:195], v151 offset:1024
	ds_read_b128 v[196:199], v151 offset:2048
	ds_read_b128 v[200:203], v151 offset:3072
	ds_read_b128 v[204:207], v151 offset:4096
	ds_read_b128 v[208:211], v151 offset:5120
	ds_read_b128 v[212:215], v151 offset:6144
	ds_read_b128 v[216:219], v151 offset:7168
	global_load_lds_dwordx4 v[144:145], off
	v_lshl_add_u64 v[144:145], s[58:59], 0, v[138:139]
	s_add_i32 m0, s57, 0xe000
	s_nop 0
	global_load_lds_dwordx4 v[144:145], off
	s_waitcnt vmcnt(8)
	s_waitcnt lgkmcnt(0)
	s_barrier
	s_setprio 1
	s_waitcnt lgkmcnt(0)
	v_mfma_f32_16x16x32_bf16 v[124:127], v[152:155], v[188:191], v[124:127]
	v_mfma_f32_16x16x32_bf16 v[120:123], v[160:163], v[188:191], v[120:123]
	v_mfma_f32_16x16x32_bf16 v[108:111], v[160:163], v[196:199], v[108:111]
	v_mfma_f32_16x16x32_bf16 v[116:119], v[152:155], v[196:199], v[116:119]
	v_mfma_f32_16x16x32_bf16 v[100:103], v[152:155], v[204:207], v[100:103]
	v_mfma_f32_16x16x32_bf16 v[92:95], v[160:163], v[204:207], v[92:95]
	v_mfma_f32_16x16x32_bf16 v[76:79], v[160:163], v[212:215], v[76:79]
	v_mfma_f32_16x16x32_bf16 v[84:87], v[152:155], v[212:215], v[84:87]
	v_mfma_f32_16x16x32_bf16 v[124:127], v[156:159], v[192:195], v[124:127]
	v_mfma_f32_16x16x32_bf16 v[120:123], v[164:167], v[192:195], v[120:123]
	v_mfma_f32_16x16x32_bf16 v[108:111], v[164:167], v[200:203], v[108:111]
	v_mfma_f32_16x16x32_bf16 v[116:119], v[156:159], v[200:203], v[116:119]
	v_mfma_f32_16x16x32_bf16 v[100:103], v[156:159], v[208:211], v[100:103]
	v_mfma_f32_16x16x32_bf16 v[92:95], v[164:167], v[208:211], v[92:95]
	v_mfma_f32_16x16x32_bf16 v[76:79], v[164:167], v[216:219], v[76:79]
	v_mfma_f32_16x16x32_bf16 v[84:87], v[156:159], v[216:219], v[84:87]
	s_setprio 0
	s_setprio 1
	v_mfma_f32_16x16x32_bf16 v[112:115], v[168:171], v[188:191], v[112:115]
	v_mfma_f32_16x16x32_bf16 v[104:107], v[176:179], v[188:191], v[104:107]
	v_mfma_f32_16x16x32_bf16 v[88:91], v[176:179], v[196:199], v[88:91]
	v_mfma_f32_16x16x32_bf16 v[96:99], v[168:171], v[196:199], v[96:99]
	v_mfma_f32_16x16x32_bf16 v[80:83], v[168:171], v[204:207], v[80:83]
	v_mfma_f32_16x16x32_bf16 v[72:75], v[176:179], v[204:207], v[72:75]
	v_mfma_f32_16x16x32_bf16 v[64:67], v[176:179], v[212:215], v[64:67]
	v_mfma_f32_16x16x32_bf16 v[68:71], v[168:171], v[212:215], v[68:71]
	v_mfma_f32_16x16x32_bf16 v[112:115], v[172:175], v[192:195], v[112:115]
	v_mfma_f32_16x16x32_bf16 v[104:107], v[184:187], v[192:195], v[104:107]
	v_mfma_f32_16x16x32_bf16 v[88:91], v[184:187], v[200:203], v[88:91]
	v_mfma_f32_16x16x32_bf16 v[96:99], v[172:175], v[200:203], v[96:99]
	v_mfma_f32_16x16x32_bf16 v[80:83], v[172:175], v[208:211], v[80:83]
	v_mfma_f32_16x16x32_bf16 v[72:75], v[184:187], v[208:211], v[72:75]
	v_mfma_f32_16x16x32_bf16 v[64:67], v[184:187], v[216:219], v[64:67]
	v_mfma_f32_16x16x32_bf16 v[68:71], v[172:175], v[216:219], v[68:71]
	s_setprio 0
	s_barrier
	s_add_i32 s18, s73, s66
	v_lshl_add_u64 v[144:145], s[60:61], 0, v[130:131]
	s_mov_b32 m0, s18
	ds_read_b128 v[188:191], v151 offset:16384
	ds_read_b128 v[192:195], v151 offset:17408
	ds_read_b128 v[196:199], v151 offset:18432
	ds_read_b128 v[200:203], v151 offset:19456
	ds_read_b128 v[204:207], v151 offset:20480
	ds_read_b128 v[208:211], v151 offset:21504
	ds_read_b128 v[212:215], v151 offset:22528
	ds_read_b128 v[216:219], v151 offset:23552
	global_load_lds_dwordx4 v[144:145], off
	s_add_i32 m0, s18, 0x2000
	s_add_u32 s18, s60, 0x40000
	v_lshl_add_u64 v[220:221], s[60:61], 0, v[134:135]
	s_addc_u32 s19, s61, 0
	s_add_i32 s79, s74, s66
	global_load_lds_dwordx4 v[220:221], off
	v_lshl_add_u64 v[222:223], s[18:19], 0, v[130:131]
	s_mov_b32 m0, s79
	v_lshl_add_u64 v[224:225], s[62:63], 0, v[132:133]
	global_load_lds_dwordx4 v[222:223], off
	v_lshl_add_u64 v[222:223], s[18:19], 0, v[134:135]
	s_add_i32 m0, s79, 0x2000
	s_nop 0
	global_load_lds_dwordx4 v[222:223], off
	v_lshl_add_u64 v[222:223], s[62:63], 0, v[128:129]
	s_mov_b32 m0, s57
	s_nop 0
	global_load_lds_dwordx4 v[222:223], off
	s_mov_b32 m0, s67
	s_nop 0
	global_load_lds_dwordx4 v[224:225], off
	s_waitcnt vmcnt(8)
	s_waitcnt lgkmcnt(0)
	s_barrier
	s_setprio 1
	s_waitcnt lgkmcnt(0)
	v_mfma_f32_16x16x32_bf16 v[60:63], v[152:155], v[188:191], v[60:63]
	v_mfma_f32_16x16x32_bf16 v[56:59], v[160:163], v[188:191], v[56:59]
	v_mfma_f32_16x16x32_bf16 v[44:47], v[160:163], v[196:199], v[44:47]
	v_mfma_f32_16x16x32_bf16 v[52:55], v[152:155], v[196:199], v[52:55]
	v_mfma_f32_16x16x32_bf16 v[36:39], v[152:155], v[204:207], v[36:39]
	v_mfma_f32_16x16x32_bf16 v[28:31], v[160:163], v[204:207], v[28:31]
	v_mfma_f32_16x16x32_bf16 v[12:15], v[160:163], v[212:215], v[12:15]
	v_mfma_f32_16x16x32_bf16 v[20:23], v[152:155], v[212:215], v[20:23]
	v_mfma_f32_16x16x32_bf16 v[60:63], v[156:159], v[192:195], v[60:63]
	v_mfma_f32_16x16x32_bf16 v[56:59], v[164:167], v[192:195], v[56:59]
	v_mfma_f32_16x16x32_bf16 v[44:47], v[164:167], v[200:203], v[44:47]
	v_mfma_f32_16x16x32_bf16 v[52:55], v[156:159], v[200:203], v[52:55]
	v_mfma_f32_16x16x32_bf16 v[36:39], v[156:159], v[208:211], v[36:39]
	v_mfma_f32_16x16x32_bf16 v[28:31], v[164:167], v[208:211], v[28:31]
	v_mfma_f32_16x16x32_bf16 v[12:15], v[164:167], v[216:219], v[12:15]
	v_mfma_f32_16x16x32_bf16 v[20:23], v[156:159], v[216:219], v[20:23]
	s_setprio 0
	s_setprio 1
	v_mfma_f32_16x16x32_bf16 v[48:51], v[168:171], v[188:191], v[48:51]
	v_mfma_f32_16x16x32_bf16 v[40:43], v[176:179], v[188:191], v[40:43]
	v_mfma_f32_16x16x32_bf16 v[24:27], v[176:179], v[196:199], v[24:27]
	v_mfma_f32_16x16x32_bf16 v[32:35], v[168:171], v[196:199], v[32:35]
	v_mfma_f32_16x16x32_bf16 v[16:19], v[168:171], v[204:207], v[16:19]
	v_mfma_f32_16x16x32_bf16 v[8:11], v[176:179], v[204:207], v[8:11]
	v_mfma_f32_16x16x32_bf16 v[0:3], v[176:179], v[212:215], v[0:3]
	v_mfma_f32_16x16x32_bf16 v[4:7], v[168:171], v[212:215], v[4:7]
	v_mfma_f32_16x16x32_bf16 v[48:51], v[172:175], v[192:195], v[48:51]
	v_mfma_f32_16x16x32_bf16 v[40:43], v[184:187], v[192:195], v[40:43]
	v_mfma_f32_16x16x32_bf16 v[24:27], v[184:187], v[200:203], v[24:27]
	v_mfma_f32_16x16x32_bf16 v[32:35], v[172:175], v[200:203], v[32:35]
	v_mfma_f32_16x16x32_bf16 v[16:19], v[172:175], v[208:211], v[16:19]
	v_mfma_f32_16x16x32_bf16 v[8:11], v[184:187], v[208:211], v[8:11]
	v_mfma_f32_16x16x32_bf16 v[0:3], v[184:187], v[216:219], v[0:3]
	v_mfma_f32_16x16x32_bf16 v[4:7], v[172:175], v[216:219], v[4:7]
	s_setprio 0
	s_barrier
	s_add_i32 s79, 0, 0x18000
	s_add_i32 s89, 0, 0x1c000
	v_add_u32_e32 v164, s79, v147
	v_add_u32_e32 v181, s89, v147
	ds_read_b128 v[152:155], v164
	ds_read_b128 v[156:159], v164 offset:1024
	ds_read_b128 v[160:163], v164 offset:2048
	ds_read_b128 v[164:167], v164 offset:3072
	ds_read_b128 v[168:171], v181
	ds_read_b128 v[172:175], v181 offset:1024
	ds_read_b128 v[176:179], v181 offset:2048
	ds_read_b128 v[184:187], v181 offset:3072
	s_add_u32 s18, s62, 0x40000
	s_addc_u32 s19, s63, 0
	s_mov_b32 m0, s68
	v_lshl_add_u64 v[226:227], s[18:19], 0, v[128:129]
	ds_read_b128 v[188:191], v151 offset:32768
	ds_read_b128 v[192:195], v151 offset:33792
	ds_read_b128 v[196:199], v151 offset:34816
	ds_read_b128 v[200:203], v151 offset:35840
	ds_read_b128 v[204:207], v151 offset:36864
	ds_read_b128 v[208:211], v151 offset:37888
	ds_read_b128 v[212:215], v151 offset:38912
	ds_read_b128 v[216:219], v151 offset:39936
	global_load_lds_dwordx4 v[226:227], off
	v_lshl_add_u64 v[226:227], s[18:19], 0, v[132:133]
	s_mov_b32 m0, s69
	s_nop 0
	global_load_lds_dwordx4 v[226:227], off
	s_waitcnt vmcnt(8)
	s_waitcnt lgkmcnt(0)
	s_barrier
	s_setprio 1
	s_waitcnt lgkmcnt(0)
	v_mfma_f32_16x16x32_bf16 v[124:127], v[152:155], v[188:191], v[124:127]
	v_mfma_f32_16x16x32_bf16 v[120:123], v[160:163], v[188:191], v[120:123]
	v_mfma_f32_16x16x32_bf16 v[108:111], v[160:163], v[196:199], v[108:111]
	v_mfma_f32_16x16x32_bf16 v[116:119], v[152:155], v[196:199], v[116:119]
	v_mfma_f32_16x16x32_bf16 v[100:103], v[152:155], v[204:207], v[100:103]
	v_mfma_f32_16x16x32_bf16 v[92:95], v[160:163], v[204:207], v[92:95]
	v_mfma_f32_16x16x32_bf16 v[76:79], v[160:163], v[212:215], v[76:79]
	v_mfma_f32_16x16x32_bf16 v[84:87], v[152:155], v[212:215], v[84:87]
	v_mfma_f32_16x16x32_bf16 v[124:127], v[156:159], v[192:195], v[124:127]
	v_mfma_f32_16x16x32_bf16 v[120:123], v[164:167], v[192:195], v[120:123]
	v_mfma_f32_16x16x32_bf16 v[108:111], v[164:167], v[200:203], v[108:111]
	v_mfma_f32_16x16x32_bf16 v[116:119], v[156:159], v[200:203], v[116:119]
	v_mfma_f32_16x16x32_bf16 v[100:103], v[156:159], v[208:211], v[100:103]
	v_mfma_f32_16x16x32_bf16 v[92:95], v[164:167], v[208:211], v[92:95]
	v_mfma_f32_16x16x32_bf16 v[76:79], v[164:167], v[216:219], v[76:79]
	v_mfma_f32_16x16x32_bf16 v[84:87], v[156:159], v[216:219], v[84:87]
	s_setprio 0
	s_setprio 1
	v_mfma_f32_16x16x32_bf16 v[112:115], v[168:171], v[188:191], v[112:115]
	v_mfma_f32_16x16x32_bf16 v[104:107], v[176:179], v[188:191], v[104:107]
	v_mfma_f32_16x16x32_bf16 v[88:91], v[176:179], v[196:199], v[88:91]
	v_mfma_f32_16x16x32_bf16 v[96:99], v[168:171], v[196:199], v[96:99]
	v_mfma_f32_16x16x32_bf16 v[80:83], v[168:171], v[204:207], v[80:83]
	v_mfma_f32_16x16x32_bf16 v[72:75], v[176:179], v[204:207], v[72:75]
	v_mfma_f32_16x16x32_bf16 v[64:67], v[176:179], v[212:215], v[64:67]
	v_mfma_f32_16x16x32_bf16 v[68:71], v[168:171], v[212:215], v[68:71]
	v_mfma_f32_16x16x32_bf16 v[112:115], v[172:175], v[192:195], v[112:115]
	v_mfma_f32_16x16x32_bf16 v[104:107], v[184:187], v[192:195], v[104:107]
	v_mfma_f32_16x16x32_bf16 v[88:91], v[184:187], v[200:203], v[88:91]
	v_mfma_f32_16x16x32_bf16 v[96:99], v[172:175], v[200:203], v[96:99]
	v_mfma_f32_16x16x32_bf16 v[80:83], v[172:175], v[208:211], v[80:83]
	v_mfma_f32_16x16x32_bf16 v[72:75], v[184:187], v[208:211], v[72:75]
	v_mfma_f32_16x16x32_bf16 v[64:67], v[184:187], v[216:219], v[64:67]
	v_mfma_f32_16x16x32_bf16 v[68:71], v[172:175], v[216:219], v[68:71]
	s_setprio 0
	s_barrier
	s_add_i32 s18, s79, s66
	v_lshl_add_u64 v[144:145], v[144:145], 0, s[10:11]
	s_mov_b32 m0, s18
	ds_read_b128 v[188:191], v151 offset:49152
	ds_read_b128 v[192:195], v151 offset:50176
	ds_read_b128 v[196:199], v151 offset:51200
	ds_read_b128 v[200:203], v151 offset:52224
	ds_read_b128 v[204:207], v151 offset:53248
	ds_read_b128 v[208:211], v151 offset:54272
	ds_read_b128 v[212:215], v151 offset:55296
	ds_read_b128 v[216:219], v151 offset:56320
	global_load_lds_dwordx4 v[144:145], off
	s_add_i32 m0, s18, 0x2000
	s_add_u32 s18, s60, 0x40080
	v_lshl_add_u64 v[144:145], v[220:221], 0, s[10:11]
	s_addc_u32 s19, s61, 0
	s_add_i32 s60, s89, s66
	global_load_lds_dwordx4 v[144:145], off
	v_lshl_add_u64 v[144:145], s[18:19], 0, v[130:131]
	s_mov_b32 m0, s60
	s_nop 0
	global_load_lds_dwordx4 v[144:145], off
	v_lshl_add_u64 v[144:145], s[18:19], 0, v[134:135]
	s_add_i32 m0, s60, 0x2000
	s_nop 0
	global_load_lds_dwordx4 v[144:145], off
	v_lshl_add_u64 v[144:145], v[222:223], 0, s[10:11]
	s_mov_b32 m0, s71
	s_nop 0
	global_load_lds_dwordx4 v[144:145], off
	v_lshl_add_u64 v[144:145], v[224:225], 0, s[10:11]
	s_mov_b32 m0, s72
	s_nop 0
	global_load_lds_dwordx4 v[144:145], off
	s_waitcnt vmcnt(8)
	s_waitcnt lgkmcnt(0)
	s_barrier
	s_setprio 1
	s_waitcnt lgkmcnt(0)
	v_mfma_f32_16x16x32_bf16 v[60:63], v[152:155], v[188:191], v[60:63]
	v_mfma_f32_16x16x32_bf16 v[56:59], v[160:163], v[188:191], v[56:59]
	v_mfma_f32_16x16x32_bf16 v[44:47], v[160:163], v[196:199], v[44:47]
	v_mfma_f32_16x16x32_bf16 v[52:55], v[152:155], v[196:199], v[52:55]
	v_mfma_f32_16x16x32_bf16 v[36:39], v[152:155], v[204:207], v[36:39]
	v_mfma_f32_16x16x32_bf16 v[28:31], v[160:163], v[204:207], v[28:31]
	v_mfma_f32_16x16x32_bf16 v[12:15], v[160:163], v[212:215], v[12:15]
	v_mfma_f32_16x16x32_bf16 v[20:23], v[152:155], v[212:215], v[20:23]
	v_mfma_f32_16x16x32_bf16 v[60:63], v[156:159], v[192:195], v[60:63]
	v_mfma_f32_16x16x32_bf16 v[56:59], v[164:167], v[192:195], v[56:59]
	v_mfma_f32_16x16x32_bf16 v[44:47], v[164:167], v[200:203], v[44:47]
	v_mfma_f32_16x16x32_bf16 v[52:55], v[156:159], v[200:203], v[52:55]
	v_mfma_f32_16x16x32_bf16 v[36:39], v[156:159], v[208:211], v[36:39]
	v_mfma_f32_16x16x32_bf16 v[28:31], v[164:167], v[208:211], v[28:31]
	v_mfma_f32_16x16x32_bf16 v[12:15], v[164:167], v[216:219], v[12:15]
	v_mfma_f32_16x16x32_bf16 v[20:23], v[156:159], v[216:219], v[20:23]
	s_setprio 0
	s_setprio 1
	v_mfma_f32_16x16x32_bf16 v[48:51], v[168:171], v[188:191], v[48:51]
	v_mfma_f32_16x16x32_bf16 v[40:43], v[176:179], v[188:191], v[40:43]
	v_mfma_f32_16x16x32_bf16 v[24:27], v[176:179], v[196:199], v[24:27]
	v_mfma_f32_16x16x32_bf16 v[32:35], v[168:171], v[196:199], v[32:35]
	v_mfma_f32_16x16x32_bf16 v[16:19], v[168:171], v[204:207], v[16:19]
	v_mfma_f32_16x16x32_bf16 v[8:11], v[176:179], v[204:207], v[8:11]
	v_mfma_f32_16x16x32_bf16 v[0:3], v[176:179], v[212:215], v[0:3]
	v_mfma_f32_16x16x32_bf16 v[4:7], v[168:171], v[212:215], v[4:7]
	v_mfma_f32_16x16x32_bf16 v[48:51], v[172:175], v[192:195], v[48:51]
	v_mfma_f32_16x16x32_bf16 v[40:43], v[184:187], v[192:195], v[40:43]
	v_mfma_f32_16x16x32_bf16 v[24:27], v[184:187], v[200:203], v[24:27]
	v_mfma_f32_16x16x32_bf16 v[32:35], v[172:175], v[200:203], v[32:35]
	v_mfma_f32_16x16x32_bf16 v[16:19], v[172:175], v[208:211], v[16:19]
	v_mfma_f32_16x16x32_bf16 v[8:11], v[184:187], v[208:211], v[8:11]
	v_mfma_f32_16x16x32_bf16 v[0:3], v[184:187], v[216:219], v[0:3]
	v_mfma_f32_16x16x32_bf16 v[4:7], v[172:175], v[216:219], v[4:7]
	s_setprio 0
	s_barrier
	s_add_i32 s88, s88, 2
	s_add_u32 s58, s58, 0x100
	s_addc_u32 s59, s59, 0
	s_add_u32 s86, s86, 0x100
	s_addc_u32 s87, s87, 0
	s_cmp_gt_u32 s88, 13
	s_cbranch_scc0 .LBB0_601
	s_and_b64 vcc, exec, s[12:13]
	s_cbranch_vccz .LBB0_604
	s_barrier

.LBB0_724:
	ds_read_b128 v[140:143], v147
	ds_read_b128 v[150:153], v147 offset:1024
	ds_read_b128 v[154:157], v147 offset:2048
	ds_read_b128 v[158:161], v147 offset:3072
	ds_read_b128 v[162:165], v148
	ds_read_b128 v[166:169], v148 offset:1024
	ds_read_b128 v[170:173], v148 offset:2048
	ds_read_b128 v[174:177], v148 offset:3072
	s_add_u32 s52, s48, 0xfffc0080
	s_addc_u32 s53, s49, -1
	s_cmp_eq_u32 s74, 12
	s_cselect_b32 s55, s31, s53
	s_cselect_b32 s54, s70, s52
	s_cselect_b32 s53, s19, s73
	s_cselect_b32 s52, s71, s72
	v_lshl_add_u64 v[178:179], s[48:49], 0, v[132:133]
	s_add_i32 m0, s47, 0xc000
	ds_read_b128 v[184:187], v149
	ds_read_b128 v[188:191], v149 offset:1024
	ds_read_b128 v[192:195], v149 offset:2048
	ds_read_b128 v[196:199], v149 offset:3072
	ds_read_b128 v[200:203], v149 offset:4096
	ds_read_b128 v[204:207], v149 offset:5120
	ds_read_b128 v[208:211], v149 offset:6144
	ds_read_b128 v[212:215], v149 offset:7168
	global_load_lds_dwordx4 v[178:179], off
	v_lshl_add_u64 v[178:179], s[48:49], 0, v[134:135]
	s_add_i32 m0, s47, 0xe000
	s_nop 0
	global_load_lds_dwordx4 v[178:179], off
	s_waitcnt vmcnt(8)
	s_waitcnt lgkmcnt(0)
	s_barrier
	s_setprio 1
	s_waitcnt lgkmcnt(0)
	v_mfma_f32_16x16x32_bf16 v[124:127], v[140:143], v[184:187], v[124:127]
	v_mfma_f32_16x16x32_bf16 v[120:123], v[154:157], v[184:187], v[120:123]
	v_mfma_f32_16x16x32_bf16 v[104:107], v[154:157], v[192:195], v[104:107]
	v_mfma_f32_16x16x32_bf16 v[108:111], v[140:143], v[192:195], v[108:111]
	v_mfma_f32_16x16x32_bf16 v[92:95], v[140:143], v[200:203], v[92:95]
	v_mfma_f32_16x16x32_bf16 v[88:91], v[154:157], v[200:203], v[88:91]
	v_mfma_f32_16x16x32_bf16 v[72:75], v[154:157], v[208:211], v[72:75]
	v_mfma_f32_16x16x32_bf16 v[76:79], v[140:143], v[208:211], v[76:79]
	v_mfma_f32_16x16x32_bf16 v[124:127], v[150:153], v[188:191], v[124:127]
	v_mfma_f32_16x16x32_bf16 v[120:123], v[158:161], v[188:191], v[120:123]
	v_mfma_f32_16x16x32_bf16 v[104:107], v[158:161], v[196:199], v[104:107]
	v_mfma_f32_16x16x32_bf16 v[108:111], v[150:153], v[196:199], v[108:111]
	v_mfma_f32_16x16x32_bf16 v[92:95], v[150:153], v[204:207], v[92:95]
	v_mfma_f32_16x16x32_bf16 v[88:91], v[158:161], v[204:207], v[88:91]
	v_mfma_f32_16x16x32_bf16 v[72:75], v[158:161], v[212:215], v[72:75]
	v_mfma_f32_16x16x32_bf16 v[76:79], v[150:153], v[212:215], v[76:79]
	s_setprio 0
	s_setprio 1
	v_mfma_f32_16x16x32_bf16 v[116:119], v[162:165], v[184:187], v[116:119]
	v_mfma_f32_16x16x32_bf16 v[112:115], v[170:173], v[184:187], v[112:115]
	v_mfma_f32_16x16x32_bf16 v[96:99], v[170:173], v[192:195], v[96:99]
	v_mfma_f32_16x16x32_bf16 v[100:103], v[162:165], v[192:195], v[100:103]
	v_mfma_f32_16x16x32_bf16 v[84:87], v[162:165], v[200:203], v[84:87]
	v_mfma_f32_16x16x32_bf16 v[80:83], v[170:173], v[200:203], v[80:83]
	v_mfma_f32_16x16x32_bf16 v[64:67], v[170:173], v[208:211], v[64:67]
	v_mfma_f32_16x16x32_bf16 v[68:71], v[162:165], v[208:211], v[68:71]
	v_mfma_f32_16x16x32_bf16 v[116:119], v[166:169], v[188:191], v[116:119]
	v_mfma_f32_16x16x32_bf16 v[112:115], v[174:177], v[188:191], v[112:115]
	v_mfma_f32_16x16x32_bf16 v[96:99], v[174:177], v[196:199], v[96:99]
	v_mfma_f32_16x16x32_bf16 v[100:103], v[166:169], v[196:199], v[100:103]
	v_mfma_f32_16x16x32_bf16 v[84:87], v[166:169], v[204:207], v[84:87]
	v_mfma_f32_16x16x32_bf16 v[80:83], v[174:177], v[204:207], v[80:83]
	v_mfma_f32_16x16x32_bf16 v[64:67], v[174:177], v[212:215], v[64:67]
	v_mfma_f32_16x16x32_bf16 v[68:71], v[166:169], v[212:215], v[68:71]
	s_setprio 0
	s_barrier
	s_add_i32 s75, s66, s58
	v_lshl_add_u64 v[178:179], s[52:53], 0, v[130:131]
	s_mov_b32 m0, s75
	ds_read_b128 v[184:187], v149 offset:16384
	ds_read_b128 v[188:191], v149 offset:17408
	ds_read_b128 v[192:195], v149 offset:18432
	ds_read_b128 v[196:199], v149 offset:19456
	ds_read_b128 v[200:203], v149 offset:20480
	ds_read_b128 v[204:207], v149 offset:21504
	ds_read_b128 v[208:211], v149 offset:22528
	ds_read_b128 v[212:215], v149 offset:23552
	global_load_lds_dwordx4 v[178:179], off
	s_add_i32 m0, s75, 0x2000
	s_add_u32 s76, s52, 0x40000
	v_lshl_add_u64 v[216:217], s[52:53], 0, v[128:129]
	s_addc_u32 s77, s53, 0
	s_add_i32 s75, s67, s58
	global_load_lds_dwordx4 v[216:217], off
	v_lshl_add_u64 v[218:219], s[76:77], 0, v[130:131]
	s_mov_b32 m0, s75
	v_lshl_add_u64 v[220:221], s[54:55], 0, v[128:129]
	global_load_lds_dwordx4 v[218:219], off
	v_lshl_add_u64 v[218:219], s[76:77], 0, v[128:129]
	s_add_i32 m0, s75, 0x2000
	s_nop 0
	global_load_lds_dwordx4 v[218:219], off
	v_lshl_add_u64 v[218:219], s[54:55], 0, v[130:131]
	s_mov_b32 m0, s47
	s_nop 0
	global_load_lds_dwordx4 v[218:219], off
	s_mov_b32 m0, s60
	s_nop 0
	global_load_lds_dwordx4 v[220:221], off
	s_waitcnt vmcnt(8)
	s_waitcnt lgkmcnt(0)
	s_barrier
	s_setprio 1
	s_waitcnt lgkmcnt(0)
	v_mfma_f32_16x16x32_bf16 v[60:63], v[140:143], v[184:187], v[60:63]
	v_mfma_f32_16x16x32_bf16 v[56:59], v[154:157], v[184:187], v[56:59]
	v_mfma_f32_16x16x32_bf16 v[40:43], v[154:157], v[192:195], v[40:43]
	v_mfma_f32_16x16x32_bf16 v[44:47], v[140:143], v[192:195], v[44:47]
	v_mfma_f32_16x16x32_bf16 v[28:31], v[140:143], v[200:203], v[28:31]
	v_mfma_f32_16x16x32_bf16 v[24:27], v[154:157], v[200:203], v[24:27]
	v_mfma_f32_16x16x32_bf16 v[8:11], v[154:157], v[208:211], v[8:11]
	v_mfma_f32_16x16x32_bf16 v[12:15], v[140:143], v[208:211], v[12:15]
	v_mfma_f32_16x16x32_bf16 v[60:63], v[150:153], v[188:191], v[60:63]
	v_mfma_f32_16x16x32_bf16 v[56:59], v[158:161], v[188:191], v[56:59]
	v_mfma_f32_16x16x32_bf16 v[40:43], v[158:161], v[196:199], v[40:43]
	v_mfma_f32_16x16x32_bf16 v[44:47], v[150:153], v[196:199], v[44:47]
	v_mfma_f32_16x16x32_bf16 v[28:31], v[150:153], v[204:207], v[28:31]
	v_mfma_f32_16x16x32_bf16 v[24:27], v[158:161], v[204:207], v[24:27]
	v_mfma_f32_16x16x32_bf16 v[8:11], v[158:161], v[212:215], v[8:11]
	v_mfma_f32_16x16x32_bf16 v[12:15], v[150:153], v[212:215], v[12:15]
	s_setprio 0
	s_setprio 1
	v_mfma_f32_16x16x32_bf16 v[52:55], v[162:165], v[184:187], v[52:55]
	v_mfma_f32_16x16x32_bf16 v[48:51], v[170:173], v[184:187], v[48:51]
	v_mfma_f32_16x16x32_bf16 v[32:35], v[170:173], v[192:195], v[32:35]
	v_mfma_f32_16x16x32_bf16 v[36:39], v[162:165], v[192:195], v[36:39]
	v_mfma_f32_16x16x32_bf16 v[20:23], v[162:165], v[200:203], v[20:23]
	v_mfma_f32_16x16x32_bf16 v[16:19], v[170:173], v[200:203], v[16:19]
	v_mfma_f32_16x16x32_bf16 v[0:3], v[170:173], v[208:211], v[0:3]
	v_mfma_f32_16x16x32_bf16 v[4:7], v[162:165], v[208:211], v[4:7]
	v_mfma_f32_16x16x32_bf16 v[52:55], v[166:169], v[188:191], v[52:55]
	v_mfma_f32_16x16x32_bf16 v[48:51], v[174:177], v[188:191], v[48:51]
	v_mfma_f32_16x16x32_bf16 v[32:35], v[174:177], v[196:199], v[32:35]
	v_mfma_f32_16x16x32_bf16 v[36:39], v[166:169], v[196:199], v[36:39]
	v_mfma_f32_16x16x32_bf16 v[20:23], v[166:169], v[204:207], v[20:23]
	v_mfma_f32_16x16x32_bf16 v[16:19], v[174:177], v[204:207], v[16:19]
	v_mfma_f32_16x16x32_bf16 v[0:3], v[174:177], v[212:215], v[0:3]
	v_mfma_f32_16x16x32_bf16 v[4:7], v[166:169], v[212:215], v[4:7]
	s_setprio 0
	s_barrier
	s_add_i32 s75, 0, 0x18000
	s_add_i32 s76, 0, 0x1c000
	v_add_u32_e32 v158, s75, v145
	v_add_u32_e32 v174, s76, v145
	ds_read_b128 v[140:143], v158
	ds_read_b128 v[150:153], v158 offset:1024
	ds_read_b128 v[154:157], v158 offset:2048
	ds_read_b128 v[158:161], v158 offset:3072
	ds_read_b128 v[162:165], v174
	ds_read_b128 v[166:169], v174 offset:1024
	ds_read_b128 v[170:173], v174 offset:2048
	ds_read_b128 v[174:177], v174 offset:3072
	s_add_u32 s54, s54, 0x40000
	s_addc_u32 s55, s55, 0
	s_mov_b32 m0, s61
	v_lshl_add_u64 v[222:223], s[54:55], 0, v[130:131]
	ds_read_b128 v[184:187], v149 offset:32768
	ds_read_b128 v[188:191], v149 offset:33792
	ds_read_b128 v[192:195], v149 offset:34816
	ds_read_b128 v[196:199], v149 offset:35840
	ds_read_b128 v[200:203], v149 offset:36864
	ds_read_b128 v[204:207], v149 offset:37888
	ds_read_b128 v[208:211], v149 offset:38912
	ds_read_b128 v[212:215], v149 offset:39936
	global_load_lds_dwordx4 v[222:223], off
	v_lshl_add_u64 v[222:223], s[54:55], 0, v[128:129]
	s_mov_b32 m0, s62
	s_nop 0
	global_load_lds_dwordx4 v[222:223], off
	s_waitcnt vmcnt(8)
	s_waitcnt lgkmcnt(0)
	s_barrier
	s_setprio 1
	s_waitcnt lgkmcnt(0)
	v_mfma_f32_16x16x32_bf16 v[124:127], v[140:143], v[184:187], v[124:127]
	v_mfma_f32_16x16x32_bf16 v[120:123], v[154:157], v[184:187], v[120:123]
	v_mfma_f32_16x16x32_bf16 v[104:107], v[154:157], v[192:195], v[104:107]
	v_mfma_f32_16x16x32_bf16 v[108:111], v[140:143], v[192:195], v[108:111]
	v_mfma_f32_16x16x32_bf16 v[92:95], v[140:143], v[200:203], v[92:95]
	v_mfma_f32_16x16x32_bf16 v[88:91], v[154:157], v[200:203], v[88:91]
	v_mfma_f32_16x16x32_bf16 v[72:75], v[154:157], v[208:211], v[72:75]
	v_mfma_f32_16x16x32_bf16 v[76:79], v[140:143], v[208:211], v[76:79]
	v_mfma_f32_16x16x32_bf16 v[124:127], v[150:153], v[188:191], v[124:127]
	v_mfma_f32_16x16x32_bf16 v[120:123], v[158:161], v[188:191], v[120:123]
	v_mfma_f32_16x16x32_bf16 v[104:107], v[158:161], v[196:199], v[104:107]
	v_mfma_f32_16x16x32_bf16 v[108:111], v[150:153], v[196:199], v[108:111]
	v_mfma_f32_16x16x32_bf16 v[92:95], v[150:153], v[204:207], v[92:95]
	v_mfma_f32_16x16x32_bf16 v[88:91], v[158:161], v[204:207], v[88:91]
	v_mfma_f32_16x16x32_bf16 v[72:75], v[158:161], v[212:215], v[72:75]
	v_mfma_f32_16x16x32_bf16 v[76:79], v[150:153], v[212:215], v[76:79]
	s_setprio 0
	s_setprio 1
	v_mfma_f32_16x16x32_bf16 v[116:119], v[162:165], v[184:187], v[116:119]
	v_mfma_f32_16x16x32_bf16 v[112:115], v[170:173], v[184:187], v[112:115]
	v_mfma_f32_16x16x32_bf16 v[96:99], v[170:173], v[192:195], v[96:99]
	v_mfma_f32_16x16x32_bf16 v[100:103], v[162:165], v[192:195], v[100:103]
	v_mfma_f32_16x16x32_bf16 v[84:87], v[162:165], v[200:203], v[84:87]
	v_mfma_f32_16x16x32_bf16 v[80:83], v[170:173], v[200:203], v[80:83]
	v_mfma_f32_16x16x32_bf16 v[64:67], v[170:173], v[208:211], v[64:67]
	v_mfma_f32_16x16x32_bf16 v[68:71], v[162:165], v[208:211], v[68:71]
	v_mfma_f32_16x16x32_bf16 v[116:119], v[166:169], v[188:191], v[116:119]
	v_mfma_f32_16x16x32_bf16 v[112:115], v[174:177], v[188:191], v[112:115]
	v_mfma_f32_16x16x32_bf16 v[96:99], v[174:177], v[196:199], v[96:99]
	v_mfma_f32_16x16x32_bf16 v[100:103], v[166:169], v[196:199], v[100:103]
	v_mfma_f32_16x16x32_bf16 v[84:87], v[166:169], v[204:207], v[84:87]
	v_mfma_f32_16x16x32_bf16 v[80:83], v[174:177], v[204:207], v[80:83]
	v_mfma_f32_16x16x32_bf16 v[64:67], v[174:177], v[212:215], v[64:67]
	v_mfma_f32_16x16x32_bf16 v[68:71], v[166:169], v[212:215], v[68:71]
	s_setprio 0
	s_barrier
	s_add_i32 s54, s75, s58
	v_lshl_add_u64 v[178:179], v[178:179], 0, s[12:13]
	s_mov_b32 m0, s54
	ds_read_b128 v[184:187], v149 offset:49152
	ds_read_b128 v[188:191], v149 offset:50176
	ds_read_b128 v[192:195], v149 offset:51200
	ds_read_b128 v[196:199], v149 offset:52224
	ds_read_b128 v[200:203], v149 offset:53248
	ds_read_b128 v[204:207], v149 offset:54272
	ds_read_b128 v[208:211], v149 offset:55296
	ds_read_b128 v[212:215], v149 offset:56320
	global_load_lds_dwordx4 v[178:179], off
	s_add_i32 m0, s54, 0x2000
	s_add_u32 s52, s52, 0x40080
	v_lshl_add_u64 v[178:179], v[216:217], 0, s[12:13]
	s_addc_u32 s53, s53, 0
	s_add_i32 s54, s76, s58
	global_load_lds_dwordx4 v[178:179], off
	v_lshl_add_u64 v[178:179], s[52:53], 0, v[130:131]
	s_mov_b32 m0, s54
	s_nop 0
	global_load_lds_dwordx4 v[178:179], off
	v_lshl_add_u64 v[178:179], s[52:53], 0, v[128:129]
	s_add_i32 m0, s54, 0x2000
	s_nop 0
	global_load_lds_dwordx4 v[178:179], off
	v_lshl_add_u64 v[178:179], v[218:219], 0, s[12:13]
	s_mov_b32 m0, s64
	s_nop 0
	global_load_lds_dwordx4 v[178:179], off
	v_lshl_add_u64 v[178:179], v[220:221], 0, s[12:13]
	s_mov_b32 m0, s65
	s_nop 0
	global_load_lds_dwordx4 v[178:179], off
	s_waitcnt vmcnt(8)
	s_waitcnt lgkmcnt(0)
	s_barrier
	s_setprio 1
	s_waitcnt lgkmcnt(0)
	v_mfma_f32_16x16x32_bf16 v[60:63], v[140:143], v[184:187], v[60:63]
	v_mfma_f32_16x16x32_bf16 v[56:59], v[154:157], v[184:187], v[56:59]
	v_mfma_f32_16x16x32_bf16 v[40:43], v[154:157], v[192:195], v[40:43]
	v_mfma_f32_16x16x32_bf16 v[44:47], v[140:143], v[192:195], v[44:47]
	v_mfma_f32_16x16x32_bf16 v[28:31], v[140:143], v[200:203], v[28:31]
	v_mfma_f32_16x16x32_bf16 v[24:27], v[154:157], v[200:203], v[24:27]
	v_mfma_f32_16x16x32_bf16 v[8:11], v[154:157], v[208:211], v[8:11]
	v_mfma_f32_16x16x32_bf16 v[12:15], v[140:143], v[208:211], v[12:15]
	v_mfma_f32_16x16x32_bf16 v[60:63], v[150:153], v[188:191], v[60:63]
	v_mfma_f32_16x16x32_bf16 v[56:59], v[158:161], v[188:191], v[56:59]
	v_mfma_f32_16x16x32_bf16 v[40:43], v[158:161], v[196:199], v[40:43]
	v_mfma_f32_16x16x32_bf16 v[44:47], v[150:153], v[196:199], v[44:47]
	v_mfma_f32_16x16x32_bf16 v[28:31], v[150:153], v[204:207], v[28:31]
	v_mfma_f32_16x16x32_bf16 v[24:27], v[158:161], v[204:207], v[24:27]
	v_mfma_f32_16x16x32_bf16 v[8:11], v[158:161], v[212:215], v[8:11]
	v_mfma_f32_16x16x32_bf16 v[12:15], v[150:153], v[212:215], v[12:15]
	s_setprio 0
	s_setprio 1
	v_mfma_f32_16x16x32_bf16 v[52:55], v[162:165], v[184:187], v[52:55]
	v_mfma_f32_16x16x32_bf16 v[48:51], v[170:173], v[184:187], v[48:51]
	v_mfma_f32_16x16x32_bf16 v[32:35], v[170:173], v[192:195], v[32:35]
	v_mfma_f32_16x16x32_bf16 v[36:39], v[162:165], v[192:195], v[36:39]
	v_mfma_f32_16x16x32_bf16 v[20:23], v[162:165], v[200:203], v[20:23]
	v_mfma_f32_16x16x32_bf16 v[16:19], v[170:173], v[200:203], v[16:19]
	v_mfma_f32_16x16x32_bf16 v[0:3], v[170:173], v[208:211], v[0:3]
	v_mfma_f32_16x16x32_bf16 v[4:7], v[162:165], v[208:211], v[4:7]
	v_mfma_f32_16x16x32_bf16 v[52:55], v[166:169], v[188:191], v[52:55]
	v_mfma_f32_16x16x32_bf16 v[48:51], v[174:177], v[188:191], v[48:51]
	v_mfma_f32_16x16x32_bf16 v[32:35], v[174:177], v[196:199], v[32:35]
	v_mfma_f32_16x16x32_bf16 v[36:39], v[166:169], v[196:199], v[36:39]
	v_mfma_f32_16x16x32_bf16 v[20:23], v[166:169], v[204:207], v[20:23]
	v_mfma_f32_16x16x32_bf16 v[16:19], v[174:177], v[204:207], v[16:19]
	v_mfma_f32_16x16x32_bf16 v[0:3], v[174:177], v[212:215], v[0:3]
	v_mfma_f32_16x16x32_bf16 v[4:7], v[166:169], v[212:215], v[4:7]
	s_setprio 0
	s_barrier
	s_add_i32 s74, s74, 2
	s_add_u32 s48, s48, 0x100
	s_addc_u32 s49, s49, 0
	s_add_u32 s72, s72, 0x100
	s_addc_u32 s73, s73, 0
	s_cmp_gt_u32 s74, 13
	s_cbranch_scc0 .LBB0_724
	s_and_b64 vcc, exec, s[16:17]
	s_cbranch_vccz .LBB0_727
	s_barrier

.LBB0_804:
	ds_read_b128 v[152:155], v149
	ds_read_b128 v[156:159], v149 offset:1024
	ds_read_b128 v[160:163], v149 offset:2048
	ds_read_b128 v[164:167], v149 offset:3072
	ds_read_b128 v[168:171], v150
	ds_read_b128 v[172:175], v150 offset:1024
	ds_read_b128 v[176:179], v150 offset:2048
	ds_read_b128 v[184:187], v150 offset:3072
	s_add_u32 s54, s52, 0x100
	s_addc_u32 s55, s53, 0
	s_cmp_eq_u32 s86, 40
	s_cselect_b32 s59, s13, s55
	s_cselect_b32 s58, s12, s54
	s_cselect_b32 s57, s49, s85
	s_cselect_b32 s56, s48, s84
	v_lshl_add_u64 v[144:145], s[52:53], 0, v[136:137]
	s_add_i32 m0, s63, 0xc000
	ds_read_b128 v[188:191], v151
	ds_read_b128 v[192:195], v151 offset:1024
	ds_read_b128 v[196:199], v151 offset:2048
	ds_read_b128 v[200:203], v151 offset:3072
	ds_read_b128 v[204:207], v151 offset:4096
	ds_read_b128 v[208:211], v151 offset:5120
	ds_read_b128 v[212:215], v151 offset:6144
	ds_read_b128 v[216:219], v151 offset:7168
	global_load_lds_dwordx4 v[144:145], off
	v_lshl_add_u64 v[144:145], s[52:53], 0, v[138:139]
	s_add_i32 m0, s63, 0xe000
	s_nop 0
	global_load_lds_dwordx4 v[144:145], off
	s_waitcnt vmcnt(8)
	s_waitcnt lgkmcnt(0)
	s_barrier
	s_setprio 1
	s_waitcnt lgkmcnt(0)
	v_mfma_f32_16x16x32_bf16 v[124:127], v[152:155], v[188:191], v[124:127]
	v_mfma_f32_16x16x32_bf16 v[120:123], v[160:163], v[188:191], v[120:123]
	v_mfma_f32_16x16x32_bf16 v[108:111], v[160:163], v[196:199], v[108:111]
	v_mfma_f32_16x16x32_bf16 v[116:119], v[152:155], v[196:199], v[116:119]
	v_mfma_f32_16x16x32_bf16 v[100:103], v[152:155], v[204:207], v[100:103]
	v_mfma_f32_16x16x32_bf16 v[92:95], v[160:163], v[204:207], v[92:95]
	v_mfma_f32_16x16x32_bf16 v[76:79], v[160:163], v[212:215], v[76:79]
	v_mfma_f32_16x16x32_bf16 v[84:87], v[152:155], v[212:215], v[84:87]
	v_mfma_f32_16x16x32_bf16 v[124:127], v[156:159], v[192:195], v[124:127]
	v_mfma_f32_16x16x32_bf16 v[120:123], v[164:167], v[192:195], v[120:123]
	v_mfma_f32_16x16x32_bf16 v[108:111], v[164:167], v[200:203], v[108:111]
	v_mfma_f32_16x16x32_bf16 v[116:119], v[156:159], v[200:203], v[116:119]
	v_mfma_f32_16x16x32_bf16 v[100:103], v[156:159], v[208:211], v[100:103]
	v_mfma_f32_16x16x32_bf16 v[92:95], v[164:167], v[208:211], v[92:95]
	v_mfma_f32_16x16x32_bf16 v[76:79], v[164:167], v[216:219], v[76:79]
	v_mfma_f32_16x16x32_bf16 v[84:87], v[156:159], v[216:219], v[84:87]
	s_setprio 0
	s_setprio 1
	v_mfma_f32_16x16x32_bf16 v[112:115], v[168:171], v[188:191], v[112:115]
	v_mfma_f32_16x16x32_bf16 v[104:107], v[176:179], v[188:191], v[104:107]
	v_mfma_f32_16x16x32_bf16 v[88:91], v[176:179], v[196:199], v[88:91]
	v_mfma_f32_16x16x32_bf16 v[96:99], v[168:171], v[196:199], v[96:99]
	v_mfma_f32_16x16x32_bf16 v[80:83], v[168:171], v[204:207], v[80:83]
	v_mfma_f32_16x16x32_bf16 v[72:75], v[176:179], v[204:207], v[72:75]
	v_mfma_f32_16x16x32_bf16 v[64:67], v[176:179], v[212:215], v[64:67]
	v_mfma_f32_16x16x32_bf16 v[68:71], v[168:171], v[212:215], v[68:71]
	v_mfma_f32_16x16x32_bf16 v[112:115], v[172:175], v[192:195], v[112:115]
	v_mfma_f32_16x16x32_bf16 v[104:107], v[184:187], v[192:195], v[104:107]
	v_mfma_f32_16x16x32_bf16 v[88:91], v[184:187], v[200:203], v[88:91]
	v_mfma_f32_16x16x32_bf16 v[96:99], v[172:175], v[200:203], v[96:99]
	v_mfma_f32_16x16x32_bf16 v[80:83], v[172:175], v[208:211], v[80:83]
	v_mfma_f32_16x16x32_bf16 v[72:75], v[184:187], v[208:211], v[72:75]
	v_mfma_f32_16x16x32_bf16 v[64:67], v[184:187], v[216:219], v[64:67]
	v_mfma_f32_16x16x32_bf16 v[68:71], v[172:175], v[216:219], v[68:71]
	s_setprio 0
	s_barrier
	s_add_i32 s52, s70, s62
	v_lshl_add_u64 v[144:145], s[56:57], 0, v[130:131]
	s_mov_b32 m0, s52
	ds_read_b128 v[188:191], v151 offset:16384
	ds_read_b128 v[192:195], v151 offset:17408
	ds_read_b128 v[196:199], v151 offset:18432
	ds_read_b128 v[200:203], v151 offset:19456
	ds_read_b128 v[204:207], v151 offset:20480
	ds_read_b128 v[208:211], v151 offset:21504
	ds_read_b128 v[212:215], v151 offset:22528
	ds_read_b128 v[216:219], v151 offset:23552
	global_load_lds_dwordx4 v[144:145], off
	s_add_i32 m0, s52, 0x2000
	s_add_u32 s52, s56, 0xb0000
	v_lshl_add_u64 v[220:221], s[56:57], 0, v[134:135]
	s_addc_u32 s53, s57, 0
	s_add_i32 s79, s71, s62
	global_load_lds_dwordx4 v[220:221], off
	v_lshl_add_u64 v[222:223], s[52:53], 0, v[130:131]
	s_mov_b32 m0, s79
	v_lshl_add_u64 v[224:225], s[58:59], 0, v[132:133]
	global_load_lds_dwordx4 v[222:223], off
	v_lshl_add_u64 v[222:223], s[52:53], 0, v[134:135]
	s_add_i32 m0, s79, 0x2000
	s_nop 0
	global_load_lds_dwordx4 v[222:223], off
	v_lshl_add_u64 v[222:223], s[58:59], 0, v[128:129]
	s_mov_b32 m0, s63
	s_nop 0
	global_load_lds_dwordx4 v[222:223], off
	s_mov_b32 m0, s64
	s_nop 0
	global_load_lds_dwordx4 v[224:225], off
	s_waitcnt vmcnt(8)
	s_waitcnt lgkmcnt(0)
	s_barrier
	s_setprio 1
	s_waitcnt lgkmcnt(0)
	v_mfma_f32_16x16x32_bf16 v[60:63], v[152:155], v[188:191], v[60:63]
	v_mfma_f32_16x16x32_bf16 v[56:59], v[160:163], v[188:191], v[56:59]
	v_mfma_f32_16x16x32_bf16 v[44:47], v[160:163], v[196:199], v[44:47]
	v_mfma_f32_16x16x32_bf16 v[52:55], v[152:155], v[196:199], v[52:55]
	v_mfma_f32_16x16x32_bf16 v[36:39], v[152:155], v[204:207], v[36:39]
	v_mfma_f32_16x16x32_bf16 v[28:31], v[160:163], v[204:207], v[28:31]
	v_mfma_f32_16x16x32_bf16 v[12:15], v[160:163], v[212:215], v[12:15]
	v_mfma_f32_16x16x32_bf16 v[20:23], v[152:155], v[212:215], v[20:23]
	v_mfma_f32_16x16x32_bf16 v[60:63], v[156:159], v[192:195], v[60:63]
	v_mfma_f32_16x16x32_bf16 v[56:59], v[164:167], v[192:195], v[56:59]
	v_mfma_f32_16x16x32_bf16 v[44:47], v[164:167], v[200:203], v[44:47]
	v_mfma_f32_16x16x32_bf16 v[52:55], v[156:159], v[200:203], v[52:55]
	v_mfma_f32_16x16x32_bf16 v[36:39], v[156:159], v[208:211], v[36:39]
	v_mfma_f32_16x16x32_bf16 v[28:31], v[164:167], v[208:211], v[28:31]
	v_mfma_f32_16x16x32_bf16 v[12:15], v[164:167], v[216:219], v[12:15]
	v_mfma_f32_16x16x32_bf16 v[20:23], v[156:159], v[216:219], v[20:23]
	s_setprio 0
	s_setprio 1
	v_mfma_f32_16x16x32_bf16 v[48:51], v[168:171], v[188:191], v[48:51]
	v_mfma_f32_16x16x32_bf16 v[40:43], v[176:179], v[188:191], v[40:43]
	v_mfma_f32_16x16x32_bf16 v[24:27], v[176:179], v[196:199], v[24:27]
	v_mfma_f32_16x16x32_bf16 v[32:35], v[168:171], v[196:199], v[32:35]
	v_mfma_f32_16x16x32_bf16 v[16:19], v[168:171], v[204:207], v[16:19]
	v_mfma_f32_16x16x32_bf16 v[8:11], v[176:179], v[204:207], v[8:11]
	v_mfma_f32_16x16x32_bf16 v[0:3], v[176:179], v[212:215], v[0:3]
	v_mfma_f32_16x16x32_bf16 v[4:7], v[168:171], v[212:215], v[4:7]
	v_mfma_f32_16x16x32_bf16 v[48:51], v[172:175], v[192:195], v[48:51]
	v_mfma_f32_16x16x32_bf16 v[40:43], v[184:187], v[192:195], v[40:43]
	v_mfma_f32_16x16x32_bf16 v[24:27], v[184:187], v[200:203], v[24:27]
	v_mfma_f32_16x16x32_bf16 v[32:35], v[172:175], v[200:203], v[32:35]
	v_mfma_f32_16x16x32_bf16 v[16:19], v[172:175], v[208:211], v[16:19]
	v_mfma_f32_16x16x32_bf16 v[8:11], v[184:187], v[208:211], v[8:11]
	v_mfma_f32_16x16x32_bf16 v[0:3], v[184:187], v[216:219], v[0:3]
	v_mfma_f32_16x16x32_bf16 v[4:7], v[172:175], v[216:219], v[4:7]
	s_setprio 0
	s_barrier
	s_add_i32 s79, 0, 0x18000
	s_add_i32 s87, 0, 0x1c000
	v_add_u32_e32 v164, s79, v147
	v_add_u32_e32 v181, s87, v147
	ds_read_b128 v[152:155], v164
	ds_read_b128 v[156:159], v164 offset:1024
	ds_read_b128 v[160:163], v164 offset:2048
	ds_read_b128 v[164:167], v164 offset:3072
	ds_read_b128 v[168:171], v181
	ds_read_b128 v[172:175], v181 offset:1024
	ds_read_b128 v[176:179], v181 offset:2048
	ds_read_b128 v[184:187], v181 offset:3072
	s_add_u32 s52, s58, 0xb0000
	s_addc_u32 s53, s59, 0
	s_mov_b32 m0, s65
	v_lshl_add_u64 v[226:227], s[52:53], 0, v[128:129]
	ds_read_b128 v[188:191], v151 offset:32768
	ds_read_b128 v[192:195], v151 offset:33792
	ds_read_b128 v[196:199], v151 offset:34816
	ds_read_b128 v[200:203], v151 offset:35840
	ds_read_b128 v[204:207], v151 offset:36864
	ds_read_b128 v[208:211], v151 offset:37888
	ds_read_b128 v[212:215], v151 offset:38912
	ds_read_b128 v[216:219], v151 offset:39936
	global_load_lds_dwordx4 v[226:227], off
	v_lshl_add_u64 v[226:227], s[52:53], 0, v[132:133]
	s_mov_b32 m0, s66
	s_nop 0
	global_load_lds_dwordx4 v[226:227], off
	s_waitcnt vmcnt(8)
	s_waitcnt lgkmcnt(0)
	s_barrier
	s_setprio 1
	s_waitcnt lgkmcnt(0)
	v_mfma_f32_16x16x32_bf16 v[124:127], v[152:155], v[188:191], v[124:127]
	v_mfma_f32_16x16x32_bf16 v[120:123], v[160:163], v[188:191], v[120:123]
	v_mfma_f32_16x16x32_bf16 v[108:111], v[160:163], v[196:199], v[108:111]
	v_mfma_f32_16x16x32_bf16 v[116:119], v[152:155], v[196:199], v[116:119]
	v_mfma_f32_16x16x32_bf16 v[100:103], v[152:155], v[204:207], v[100:103]
	v_mfma_f32_16x16x32_bf16 v[92:95], v[160:163], v[204:207], v[92:95]
	v_mfma_f32_16x16x32_bf16 v[76:79], v[160:163], v[212:215], v[76:79]
	v_mfma_f32_16x16x32_bf16 v[84:87], v[152:155], v[212:215], v[84:87]
	v_mfma_f32_16x16x32_bf16 v[124:127], v[156:159], v[192:195], v[124:127]
	v_mfma_f32_16x16x32_bf16 v[120:123], v[164:167], v[192:195], v[120:123]
	v_mfma_f32_16x16x32_bf16 v[108:111], v[164:167], v[200:203], v[108:111]
	v_mfma_f32_16x16x32_bf16 v[116:119], v[156:159], v[200:203], v[116:119]
	v_mfma_f32_16x16x32_bf16 v[100:103], v[156:159], v[208:211], v[100:103]
	v_mfma_f32_16x16x32_bf16 v[92:95], v[164:167], v[208:211], v[92:95]
	v_mfma_f32_16x16x32_bf16 v[76:79], v[164:167], v[216:219], v[76:79]
	v_mfma_f32_16x16x32_bf16 v[84:87], v[156:159], v[216:219], v[84:87]
	s_setprio 0
	s_setprio 1
	v_mfma_f32_16x16x32_bf16 v[112:115], v[168:171], v[188:191], v[112:115]
	v_mfma_f32_16x16x32_bf16 v[104:107], v[176:179], v[188:191], v[104:107]
	v_mfma_f32_16x16x32_bf16 v[88:91], v[176:179], v[196:199], v[88:91]
	v_mfma_f32_16x16x32_bf16 v[96:99], v[168:171], v[196:199], v[96:99]
	v_mfma_f32_16x16x32_bf16 v[80:83], v[168:171], v[204:207], v[80:83]
	v_mfma_f32_16x16x32_bf16 v[72:75], v[176:179], v[204:207], v[72:75]
	v_mfma_f32_16x16x32_bf16 v[64:67], v[176:179], v[212:215], v[64:67]
	v_mfma_f32_16x16x32_bf16 v[68:71], v[168:171], v[212:215], v[68:71]
	v_mfma_f32_16x16x32_bf16 v[112:115], v[172:175], v[192:195], v[112:115]
	v_mfma_f32_16x16x32_bf16 v[104:107], v[184:187], v[192:195], v[104:107]
	v_mfma_f32_16x16x32_bf16 v[88:91], v[184:187], v[200:203], v[88:91]
	v_mfma_f32_16x16x32_bf16 v[96:99], v[172:175], v[200:203], v[96:99]
	v_mfma_f32_16x16x32_bf16 v[80:83], v[172:175], v[208:211], v[80:83]
	v_mfma_f32_16x16x32_bf16 v[72:75], v[184:187], v[208:211], v[72:75]
	v_mfma_f32_16x16x32_bf16 v[64:67], v[184:187], v[216:219], v[64:67]
	v_mfma_f32_16x16x32_bf16 v[68:71], v[172:175], v[216:219], v[68:71]
	s_setprio 0
	s_barrier
	s_add_i32 s52, s79, s62
	v_lshl_add_u64 v[144:145], v[144:145], 0, s[16:17]
	s_mov_b32 m0, s52
	ds_read_b128 v[188:191], v151 offset:49152
	ds_read_b128 v[192:195], v151 offset:50176
	ds_read_b128 v[196:199], v151 offset:51200
	ds_read_b128 v[200:203], v151 offset:52224
	ds_read_b128 v[204:207], v151 offset:53248
	ds_read_b128 v[208:211], v151 offset:54272
	ds_read_b128 v[212:215], v151 offset:55296
	ds_read_b128 v[216:219], v151 offset:56320
	global_load_lds_dwordx4 v[144:145], off
	s_add_i32 m0, s52, 0x2000
	s_add_u32 s52, s56, 0xb0080
	v_lshl_add_u64 v[144:145], v[220:221], 0, s[16:17]
	s_addc_u32 s53, s57, 0
	s_add_i32 s56, s87, s62
	global_load_lds_dwordx4 v[144:145], off
	v_lshl_add_u64 v[144:145], s[52:53], 0, v[130:131]
	s_mov_b32 m0, s56
	s_nop 0
	global_load_lds_dwordx4 v[144:145], off
	v_lshl_add_u64 v[144:145], s[52:53], 0, v[134:135]
	s_add_i32 m0, s56, 0x2000
	s_nop 0
	global_load_lds_dwordx4 v[144:145], off
	v_lshl_add_u64 v[144:145], v[222:223], 0, s[16:17]
	s_mov_b32 m0, s68
	s_nop 0
	global_load_lds_dwordx4 v[144:145], off
	v_lshl_add_u64 v[144:145], v[224:225], 0, s[16:17]
	s_mov_b32 m0, s69
	s_nop 0
	global_load_lds_dwordx4 v[144:145], off
	s_waitcnt vmcnt(8)
	s_waitcnt lgkmcnt(0)
	s_barrier
	s_setprio 1
	s_waitcnt lgkmcnt(0)
	v_mfma_f32_16x16x32_bf16 v[60:63], v[152:155], v[188:191], v[60:63]
	v_mfma_f32_16x16x32_bf16 v[56:59], v[160:163], v[188:191], v[56:59]
	v_mfma_f32_16x16x32_bf16 v[44:47], v[160:163], v[196:199], v[44:47]
	v_mfma_f32_16x16x32_bf16 v[52:55], v[152:155], v[196:199], v[52:55]
	v_mfma_f32_16x16x32_bf16 v[36:39], v[152:155], v[204:207], v[36:39]
	v_mfma_f32_16x16x32_bf16 v[28:31], v[160:163], v[204:207], v[28:31]
	v_mfma_f32_16x16x32_bf16 v[12:15], v[160:163], v[212:215], v[12:15]
	v_mfma_f32_16x16x32_bf16 v[20:23], v[152:155], v[212:215], v[20:23]
	v_mfma_f32_16x16x32_bf16 v[60:63], v[156:159], v[192:195], v[60:63]
	v_mfma_f32_16x16x32_bf16 v[56:59], v[164:167], v[192:195], v[56:59]
	v_mfma_f32_16x16x32_bf16 v[44:47], v[164:167], v[200:203], v[44:47]
	v_mfma_f32_16x16x32_bf16 v[52:55], v[156:159], v[200:203], v[52:55]
	v_mfma_f32_16x16x32_bf16 v[36:39], v[156:159], v[208:211], v[36:39]
	v_mfma_f32_16x16x32_bf16 v[28:31], v[164:167], v[208:211], v[28:31]
	v_mfma_f32_16x16x32_bf16 v[12:15], v[164:167], v[216:219], v[12:15]
	v_mfma_f32_16x16x32_bf16 v[20:23], v[156:159], v[216:219], v[20:23]
	s_setprio 0
	s_setprio 1
	v_mfma_f32_16x16x32_bf16 v[48:51], v[168:171], v[188:191], v[48:51]
	v_mfma_f32_16x16x32_bf16 v[40:43], v[176:179], v[188:191], v[40:43]
	v_mfma_f32_16x16x32_bf16 v[24:27], v[176:179], v[196:199], v[24:27]
	v_mfma_f32_16x16x32_bf16 v[32:35], v[168:171], v[196:199], v[32:35]
	v_mfma_f32_16x16x32_bf16 v[16:19], v[168:171], v[204:207], v[16:19]
	v_mfma_f32_16x16x32_bf16 v[8:11], v[176:179], v[204:207], v[8:11]
	v_mfma_f32_16x16x32_bf16 v[0:3], v[176:179], v[212:215], v[0:3]
	v_mfma_f32_16x16x32_bf16 v[4:7], v[168:171], v[212:215], v[4:7]
	v_mfma_f32_16x16x32_bf16 v[48:51], v[172:175], v[192:195], v[48:51]
	v_mfma_f32_16x16x32_bf16 v[40:43], v[184:187], v[192:195], v[40:43]
	v_mfma_f32_16x16x32_bf16 v[24:27], v[184:187], v[200:203], v[24:27]
	v_mfma_f32_16x16x32_bf16 v[32:35], v[172:175], v[200:203], v[32:35]
	v_mfma_f32_16x16x32_bf16 v[16:19], v[172:175], v[208:211], v[16:19]
	v_mfma_f32_16x16x32_bf16 v[8:11], v[184:187], v[208:211], v[8:11]
	v_mfma_f32_16x16x32_bf16 v[0:3], v[184:187], v[216:219], v[0:3]
	v_mfma_f32_16x16x32_bf16 v[4:7], v[172:175], v[216:219], v[4:7]
	s_setprio 0
	s_barrier
	s_add_i32 s86, s86, 2
	s_add_u32 s84, s84, 0x100
	s_addc_u32 s85, s85, 0
	s_cmp_gt_u32 s86, 41
	s_mov_b64 s[52:53], s[54:55]
	s_cbranch_scc0 .LBB0_804
	s_and_b64 vcc, exec, s[18:19]
	s_cbranch_vccz .LBB0_807
	s_barrier

.LBB0_935:
	ds_read_b128 v[152:155], v148
	ds_read_b128 v[156:159], v148 offset:1024
	ds_read_b128 v[160:163], v148 offset:2048
	ds_read_b128 v[164:167], v148 offset:3072
	ds_read_b128 v[168:171], v149
	ds_read_b128 v[172:175], v149 offset:1024
	ds_read_b128 v[176:179], v149 offset:2048
	ds_read_b128 v[184:187], v149 offset:3072
	s_add_u32 s62, s60, 0xfffc0080
	s_addc_u32 s63, s61, -1
	s_cmp_eq_u32 s87, 12
	s_cselect_b32 s65, s53, s63
	s_cselect_b32 s64, s83, s62
	s_cselect_b32 s63, s49, s86
	s_cselect_b32 s62, s84, s85
	v_lshl_add_u64 v[220:221], s[60:61], 0, v[138:139]
	s_add_i32 m0, s69, 0xc000
	ds_read_b128 v[188:191], v150
	ds_read_b128 v[192:195], v150 offset:1024
	ds_read_b128 v[196:199], v150 offset:2048
	ds_read_b128 v[200:203], v150 offset:3072
	ds_read_b128 v[204:207], v150 offset:4096
	ds_read_b128 v[208:211], v150 offset:5120
	ds_read_b128 v[212:215], v150 offset:6144
	ds_read_b128 v[216:219], v150 offset:7168
	global_load_lds_dwordx4 v[220:221], off
	v_lshl_add_u64 v[220:221], s[60:61], 0, v[140:141]
	s_add_i32 m0, s69, 0xe000
	s_nop 0
	global_load_lds_dwordx4 v[220:221], off
	s_waitcnt vmcnt(8)
	s_waitcnt lgkmcnt(0)
	s_barrier
	s_setprio 1
	s_waitcnt lgkmcnt(0)
	v_mfma_f32_16x16x32_bf16 v[124:127], v[152:155], v[188:191], v[124:127]
	v_mfma_f32_16x16x32_bf16 v[120:123], v[160:163], v[188:191], v[120:123]
	v_mfma_f32_16x16x32_bf16 v[112:115], v[160:163], v[196:199], v[112:115]
	v_mfma_f32_16x16x32_bf16 v[116:119], v[152:155], v[196:199], v[116:119]
	v_mfma_f32_16x16x32_bf16 v[108:111], v[152:155], v[204:207], v[108:111]
	v_mfma_f32_16x16x32_bf16 v[104:107], v[160:163], v[204:207], v[104:107]
	v_mfma_f32_16x16x32_bf16 v[96:99], v[160:163], v[212:215], v[96:99]
	v_mfma_f32_16x16x32_bf16 v[100:103], v[152:155], v[212:215], v[100:103]
	v_mfma_f32_16x16x32_bf16 v[124:127], v[156:159], v[192:195], v[124:127]
	v_mfma_f32_16x16x32_bf16 v[120:123], v[164:167], v[192:195], v[120:123]
	v_mfma_f32_16x16x32_bf16 v[112:115], v[164:167], v[200:203], v[112:115]
	v_mfma_f32_16x16x32_bf16 v[116:119], v[156:159], v[200:203], v[116:119]
	v_mfma_f32_16x16x32_bf16 v[108:111], v[156:159], v[208:211], v[108:111]
	v_mfma_f32_16x16x32_bf16 v[104:107], v[164:167], v[208:211], v[104:107]
	v_mfma_f32_16x16x32_bf16 v[96:99], v[164:167], v[216:219], v[96:99]
	v_mfma_f32_16x16x32_bf16 v[100:103], v[156:159], v[216:219], v[100:103]
	s_setprio 0
	s_setprio 1
	v_mfma_f32_16x16x32_bf16 v[76:79], v[168:171], v[188:191], v[76:79]
	v_mfma_f32_16x16x32_bf16 v[68:71], v[176:179], v[188:191], v[68:71]
	v_mfma_f32_16x16x32_bf16 v[52:55], v[176:179], v[196:199], v[52:55]
	v_mfma_f32_16x16x32_bf16 v[60:63], v[168:171], v[196:199], v[60:63]
	v_mfma_f32_16x16x32_bf16 v[44:47], v[168:171], v[204:207], v[44:47]
	v_mfma_f32_16x16x32_bf16 v[40:43], v[176:179], v[204:207], v[40:43]
	v_mfma_f32_16x16x32_bf16 v[32:35], v[176:179], v[212:215], v[32:35]
	v_mfma_f32_16x16x32_bf16 v[36:39], v[168:171], v[212:215], v[36:39]
	v_mfma_f32_16x16x32_bf16 v[76:79], v[172:175], v[192:195], v[76:79]
	v_mfma_f32_16x16x32_bf16 v[68:71], v[184:187], v[192:195], v[68:71]
	v_mfma_f32_16x16x32_bf16 v[52:55], v[184:187], v[200:203], v[52:55]
	v_mfma_f32_16x16x32_bf16 v[60:63], v[172:175], v[200:203], v[60:63]
	v_mfma_f32_16x16x32_bf16 v[44:47], v[172:175], v[208:211], v[44:47]
	v_mfma_f32_16x16x32_bf16 v[40:43], v[184:187], v[208:211], v[40:43]
	v_mfma_f32_16x16x32_bf16 v[32:35], v[184:187], v[216:219], v[32:35]
	v_mfma_f32_16x16x32_bf16 v[36:39], v[172:175], v[216:219], v[36:39]
	s_setprio 0
	s_barrier
	s_add_i32 s79, s77, s68
	v_lshl_add_u64 v[220:221], s[62:63], 0, v[130:131]
	s_mov_b32 m0, s79
	ds_read_b128 v[188:191], v150 offset:16384
	ds_read_b128 v[192:195], v150 offset:17408
	ds_read_b128 v[196:199], v150 offset:18432
	ds_read_b128 v[200:203], v150 offset:19456
	ds_read_b128 v[204:207], v150 offset:20480
	ds_read_b128 v[208:211], v150 offset:21504
	ds_read_b128 v[212:215], v150 offset:22528
	ds_read_b128 v[216:219], v150 offset:23552
	global_load_lds_dwordx4 v[220:221], off
	s_add_i32 m0, s79, 0x2000
	s_add_u32 s88, s62, 0x40000
	v_lshl_add_u64 v[222:223], s[62:63], 0, v[134:135]
	s_addc_u32 s89, s63, 0
	s_add_i32 s79, s82, s68
	global_load_lds_dwordx4 v[222:223], off
	v_lshl_add_u64 v[224:225], s[88:89], 0, v[130:131]
	s_mov_b32 m0, s79
	v_lshl_add_u64 v[226:227], s[64:65], 0, v[132:133]
	global_load_lds_dwordx4 v[224:225], off
	v_lshl_add_u64 v[224:225], s[88:89], 0, v[134:135]
	s_add_i32 m0, s79, 0x2000
	s_nop 0
	global_load_lds_dwordx4 v[224:225], off
	v_lshl_add_u64 v[224:225], s[64:65], 0, v[128:129]
	s_mov_b32 m0, s69
	s_nop 0
	global_load_lds_dwordx4 v[224:225], off
	s_mov_b32 m0, s70
	s_nop 0
	global_load_lds_dwordx4 v[226:227], off
	s_waitcnt vmcnt(8)
	s_waitcnt lgkmcnt(0)
	s_barrier
	s_setprio 1
	s_waitcnt lgkmcnt(0)
	v_mfma_f32_16x16x32_bf16 v[92:95], v[152:155], v[188:191], v[92:95]
	v_mfma_f32_16x16x32_bf16 v[88:91], v[160:163], v[188:191], v[88:91]
	v_mfma_f32_16x16x32_bf16 v[80:83], v[160:163], v[196:199], v[80:83]
	v_mfma_f32_16x16x32_bf16 v[84:87], v[152:155], v[196:199], v[84:87]
	v_mfma_f32_16x16x32_bf16 v[72:75], v[152:155], v[204:207], v[72:75]
	v_mfma_f32_16x16x32_bf16 v[64:67], v[160:163], v[204:207], v[64:67]
	v_mfma_f32_16x16x32_bf16 v[48:51], v[160:163], v[212:215], v[48:51]
	v_mfma_f32_16x16x32_bf16 v[56:59], v[152:155], v[212:215], v[56:59]
	v_mfma_f32_16x16x32_bf16 v[92:95], v[156:159], v[192:195], v[92:95]
	v_mfma_f32_16x16x32_bf16 v[88:91], v[164:167], v[192:195], v[88:91]
	v_mfma_f32_16x16x32_bf16 v[80:83], v[164:167], v[200:203], v[80:83]
	v_mfma_f32_16x16x32_bf16 v[84:87], v[156:159], v[200:203], v[84:87]
	v_mfma_f32_16x16x32_bf16 v[72:75], v[156:159], v[208:211], v[72:75]
	v_mfma_f32_16x16x32_bf16 v[64:67], v[164:167], v[208:211], v[64:67]
	v_mfma_f32_16x16x32_bf16 v[48:51], v[164:167], v[216:219], v[48:51]
	v_mfma_f32_16x16x32_bf16 v[56:59], v[156:159], v[216:219], v[56:59]
	s_setprio 0
	s_setprio 1
	v_mfma_f32_16x16x32_bf16 v[28:31], v[168:171], v[188:191], v[28:31]
	v_mfma_f32_16x16x32_bf16 v[24:27], v[176:179], v[188:191], v[24:27]
	v_mfma_f32_16x16x32_bf16 v[16:19], v[176:179], v[196:199], v[16:19]
	v_mfma_f32_16x16x32_bf16 v[20:23], v[168:171], v[196:199], v[20:23]
	v_mfma_f32_16x16x32_bf16 v[12:15], v[168:171], v[204:207], v[12:15]
	v_mfma_f32_16x16x32_bf16 v[8:11], v[176:179], v[204:207], v[8:11]
	v_mfma_f32_16x16x32_bf16 v[0:3], v[176:179], v[212:215], v[0:3]
	v_mfma_f32_16x16x32_bf16 v[4:7], v[168:171], v[212:215], v[4:7]
	v_mfma_f32_16x16x32_bf16 v[28:31], v[172:175], v[192:195], v[28:31]
	v_mfma_f32_16x16x32_bf16 v[24:27], v[184:187], v[192:195], v[24:27]
	v_mfma_f32_16x16x32_bf16 v[16:19], v[184:187], v[200:203], v[16:19]
	v_mfma_f32_16x16x32_bf16 v[20:23], v[172:175], v[200:203], v[20:23]
	v_mfma_f32_16x16x32_bf16 v[12:15], v[172:175], v[208:211], v[12:15]
	v_mfma_f32_16x16x32_bf16 v[8:11], v[184:187], v[208:211], v[8:11]
	v_mfma_f32_16x16x32_bf16 v[0:3], v[184:187], v[216:219], v[0:3]
	v_mfma_f32_16x16x32_bf16 v[4:7], v[172:175], v[216:219], v[4:7]
	s_setprio 0
	s_barrier
	s_add_i32 s79, 0, 0x18000
	v_add_u32_e32 v151, s79, v147
	s_add_i32 s88, 0, 0x1c000
	ds_read_b128 v[152:155], v151
	ds_read_b128 v[156:159], v151 offset:1024
	ds_read_b128 v[160:163], v151 offset:2048
	ds_read_b128 v[164:167], v151 offset:3072
	v_add_u32_e32 v151, s88, v147
	ds_read_b128 v[168:171], v151
	ds_read_b128 v[172:175], v151 offset:1024
	ds_read_b128 v[176:179], v151 offset:2048
	ds_read_b128 v[184:187], v151 offset:3072
	s_add_u32 s64, s64, 0x40000
	s_addc_u32 s65, s65, 0
	s_mov_b32 m0, s71
	v_lshl_add_u64 v[228:229], s[64:65], 0, v[128:129]
	ds_read_b128 v[188:191], v150 offset:32768
	ds_read_b128 v[192:195], v150 offset:33792
	ds_read_b128 v[196:199], v150 offset:34816
	ds_read_b128 v[200:203], v150 offset:35840
	ds_read_b128 v[204:207], v150 offset:36864
	ds_read_b128 v[208:211], v150 offset:37888
	ds_read_b128 v[212:215], v150 offset:38912
	ds_read_b128 v[216:219], v150 offset:39936
	global_load_lds_dwordx4 v[228:229], off
	v_lshl_add_u64 v[228:229], s[64:65], 0, v[132:133]
	s_mov_b32 m0, s72
	s_nop 0
	global_load_lds_dwordx4 v[228:229], off
	s_waitcnt vmcnt(8)
	s_waitcnt lgkmcnt(0)
	s_barrier
	s_setprio 1
	s_waitcnt lgkmcnt(0)
	v_mfma_f32_16x16x32_bf16 v[124:127], v[152:155], v[188:191], v[124:127]
	v_mfma_f32_16x16x32_bf16 v[120:123], v[160:163], v[188:191], v[120:123]
	v_mfma_f32_16x16x32_bf16 v[112:115], v[160:163], v[196:199], v[112:115]
	v_mfma_f32_16x16x32_bf16 v[116:119], v[152:155], v[196:199], v[116:119]
	v_mfma_f32_16x16x32_bf16 v[108:111], v[152:155], v[204:207], v[108:111]
	v_mfma_f32_16x16x32_bf16 v[104:107], v[160:163], v[204:207], v[104:107]
	v_mfma_f32_16x16x32_bf16 v[96:99], v[160:163], v[212:215], v[96:99]
	v_mfma_f32_16x16x32_bf16 v[100:103], v[152:155], v[212:215], v[100:103]
	v_mfma_f32_16x16x32_bf16 v[124:127], v[156:159], v[192:195], v[124:127]
	v_mfma_f32_16x16x32_bf16 v[120:123], v[164:167], v[192:195], v[120:123]
	v_mfma_f32_16x16x32_bf16 v[112:115], v[164:167], v[200:203], v[112:115]
	v_mfma_f32_16x16x32_bf16 v[116:119], v[156:159], v[200:203], v[116:119]
	v_mfma_f32_16x16x32_bf16 v[108:111], v[156:159], v[208:211], v[108:111]
	v_mfma_f32_16x16x32_bf16 v[104:107], v[164:167], v[208:211], v[104:107]
	v_mfma_f32_16x16x32_bf16 v[96:99], v[164:167], v[216:219], v[96:99]
	v_mfma_f32_16x16x32_bf16 v[100:103], v[156:159], v[216:219], v[100:103]
	s_setprio 0
	s_setprio 1
	v_mfma_f32_16x16x32_bf16 v[76:79], v[168:171], v[188:191], v[76:79]
	v_mfma_f32_16x16x32_bf16 v[68:71], v[176:179], v[188:191], v[68:71]
	v_mfma_f32_16x16x32_bf16 v[52:55], v[176:179], v[196:199], v[52:55]
	v_mfma_f32_16x16x32_bf16 v[60:63], v[168:171], v[196:199], v[60:63]
	v_mfma_f32_16x16x32_bf16 v[44:47], v[168:171], v[204:207], v[44:47]
	v_mfma_f32_16x16x32_bf16 v[40:43], v[176:179], v[204:207], v[40:43]
	v_mfma_f32_16x16x32_bf16 v[32:35], v[176:179], v[212:215], v[32:35]
	v_mfma_f32_16x16x32_bf16 v[36:39], v[168:171], v[212:215], v[36:39]
	v_mfma_f32_16x16x32_bf16 v[76:79], v[172:175], v[192:195], v[76:79]
	v_mfma_f32_16x16x32_bf16 v[68:71], v[184:187], v[192:195], v[68:71]
	v_mfma_f32_16x16x32_bf16 v[52:55], v[184:187], v[200:203], v[52:55]
	v_mfma_f32_16x16x32_bf16 v[60:63], v[172:175], v[200:203], v[60:63]
	v_mfma_f32_16x16x32_bf16 v[44:47], v[172:175], v[208:211], v[44:47]
	v_mfma_f32_16x16x32_bf16 v[40:43], v[184:187], v[208:211], v[40:43]
	v_mfma_f32_16x16x32_bf16 v[32:35], v[184:187], v[216:219], v[32:35]
	v_mfma_f32_16x16x32_bf16 v[36:39], v[172:175], v[216:219], v[36:39]
	s_setprio 0
	s_barrier
	s_add_i32 s64, s79, s68
	v_lshl_add_u64 v[220:221], v[220:221], 0, s[12:13]
	s_mov_b32 m0, s64
	ds_read_b128 v[188:191], v150 offset:49152
	ds_read_b128 v[192:195], v150 offset:50176
	ds_read_b128 v[196:199], v150 offset:51200
	ds_read_b128 v[200:203], v150 offset:52224
	ds_read_b128 v[204:207], v150 offset:53248
	ds_read_b128 v[208:211], v150 offset:54272
	ds_read_b128 v[212:215], v150 offset:55296
	ds_read_b128 v[216:219], v150 offset:56320
	global_load_lds_dwordx4 v[220:221], off
	s_add_i32 m0, s64, 0x2000
	s_add_u32 s62, s62, 0x40080
	v_lshl_add_u64 v[220:221], v[222:223], 0, s[12:13]
	s_addc_u32 s63, s63, 0
	s_add_i32 s64, s88, s68
	global_load_lds_dwordx4 v[220:221], off
	v_lshl_add_u64 v[220:221], s[62:63], 0, v[130:131]
	s_mov_b32 m0, s64
	s_nop 0
	global_load_lds_dwordx4 v[220:221], off
	v_lshl_add_u64 v[220:221], s[62:63], 0, v[134:135]
	s_add_i32 m0, s64, 0x2000
	s_nop 0
	global_load_lds_dwordx4 v[220:221], off
	v_lshl_add_u64 v[220:221], v[224:225], 0, s[12:13]
	s_mov_b32 m0, s75
	s_nop 0
	global_load_lds_dwordx4 v[220:221], off
	v_lshl_add_u64 v[220:221], v[226:227], 0, s[12:13]
	s_mov_b32 m0, s76
	s_nop 0
	global_load_lds_dwordx4 v[220:221], off
	s_waitcnt vmcnt(8)
	s_waitcnt lgkmcnt(0)
	s_barrier
	s_setprio 1
	s_waitcnt lgkmcnt(0)
	v_mfma_f32_16x16x32_bf16 v[92:95], v[152:155], v[188:191], v[92:95]
	v_mfma_f32_16x16x32_bf16 v[88:91], v[160:163], v[188:191], v[88:91]
	v_mfma_f32_16x16x32_bf16 v[80:83], v[160:163], v[196:199], v[80:83]
	v_mfma_f32_16x16x32_bf16 v[84:87], v[152:155], v[196:199], v[84:87]
	v_mfma_f32_16x16x32_bf16 v[72:75], v[152:155], v[204:207], v[72:75]
	v_mfma_f32_16x16x32_bf16 v[64:67], v[160:163], v[204:207], v[64:67]
	v_mfma_f32_16x16x32_bf16 v[48:51], v[160:163], v[212:215], v[48:51]
	v_mfma_f32_16x16x32_bf16 v[56:59], v[152:155], v[212:215], v[56:59]
	v_mfma_f32_16x16x32_bf16 v[92:95], v[156:159], v[192:195], v[92:95]
	v_mfma_f32_16x16x32_bf16 v[88:91], v[164:167], v[192:195], v[88:91]
	v_mfma_f32_16x16x32_bf16 v[80:83], v[164:167], v[200:203], v[80:83]
	v_mfma_f32_16x16x32_bf16 v[84:87], v[156:159], v[200:203], v[84:87]
	v_mfma_f32_16x16x32_bf16 v[72:75], v[156:159], v[208:211], v[72:75]
	v_mfma_f32_16x16x32_bf16 v[64:67], v[164:167], v[208:211], v[64:67]
	v_mfma_f32_16x16x32_bf16 v[48:51], v[164:167], v[216:219], v[48:51]
	v_mfma_f32_16x16x32_bf16 v[56:59], v[156:159], v[216:219], v[56:59]
	s_setprio 0
	s_setprio 1
	v_mfma_f32_16x16x32_bf16 v[28:31], v[168:171], v[188:191], v[28:31]
	v_mfma_f32_16x16x32_bf16 v[24:27], v[176:179], v[188:191], v[24:27]
	v_mfma_f32_16x16x32_bf16 v[16:19], v[176:179], v[196:199], v[16:19]
	v_mfma_f32_16x16x32_bf16 v[20:23], v[168:171], v[196:199], v[20:23]
	v_mfma_f32_16x16x32_bf16 v[12:15], v[168:171], v[204:207], v[12:15]
	v_mfma_f32_16x16x32_bf16 v[8:11], v[176:179], v[204:207], v[8:11]
	v_mfma_f32_16x16x32_bf16 v[0:3], v[176:179], v[212:215], v[0:3]
	v_mfma_f32_16x16x32_bf16 v[4:7], v[168:171], v[212:215], v[4:7]
	v_mfma_f32_16x16x32_bf16 v[28:31], v[172:175], v[192:195], v[28:31]
	v_mfma_f32_16x16x32_bf16 v[24:27], v[184:187], v[192:195], v[24:27]
	v_mfma_f32_16x16x32_bf16 v[16:19], v[184:187], v[200:203], v[16:19]
	v_mfma_f32_16x16x32_bf16 v[20:23], v[172:175], v[200:203], v[20:23]
	v_mfma_f32_16x16x32_bf16 v[12:15], v[172:175], v[208:211], v[12:15]
	v_mfma_f32_16x16x32_bf16 v[8:11], v[184:187], v[208:211], v[8:11]
	v_mfma_f32_16x16x32_bf16 v[0:3], v[184:187], v[216:219], v[0:3]
	v_mfma_f32_16x16x32_bf16 v[4:7], v[172:175], v[216:219], v[4:7]
	s_setprio 0
	s_barrier
	s_add_i32 s87, s87, 2
	s_add_u32 s60, s60, 0x100
	s_addc_u32 s61, s61, 0
	s_add_u32 s85, s85, 0x100
	s_addc_u32 s86, s86, 0
	s_cmp_gt_u32 s87, 13
	s_cbranch_scc0 .LBB0_935
	s_and_b64 vcc, exec, s[16:17]
	s_cbranch_vccz .LBB0_938
	s_barrier

.LBB0_951:
	ds_read_b128 v[140:143], v147
	ds_read_b128 v[150:153], v147 offset:1024
	ds_read_b128 v[154:157], v147 offset:2048
	ds_read_b128 v[158:161], v147 offset:3072
	ds_read_b128 v[162:165], v148
	ds_read_b128 v[166:169], v148 offset:1024
	ds_read_b128 v[170:173], v148 offset:2048
	ds_read_b128 v[174:177], v148 offset:3072
	s_add_u32 s54, s52, 0xfffc0080
	s_addc_u32 s55, s53, -1
	s_cmp_eq_u32 s76, 12
	s_cselect_b32 s57, s37, s55
	s_cselect_b32 s56, s72, s54
	s_cselect_b32 s55, s19, s75
	s_cselect_b32 s54, s73, s74
	v_lshl_add_u64 v[178:179], s[52:53], 0, v[132:133]
	s_add_i32 m0, s49, 0xc000
	ds_read_b128 v[184:187], v149
	ds_read_b128 v[188:191], v149 offset:1024
	ds_read_b128 v[192:195], v149 offset:2048
	ds_read_b128 v[196:199], v149 offset:3072
	ds_read_b128 v[200:203], v149 offset:4096
	ds_read_b128 v[204:207], v149 offset:5120
	ds_read_b128 v[208:211], v149 offset:6144
	ds_read_b128 v[212:215], v149 offset:7168
	global_load_lds_dwordx4 v[178:179], off
	v_lshl_add_u64 v[178:179], s[52:53], 0, v[134:135]
	s_add_i32 m0, s49, 0xe000
	s_nop 0
	global_load_lds_dwordx4 v[178:179], off
	s_waitcnt vmcnt(8)
	s_waitcnt lgkmcnt(0)
	s_barrier
	s_setprio 1
	s_waitcnt lgkmcnt(0)
	v_mfma_f32_16x16x32_bf16 v[124:127], v[140:143], v[184:187], v[124:127]
	v_mfma_f32_16x16x32_bf16 v[120:123], v[154:157], v[184:187], v[120:123]
	v_mfma_f32_16x16x32_bf16 v[104:107], v[154:157], v[192:195], v[104:107]
	v_mfma_f32_16x16x32_bf16 v[108:111], v[140:143], v[192:195], v[108:111]
	v_mfma_f32_16x16x32_bf16 v[92:95], v[140:143], v[200:203], v[92:95]
	v_mfma_f32_16x16x32_bf16 v[88:91], v[154:157], v[200:203], v[88:91]
	v_mfma_f32_16x16x32_bf16 v[72:75], v[154:157], v[208:211], v[72:75]
	v_mfma_f32_16x16x32_bf16 v[76:79], v[140:143], v[208:211], v[76:79]
	v_mfma_f32_16x16x32_bf16 v[124:127], v[150:153], v[188:191], v[124:127]
	v_mfma_f32_16x16x32_bf16 v[120:123], v[158:161], v[188:191], v[120:123]
	v_mfma_f32_16x16x32_bf16 v[104:107], v[158:161], v[196:199], v[104:107]
	v_mfma_f32_16x16x32_bf16 v[108:111], v[150:153], v[196:199], v[108:111]
	v_mfma_f32_16x16x32_bf16 v[92:95], v[150:153], v[204:207], v[92:95]
	v_mfma_f32_16x16x32_bf16 v[88:91], v[158:161], v[204:207], v[88:91]
	v_mfma_f32_16x16x32_bf16 v[72:75], v[158:161], v[212:215], v[72:75]
	v_mfma_f32_16x16x32_bf16 v[76:79], v[150:153], v[212:215], v[76:79]
	s_setprio 0
	s_setprio 1
	v_mfma_f32_16x16x32_bf16 v[116:119], v[162:165], v[184:187], v[116:119]
	v_mfma_f32_16x16x32_bf16 v[112:115], v[170:173], v[184:187], v[112:115]
	v_mfma_f32_16x16x32_bf16 v[96:99], v[170:173], v[192:195], v[96:99]
	v_mfma_f32_16x16x32_bf16 v[100:103], v[162:165], v[192:195], v[100:103]
	v_mfma_f32_16x16x32_bf16 v[84:87], v[162:165], v[200:203], v[84:87]
	v_mfma_f32_16x16x32_bf16 v[80:83], v[170:173], v[200:203], v[80:83]
	v_mfma_f32_16x16x32_bf16 v[64:67], v[170:173], v[208:211], v[64:67]
	v_mfma_f32_16x16x32_bf16 v[68:71], v[162:165], v[208:211], v[68:71]
	v_mfma_f32_16x16x32_bf16 v[116:119], v[166:169], v[188:191], v[116:119]
	v_mfma_f32_16x16x32_bf16 v[112:115], v[174:177], v[188:191], v[112:115]
	v_mfma_f32_16x16x32_bf16 v[96:99], v[174:177], v[196:199], v[96:99]
	v_mfma_f32_16x16x32_bf16 v[100:103], v[166:169], v[196:199], v[100:103]
	v_mfma_f32_16x16x32_bf16 v[84:87], v[166:169], v[204:207], v[84:87]
	v_mfma_f32_16x16x32_bf16 v[80:83], v[174:177], v[204:207], v[80:83]
	v_mfma_f32_16x16x32_bf16 v[64:67], v[174:177], v[212:215], v[64:67]
	v_mfma_f32_16x16x32_bf16 v[68:71], v[166:169], v[212:215], v[68:71]
	s_setprio 0
	s_barrier
	s_add_i32 s77, s68, s60
	v_lshl_add_u64 v[178:179], s[54:55], 0, v[130:131]
	s_mov_b32 m0, s77
	ds_read_b128 v[184:187], v149 offset:16384
	ds_read_b128 v[188:191], v149 offset:17408
	ds_read_b128 v[192:195], v149 offset:18432
	ds_read_b128 v[196:199], v149 offset:19456
	ds_read_b128 v[200:203], v149 offset:20480
	ds_read_b128 v[204:207], v149 offset:21504
	ds_read_b128 v[208:211], v149 offset:22528
	ds_read_b128 v[212:215], v149 offset:23552
	global_load_lds_dwordx4 v[178:179], off
	s_add_i32 m0, s77, 0x2000
	s_add_u32 s82, s54, 0x40000
	v_lshl_add_u64 v[216:217], s[54:55], 0, v[128:129]
	s_addc_u32 s83, s55, 0
	s_add_i32 s77, s69, s60
	global_load_lds_dwordx4 v[216:217], off
	v_lshl_add_u64 v[218:219], s[82:83], 0, v[130:131]
	s_mov_b32 m0, s77
	v_lshl_add_u64 v[220:221], s[56:57], 0, v[128:129]
	global_load_lds_dwordx4 v[218:219], off
	v_lshl_add_u64 v[218:219], s[82:83], 0, v[128:129]
	s_add_i32 m0, s77, 0x2000
	s_nop 0
	global_load_lds_dwordx4 v[218:219], off
	v_lshl_add_u64 v[218:219], s[56:57], 0, v[130:131]
	s_mov_b32 m0, s49
	s_nop 0
	global_load_lds_dwordx4 v[218:219], off
	s_mov_b32 m0, s62
	s_nop 0
	global_load_lds_dwordx4 v[220:221], off
	s_waitcnt vmcnt(8)
	s_waitcnt lgkmcnt(0)
	s_barrier
	s_setprio 1
	s_waitcnt lgkmcnt(0)
	v_mfma_f32_16x16x32_bf16 v[60:63], v[140:143], v[184:187], v[60:63]
	v_mfma_f32_16x16x32_bf16 v[56:59], v[154:157], v[184:187], v[56:59]
	v_mfma_f32_16x16x32_bf16 v[40:43], v[154:157], v[192:195], v[40:43]
	v_mfma_f32_16x16x32_bf16 v[44:47], v[140:143], v[192:195], v[44:47]
	v_mfma_f32_16x16x32_bf16 v[28:31], v[140:143], v[200:203], v[28:31]
	v_mfma_f32_16x16x32_bf16 v[24:27], v[154:157], v[200:203], v[24:27]
	v_mfma_f32_16x16x32_bf16 v[8:11], v[154:157], v[208:211], v[8:11]
	v_mfma_f32_16x16x32_bf16 v[12:15], v[140:143], v[208:211], v[12:15]
	v_mfma_f32_16x16x32_bf16 v[60:63], v[150:153], v[188:191], v[60:63]
	v_mfma_f32_16x16x32_bf16 v[56:59], v[158:161], v[188:191], v[56:59]
	v_mfma_f32_16x16x32_bf16 v[40:43], v[158:161], v[196:199], v[40:43]
	v_mfma_f32_16x16x32_bf16 v[44:47], v[150:153], v[196:199], v[44:47]
	v_mfma_f32_16x16x32_bf16 v[28:31], v[150:153], v[204:207], v[28:31]
	v_mfma_f32_16x16x32_bf16 v[24:27], v[158:161], v[204:207], v[24:27]
	v_mfma_f32_16x16x32_bf16 v[8:11], v[158:161], v[212:215], v[8:11]
	v_mfma_f32_16x16x32_bf16 v[12:15], v[150:153], v[212:215], v[12:15]
	s_setprio 0
	s_setprio 1
	v_mfma_f32_16x16x32_bf16 v[52:55], v[162:165], v[184:187], v[52:55]
	v_mfma_f32_16x16x32_bf16 v[48:51], v[170:173], v[184:187], v[48:51]
	v_mfma_f32_16x16x32_bf16 v[32:35], v[170:173], v[192:195], v[32:35]
	v_mfma_f32_16x16x32_bf16 v[36:39], v[162:165], v[192:195], v[36:39]
	v_mfma_f32_16x16x32_bf16 v[20:23], v[162:165], v[200:203], v[20:23]
	v_mfma_f32_16x16x32_bf16 v[16:19], v[170:173], v[200:203], v[16:19]
	v_mfma_f32_16x16x32_bf16 v[0:3], v[170:173], v[208:211], v[0:3]
	v_mfma_f32_16x16x32_bf16 v[4:7], v[162:165], v[208:211], v[4:7]
	v_mfma_f32_16x16x32_bf16 v[52:55], v[166:169], v[188:191], v[52:55]
	v_mfma_f32_16x16x32_bf16 v[48:51], v[174:177], v[188:191], v[48:51]
	v_mfma_f32_16x16x32_bf16 v[32:35], v[174:177], v[196:199], v[32:35]
	v_mfma_f32_16x16x32_bf16 v[36:39], v[166:169], v[196:199], v[36:39]
	v_mfma_f32_16x16x32_bf16 v[20:23], v[166:169], v[204:207], v[20:23]
	v_mfma_f32_16x16x32_bf16 v[16:19], v[174:177], v[204:207], v[16:19]
	v_mfma_f32_16x16x32_bf16 v[0:3], v[174:177], v[212:215], v[0:3]
	v_mfma_f32_16x16x32_bf16 v[4:7], v[166:169], v[212:215], v[4:7]
	s_setprio 0
	s_barrier
	s_add_i32 s77, 0, 0x18000
	s_add_i32 s79, 0, 0x1c000
	v_add_u32_e32 v158, s77, v145
	v_add_u32_e32 v174, s79, v145
	ds_read_b128 v[140:143], v158
	ds_read_b128 v[150:153], v158 offset:1024
	ds_read_b128 v[154:157], v158 offset:2048
	ds_read_b128 v[158:161], v158 offset:3072
	ds_read_b128 v[162:165], v174
	ds_read_b128 v[166:169], v174 offset:1024
	ds_read_b128 v[170:173], v174 offset:2048
	ds_read_b128 v[174:177], v174 offset:3072
	s_add_u32 s56, s56, 0x40000
	s_addc_u32 s57, s57, 0
	s_mov_b32 m0, s63
	v_lshl_add_u64 v[222:223], s[56:57], 0, v[130:131]
	ds_read_b128 v[184:187], v149 offset:32768
	ds_read_b128 v[188:191], v149 offset:33792
	ds_read_b128 v[192:195], v149 offset:34816
	ds_read_b128 v[196:199], v149 offset:35840
	ds_read_b128 v[200:203], v149 offset:36864
	ds_read_b128 v[204:207], v149 offset:37888
	ds_read_b128 v[208:211], v149 offset:38912
	ds_read_b128 v[212:215], v149 offset:39936
	global_load_lds_dwordx4 v[222:223], off
	v_lshl_add_u64 v[222:223], s[56:57], 0, v[128:129]
	s_mov_b32 m0, s64
	s_nop 0
	global_load_lds_dwordx4 v[222:223], off
	s_waitcnt vmcnt(8)
	s_waitcnt lgkmcnt(0)
	s_barrier
	s_setprio 1
	s_waitcnt lgkmcnt(0)
	v_mfma_f32_16x16x32_bf16 v[124:127], v[140:143], v[184:187], v[124:127]
	v_mfma_f32_16x16x32_bf16 v[120:123], v[154:157], v[184:187], v[120:123]
	v_mfma_f32_16x16x32_bf16 v[104:107], v[154:157], v[192:195], v[104:107]
	v_mfma_f32_16x16x32_bf16 v[108:111], v[140:143], v[192:195], v[108:111]
	v_mfma_f32_16x16x32_bf16 v[92:95], v[140:143], v[200:203], v[92:95]
	v_mfma_f32_16x16x32_bf16 v[88:91], v[154:157], v[200:203], v[88:91]
	v_mfma_f32_16x16x32_bf16 v[72:75], v[154:157], v[208:211], v[72:75]
	v_mfma_f32_16x16x32_bf16 v[76:79], v[140:143], v[208:211], v[76:79]
	v_mfma_f32_16x16x32_bf16 v[124:127], v[150:153], v[188:191], v[124:127]
	v_mfma_f32_16x16x32_bf16 v[120:123], v[158:161], v[188:191], v[120:123]
	v_mfma_f32_16x16x32_bf16 v[104:107], v[158:161], v[196:199], v[104:107]
	v_mfma_f32_16x16x32_bf16 v[108:111], v[150:153], v[196:199], v[108:111]
	v_mfma_f32_16x16x32_bf16 v[92:95], v[150:153], v[204:207], v[92:95]
	v_mfma_f32_16x16x32_bf16 v[88:91], v[158:161], v[204:207], v[88:91]
	v_mfma_f32_16x16x32_bf16 v[72:75], v[158:161], v[212:215], v[72:75]
	v_mfma_f32_16x16x32_bf16 v[76:79], v[150:153], v[212:215], v[76:79]
	s_setprio 0
	s_setprio 1
	v_mfma_f32_16x16x32_bf16 v[116:119], v[162:165], v[184:187], v[116:119]
	v_mfma_f32_16x16x32_bf16 v[112:115], v[170:173], v[184:187], v[112:115]
	v_mfma_f32_16x16x32_bf16 v[96:99], v[170:173], v[192:195], v[96:99]
	v_mfma_f32_16x16x32_bf16 v[100:103], v[162:165], v[192:195], v[100:103]
	v_mfma_f32_16x16x32_bf16 v[84:87], v[162:165], v[200:203], v[84:87]
	v_mfma_f32_16x16x32_bf16 v[80:83], v[170:173], v[200:203], v[80:83]
	v_mfma_f32_16x16x32_bf16 v[64:67], v[170:173], v[208:211], v[64:67]
	v_mfma_f32_16x16x32_bf16 v[68:71], v[162:165], v[208:211], v[68:71]
	v_mfma_f32_16x16x32_bf16 v[116:119], v[166:169], v[188:191], v[116:119]
	v_mfma_f32_16x16x32_bf16 v[112:115], v[174:177], v[188:191], v[112:115]
	v_mfma_f32_16x16x32_bf16 v[96:99], v[174:177], v[196:199], v[96:99]
	v_mfma_f32_16x16x32_bf16 v[100:103], v[166:169], v[196:199], v[100:103]
	v_mfma_f32_16x16x32_bf16 v[84:87], v[166:169], v[204:207], v[84:87]
	v_mfma_f32_16x16x32_bf16 v[80:83], v[174:177], v[204:207], v[80:83]
	v_mfma_f32_16x16x32_bf16 v[64:67], v[174:177], v[212:215], v[64:67]
	v_mfma_f32_16x16x32_bf16 v[68:71], v[166:169], v[212:215], v[68:71]
	s_setprio 0
	s_barrier
	s_add_i32 s56, s77, s60
	v_lshl_add_u64 v[178:179], v[178:179], 0, s[12:13]
	s_mov_b32 m0, s56
	ds_read_b128 v[184:187], v149 offset:49152
	ds_read_b128 v[188:191], v149 offset:50176
	ds_read_b128 v[192:195], v149 offset:51200
	ds_read_b128 v[196:199], v149 offset:52224
	ds_read_b128 v[200:203], v149 offset:53248
	ds_read_b128 v[204:207], v149 offset:54272
	ds_read_b128 v[208:211], v149 offset:55296
	ds_read_b128 v[212:215], v149 offset:56320
	global_load_lds_dwordx4 v[178:179], off
	s_add_i32 m0, s56, 0x2000
	s_add_u32 s54, s54, 0x40080
	v_lshl_add_u64 v[178:179], v[216:217], 0, s[12:13]
	s_addc_u32 s55, s55, 0
	s_add_i32 s56, s79, s60
	global_load_lds_dwordx4 v[178:179], off
	v_lshl_add_u64 v[178:179], s[54:55], 0, v[130:131]
	s_mov_b32 m0, s56
	s_nop 0
	global_load_lds_dwordx4 v[178:179], off
	v_lshl_add_u64 v[178:179], s[54:55], 0, v[128:129]
	s_add_i32 m0, s56, 0x2000
	s_nop 0
	global_load_lds_dwordx4 v[178:179], off
	v_lshl_add_u64 v[178:179], v[218:219], 0, s[12:13]
	s_mov_b32 m0, s66
	s_nop 0
	global_load_lds_dwordx4 v[178:179], off
	v_lshl_add_u64 v[178:179], v[220:221], 0, s[12:13]
	s_mov_b32 m0, s67
	s_nop 0
	global_load_lds_dwordx4 v[178:179], off
	s_waitcnt vmcnt(8)
	s_waitcnt lgkmcnt(0)
	s_barrier
	s_setprio 1
	s_waitcnt lgkmcnt(0)
	v_mfma_f32_16x16x32_bf16 v[60:63], v[140:143], v[184:187], v[60:63]
	v_mfma_f32_16x16x32_bf16 v[56:59], v[154:157], v[184:187], v[56:59]
	v_mfma_f32_16x16x32_bf16 v[40:43], v[154:157], v[192:195], v[40:43]
	v_mfma_f32_16x16x32_bf16 v[44:47], v[140:143], v[192:195], v[44:47]
	v_mfma_f32_16x16x32_bf16 v[28:31], v[140:143], v[200:203], v[28:31]
	v_mfma_f32_16x16x32_bf16 v[24:27], v[154:157], v[200:203], v[24:27]
	v_mfma_f32_16x16x32_bf16 v[8:11], v[154:157], v[208:211], v[8:11]
	v_mfma_f32_16x16x32_bf16 v[12:15], v[140:143], v[208:211], v[12:15]
	v_mfma_f32_16x16x32_bf16 v[60:63], v[150:153], v[188:191], v[60:63]
	v_mfma_f32_16x16x32_bf16 v[56:59], v[158:161], v[188:191], v[56:59]
	v_mfma_f32_16x16x32_bf16 v[40:43], v[158:161], v[196:199], v[40:43]
	v_mfma_f32_16x16x32_bf16 v[44:47], v[150:153], v[196:199], v[44:47]
	v_mfma_f32_16x16x32_bf16 v[28:31], v[150:153], v[204:207], v[28:31]
	v_mfma_f32_16x16x32_bf16 v[24:27], v[158:161], v[204:207], v[24:27]
	v_mfma_f32_16x16x32_bf16 v[8:11], v[158:161], v[212:215], v[8:11]
	v_mfma_f32_16x16x32_bf16 v[12:15], v[150:153], v[212:215], v[12:15]
	s_setprio 0
	s_setprio 1
	v_mfma_f32_16x16x32_bf16 v[52:55], v[162:165], v[184:187], v[52:55]
	v_mfma_f32_16x16x32_bf16 v[48:51], v[170:173], v[184:187], v[48:51]
	v_mfma_f32_16x16x32_bf16 v[32:35], v[170:173], v[192:195], v[32:35]
	v_mfma_f32_16x16x32_bf16 v[36:39], v[162:165], v[192:195], v[36:39]
	v_mfma_f32_16x16x32_bf16 v[20:23], v[162:165], v[200:203], v[20:23]
	v_mfma_f32_16x16x32_bf16 v[16:19], v[170:173], v[200:203], v[16:19]
	v_mfma_f32_16x16x32_bf16 v[0:3], v[170:173], v[208:211], v[0:3]
	v_mfma_f32_16x16x32_bf16 v[4:7], v[162:165], v[208:211], v[4:7]
	v_mfma_f32_16x16x32_bf16 v[52:55], v[166:169], v[188:191], v[52:55]
	v_mfma_f32_16x16x32_bf16 v[48:51], v[174:177], v[188:191], v[48:51]
	v_mfma_f32_16x16x32_bf16 v[32:35], v[174:177], v[196:199], v[32:35]
	v_mfma_f32_16x16x32_bf16 v[36:39], v[166:169], v[196:199], v[36:39]
	v_mfma_f32_16x16x32_bf16 v[20:23], v[166:169], v[204:207], v[20:23]
	v_mfma_f32_16x16x32_bf16 v[16:19], v[174:177], v[204:207], v[16:19]
	v_mfma_f32_16x16x32_bf16 v[0:3], v[174:177], v[212:215], v[0:3]
	v_mfma_f32_16x16x32_bf16 v[4:7], v[166:169], v[212:215], v[4:7]
	s_setprio 0
	s_barrier
	s_add_i32 s76, s76, 2
	s_add_u32 s52, s52, 0x100
	s_addc_u32 s53, s53, 0
	s_add_u32 s74, s74, 0x100
	s_addc_u32 s75, s75, 0
	s_cmp_gt_u32 s76, 13
	s_cbranch_scc0 .LBB0_951
	s_and_b64 vcc, exec, s[16:17]
	s_cbranch_vccz .LBB0_954
	s_barrier

.LBB0_1031:
	ds_read_b128 v[152:155], v149
	ds_read_b128 v[156:159], v149 offset:1024
	ds_read_b128 v[160:163], v149 offset:2048
	ds_read_b128 v[164:167], v149 offset:3072
	ds_read_b128 v[168:171], v150
	ds_read_b128 v[172:175], v150 offset:1024
	ds_read_b128 v[176:179], v150 offset:2048
	ds_read_b128 v[184:187], v150 offset:3072
	s_add_u32 s56, s54, 0x100
	s_addc_u32 s57, s55, 0
	s_cmp_eq_u32 s88, 40
	s_cselect_b32 s61, s13, s57
	s_cselect_b32 s60, s12, s56
	s_cselect_b32 s59, s53, s87
	s_cselect_b32 s58, s52, s86
	v_lshl_add_u64 v[144:145], s[54:55], 0, v[136:137]
	s_add_i32 m0, s65, 0xc000
	ds_read_b128 v[188:191], v151
	ds_read_b128 v[192:195], v151 offset:1024
	ds_read_b128 v[196:199], v151 offset:2048
	ds_read_b128 v[200:203], v151 offset:3072
	ds_read_b128 v[204:207], v151 offset:4096
	ds_read_b128 v[208:211], v151 offset:5120
	ds_read_b128 v[212:215], v151 offset:6144
	ds_read_b128 v[216:219], v151 offset:7168
	global_load_lds_dwordx4 v[144:145], off
	v_lshl_add_u64 v[144:145], s[54:55], 0, v[138:139]
	s_add_i32 m0, s65, 0xe000
	s_nop 0
	global_load_lds_dwordx4 v[144:145], off
	s_waitcnt vmcnt(8)
	s_waitcnt lgkmcnt(0)
	s_barrier
	s_setprio 1
	s_waitcnt lgkmcnt(0)
	v_mfma_f32_16x16x32_bf16 v[124:127], v[152:155], v[188:191], v[124:127]
	v_mfma_f32_16x16x32_bf16 v[120:123], v[160:163], v[188:191], v[120:123]
	v_mfma_f32_16x16x32_bf16 v[108:111], v[160:163], v[196:199], v[108:111]
	v_mfma_f32_16x16x32_bf16 v[116:119], v[152:155], v[196:199], v[116:119]
	v_mfma_f32_16x16x32_bf16 v[100:103], v[152:155], v[204:207], v[100:103]
	v_mfma_f32_16x16x32_bf16 v[92:95], v[160:163], v[204:207], v[92:95]
	v_mfma_f32_16x16x32_bf16 v[76:79], v[160:163], v[212:215], v[76:79]
	v_mfma_f32_16x16x32_bf16 v[84:87], v[152:155], v[212:215], v[84:87]
	v_mfma_f32_16x16x32_bf16 v[124:127], v[156:159], v[192:195], v[124:127]
	v_mfma_f32_16x16x32_bf16 v[120:123], v[164:167], v[192:195], v[120:123]
	v_mfma_f32_16x16x32_bf16 v[108:111], v[164:167], v[200:203], v[108:111]
	v_mfma_f32_16x16x32_bf16 v[116:119], v[156:159], v[200:203], v[116:119]
	v_mfma_f32_16x16x32_bf16 v[100:103], v[156:159], v[208:211], v[100:103]
	v_mfma_f32_16x16x32_bf16 v[92:95], v[164:167], v[208:211], v[92:95]
	v_mfma_f32_16x16x32_bf16 v[76:79], v[164:167], v[216:219], v[76:79]
	v_mfma_f32_16x16x32_bf16 v[84:87], v[156:159], v[216:219], v[84:87]
	s_setprio 0
	s_setprio 1
	v_mfma_f32_16x16x32_bf16 v[112:115], v[168:171], v[188:191], v[112:115]
	v_mfma_f32_16x16x32_bf16 v[104:107], v[176:179], v[188:191], v[104:107]
	v_mfma_f32_16x16x32_bf16 v[88:91], v[176:179], v[196:199], v[88:91]
	v_mfma_f32_16x16x32_bf16 v[96:99], v[168:171], v[196:199], v[96:99]
	v_mfma_f32_16x16x32_bf16 v[80:83], v[168:171], v[204:207], v[80:83]
	v_mfma_f32_16x16x32_bf16 v[72:75], v[176:179], v[204:207], v[72:75]
	v_mfma_f32_16x16x32_bf16 v[64:67], v[176:179], v[212:215], v[64:67]
	v_mfma_f32_16x16x32_bf16 v[68:71], v[168:171], v[212:215], v[68:71]
	v_mfma_f32_16x16x32_bf16 v[112:115], v[172:175], v[192:195], v[112:115]
	v_mfma_f32_16x16x32_bf16 v[104:107], v[184:187], v[192:195], v[104:107]
	v_mfma_f32_16x16x32_bf16 v[88:91], v[184:187], v[200:203], v[88:91]
	v_mfma_f32_16x16x32_bf16 v[96:99], v[172:175], v[200:203], v[96:99]
	v_mfma_f32_16x16x32_bf16 v[80:83], v[172:175], v[208:211], v[80:83]
	v_mfma_f32_16x16x32_bf16 v[72:75], v[184:187], v[208:211], v[72:75]
	v_mfma_f32_16x16x32_bf16 v[64:67], v[184:187], v[216:219], v[64:67]
	v_mfma_f32_16x16x32_bf16 v[68:71], v[172:175], v[216:219], v[68:71]
	s_setprio 0
	s_barrier
	s_add_i32 s54, s72, s64
	v_lshl_add_u64 v[144:145], s[58:59], 0, v[130:131]
	s_mov_b32 m0, s54
	ds_read_b128 v[188:191], v151 offset:16384
	ds_read_b128 v[192:195], v151 offset:17408
	ds_read_b128 v[196:199], v151 offset:18432
	ds_read_b128 v[200:203], v151 offset:19456
	ds_read_b128 v[204:207], v151 offset:20480
	ds_read_b128 v[208:211], v151 offset:21504
	ds_read_b128 v[212:215], v151 offset:22528
	ds_read_b128 v[216:219], v151 offset:23552
	global_load_lds_dwordx4 v[144:145], off
	s_add_i32 m0, s54, 0x2000
	s_add_u32 s54, s58, 0xb0000
	v_lshl_add_u64 v[220:221], s[58:59], 0, v[134:135]
	s_addc_u32 s55, s59, 0
	s_add_i32 s79, s73, s64
	global_load_lds_dwordx4 v[220:221], off
	v_lshl_add_u64 v[222:223], s[54:55], 0, v[130:131]
	s_mov_b32 m0, s79
	v_lshl_add_u64 v[224:225], s[60:61], 0, v[132:133]
	global_load_lds_dwordx4 v[222:223], off
	v_lshl_add_u64 v[222:223], s[54:55], 0, v[134:135]
	s_add_i32 m0, s79, 0x2000
	s_nop 0
	global_load_lds_dwordx4 v[222:223], off
	v_lshl_add_u64 v[222:223], s[60:61], 0, v[128:129]
	s_mov_b32 m0, s65
	s_nop 0
	global_load_lds_dwordx4 v[222:223], off
	s_mov_b32 m0, s66
	s_nop 0
	global_load_lds_dwordx4 v[224:225], off
	s_waitcnt vmcnt(8)
	s_waitcnt lgkmcnt(0)
	s_barrier
	s_setprio 1
	s_waitcnt lgkmcnt(0)
	v_mfma_f32_16x16x32_bf16 v[60:63], v[152:155], v[188:191], v[60:63]
	v_mfma_f32_16x16x32_bf16 v[56:59], v[160:163], v[188:191], v[56:59]
	v_mfma_f32_16x16x32_bf16 v[44:47], v[160:163], v[196:199], v[44:47]
	v_mfma_f32_16x16x32_bf16 v[52:55], v[152:155], v[196:199], v[52:55]
	v_mfma_f32_16x16x32_bf16 v[36:39], v[152:155], v[204:207], v[36:39]
	v_mfma_f32_16x16x32_bf16 v[28:31], v[160:163], v[204:207], v[28:31]
	v_mfma_f32_16x16x32_bf16 v[12:15], v[160:163], v[212:215], v[12:15]
	v_mfma_f32_16x16x32_bf16 v[20:23], v[152:155], v[212:215], v[20:23]
	v_mfma_f32_16x16x32_bf16 v[60:63], v[156:159], v[192:195], v[60:63]
	v_mfma_f32_16x16x32_bf16 v[56:59], v[164:167], v[192:195], v[56:59]
	v_mfma_f32_16x16x32_bf16 v[44:47], v[164:167], v[200:203], v[44:47]
	v_mfma_f32_16x16x32_bf16 v[52:55], v[156:159], v[200:203], v[52:55]
	v_mfma_f32_16x16x32_bf16 v[36:39], v[156:159], v[208:211], v[36:39]
	v_mfma_f32_16x16x32_bf16 v[28:31], v[164:167], v[208:211], v[28:31]
	v_mfma_f32_16x16x32_bf16 v[12:15], v[164:167], v[216:219], v[12:15]
	v_mfma_f32_16x16x32_bf16 v[20:23], v[156:159], v[216:219], v[20:23]
	s_setprio 0
	s_setprio 1
	v_mfma_f32_16x16x32_bf16 v[48:51], v[168:171], v[188:191], v[48:51]
	v_mfma_f32_16x16x32_bf16 v[40:43], v[176:179], v[188:191], v[40:43]
	v_mfma_f32_16x16x32_bf16 v[24:27], v[176:179], v[196:199], v[24:27]
	v_mfma_f32_16x16x32_bf16 v[32:35], v[168:171], v[196:199], v[32:35]
	v_mfma_f32_16x16x32_bf16 v[16:19], v[168:171], v[204:207], v[16:19]
	v_mfma_f32_16x16x32_bf16 v[8:11], v[176:179], v[204:207], v[8:11]
	v_mfma_f32_16x16x32_bf16 v[0:3], v[176:179], v[212:215], v[0:3]
	v_mfma_f32_16x16x32_bf16 v[4:7], v[168:171], v[212:215], v[4:7]
	v_mfma_f32_16x16x32_bf16 v[48:51], v[172:175], v[192:195], v[48:51]
	v_mfma_f32_16x16x32_bf16 v[40:43], v[184:187], v[192:195], v[40:43]
	v_mfma_f32_16x16x32_bf16 v[24:27], v[184:187], v[200:203], v[24:27]
	v_mfma_f32_16x16x32_bf16 v[32:35], v[172:175], v[200:203], v[32:35]
	v_mfma_f32_16x16x32_bf16 v[16:19], v[172:175], v[208:211], v[16:19]
	v_mfma_f32_16x16x32_bf16 v[8:11], v[184:187], v[208:211], v[8:11]
	v_mfma_f32_16x16x32_bf16 v[0:3], v[184:187], v[216:219], v[0:3]
	v_mfma_f32_16x16x32_bf16 v[4:7], v[172:175], v[216:219], v[4:7]
	s_setprio 0
	s_barrier
	s_add_i32 s79, 0, 0x18000
	s_add_i32 s89, 0, 0x1c000
	v_add_u32_e32 v164, s79, v147
	v_add_u32_e32 v181, s89, v147
	ds_read_b128 v[152:155], v164
	ds_read_b128 v[156:159], v164 offset:1024
	ds_read_b128 v[160:163], v164 offset:2048
	ds_read_b128 v[164:167], v164 offset:3072
	ds_read_b128 v[168:171], v181
	ds_read_b128 v[172:175], v181 offset:1024
	ds_read_b128 v[176:179], v181 offset:2048
	ds_read_b128 v[184:187], v181 offset:3072
	s_add_u32 s54, s60, 0xb0000
	s_addc_u32 s55, s61, 0
	s_mov_b32 m0, s67
	v_lshl_add_u64 v[226:227], s[54:55], 0, v[128:129]
	ds_read_b128 v[188:191], v151 offset:32768
	ds_read_b128 v[192:195], v151 offset:33792
	ds_read_b128 v[196:199], v151 offset:34816
	ds_read_b128 v[200:203], v151 offset:35840
	ds_read_b128 v[204:207], v151 offset:36864
	ds_read_b128 v[208:211], v151 offset:37888
	ds_read_b128 v[212:215], v151 offset:38912
	ds_read_b128 v[216:219], v151 offset:39936
	global_load_lds_dwordx4 v[226:227], off
	v_lshl_add_u64 v[226:227], s[54:55], 0, v[132:133]
	s_mov_b32 m0, s68
	s_nop 0
	global_load_lds_dwordx4 v[226:227], off
	s_waitcnt vmcnt(8)
	s_waitcnt lgkmcnt(0)
	s_barrier
	s_setprio 1
	s_waitcnt lgkmcnt(0)
	v_mfma_f32_16x16x32_bf16 v[124:127], v[152:155], v[188:191], v[124:127]
	v_mfma_f32_16x16x32_bf16 v[120:123], v[160:163], v[188:191], v[120:123]
	v_mfma_f32_16x16x32_bf16 v[108:111], v[160:163], v[196:199], v[108:111]
	v_mfma_f32_16x16x32_bf16 v[116:119], v[152:155], v[196:199], v[116:119]
	v_mfma_f32_16x16x32_bf16 v[100:103], v[152:155], v[204:207], v[100:103]
	v_mfma_f32_16x16x32_bf16 v[92:95], v[160:163], v[204:207], v[92:95]
	v_mfma_f32_16x16x32_bf16 v[76:79], v[160:163], v[212:215], v[76:79]
	v_mfma_f32_16x16x32_bf16 v[84:87], v[152:155], v[212:215], v[84:87]
	v_mfma_f32_16x16x32_bf16 v[124:127], v[156:159], v[192:195], v[124:127]
	v_mfma_f32_16x16x32_bf16 v[120:123], v[164:167], v[192:195], v[120:123]
	v_mfma_f32_16x16x32_bf16 v[108:111], v[164:167], v[200:203], v[108:111]
	v_mfma_f32_16x16x32_bf16 v[116:119], v[156:159], v[200:203], v[116:119]
	v_mfma_f32_16x16x32_bf16 v[100:103], v[156:159], v[208:211], v[100:103]
	v_mfma_f32_16x16x32_bf16 v[92:95], v[164:167], v[208:211], v[92:95]
	v_mfma_f32_16x16x32_bf16 v[76:79], v[164:167], v[216:219], v[76:79]
	v_mfma_f32_16x16x32_bf16 v[84:87], v[156:159], v[216:219], v[84:87]
	s_setprio 0
	s_setprio 1
	v_mfma_f32_16x16x32_bf16 v[112:115], v[168:171], v[188:191], v[112:115]
	v_mfma_f32_16x16x32_bf16 v[104:107], v[176:179], v[188:191], v[104:107]
	v_mfma_f32_16x16x32_bf16 v[88:91], v[176:179], v[196:199], v[88:91]
	v_mfma_f32_16x16x32_bf16 v[96:99], v[168:171], v[196:199], v[96:99]
	v_mfma_f32_16x16x32_bf16 v[80:83], v[168:171], v[204:207], v[80:83]
	v_mfma_f32_16x16x32_bf16 v[72:75], v[176:179], v[204:207], v[72:75]
	v_mfma_f32_16x16x32_bf16 v[64:67], v[176:179], v[212:215], v[64:67]
	v_mfma_f32_16x16x32_bf16 v[68:71], v[168:171], v[212:215], v[68:71]
	v_mfma_f32_16x16x32_bf16 v[112:115], v[172:175], v[192:195], v[112:115]
	v_mfma_f32_16x16x32_bf16 v[104:107], v[184:187], v[192:195], v[104:107]
	v_mfma_f32_16x16x32_bf16 v[88:91], v[184:187], v[200:203], v[88:91]
	v_mfma_f32_16x16x32_bf16 v[96:99], v[172:175], v[200:203], v[96:99]
	v_mfma_f32_16x16x32_bf16 v[80:83], v[172:175], v[208:211], v[80:83]
	v_mfma_f32_16x16x32_bf16 v[72:75], v[184:187], v[208:211], v[72:75]
	v_mfma_f32_16x16x32_bf16 v[64:67], v[184:187], v[216:219], v[64:67]
	v_mfma_f32_16x16x32_bf16 v[68:71], v[172:175], v[216:219], v[68:71]
	s_setprio 0
	s_barrier
	s_add_i32 s54, s79, s64
	v_lshl_add_u64 v[144:145], v[144:145], 0, s[16:17]
	s_mov_b32 m0, s54
	ds_read_b128 v[188:191], v151 offset:49152
	ds_read_b128 v[192:195], v151 offset:50176
	ds_read_b128 v[196:199], v151 offset:51200
	ds_read_b128 v[200:203], v151 offset:52224
	ds_read_b128 v[204:207], v151 offset:53248
	ds_read_b128 v[208:211], v151 offset:54272
	ds_read_b128 v[212:215], v151 offset:55296
	ds_read_b128 v[216:219], v151 offset:56320
	global_load_lds_dwordx4 v[144:145], off
	s_add_i32 m0, s54, 0x2000
	s_add_u32 s54, s58, 0xb0080
	v_lshl_add_u64 v[144:145], v[220:221], 0, s[16:17]
	s_addc_u32 s55, s59, 0
	s_add_i32 s58, s89, s64
	global_load_lds_dwordx4 v[144:145], off
	v_lshl_add_u64 v[144:145], s[54:55], 0, v[130:131]
	s_mov_b32 m0, s58
	s_nop 0
	global_load_lds_dwordx4 v[144:145], off
	v_lshl_add_u64 v[144:145], s[54:55], 0, v[134:135]
	s_add_i32 m0, s58, 0x2000
	s_nop 0
	global_load_lds_dwordx4 v[144:145], off
	v_lshl_add_u64 v[144:145], v[222:223], 0, s[16:17]
	s_mov_b32 m0, s70
	s_nop 0
	global_load_lds_dwordx4 v[144:145], off
	v_lshl_add_u64 v[144:145], v[224:225], 0, s[16:17]
	s_mov_b32 m0, s71
	s_nop 0
	global_load_lds_dwordx4 v[144:145], off
	s_waitcnt vmcnt(8)
	s_waitcnt lgkmcnt(0)
	s_barrier
	s_setprio 1
	s_waitcnt lgkmcnt(0)
	v_mfma_f32_16x16x32_bf16 v[60:63], v[152:155], v[188:191], v[60:63]
	v_mfma_f32_16x16x32_bf16 v[56:59], v[160:163], v[188:191], v[56:59]
	v_mfma_f32_16x16x32_bf16 v[44:47], v[160:163], v[196:199], v[44:47]
	v_mfma_f32_16x16x32_bf16 v[52:55], v[152:155], v[196:199], v[52:55]
	v_mfma_f32_16x16x32_bf16 v[36:39], v[152:155], v[204:207], v[36:39]
	v_mfma_f32_16x16x32_bf16 v[28:31], v[160:163], v[204:207], v[28:31]
	v_mfma_f32_16x16x32_bf16 v[12:15], v[160:163], v[212:215], v[12:15]
	v_mfma_f32_16x16x32_bf16 v[20:23], v[152:155], v[212:215], v[20:23]
	v_mfma_f32_16x16x32_bf16 v[60:63], v[156:159], v[192:195], v[60:63]
	v_mfma_f32_16x16x32_bf16 v[56:59], v[164:167], v[192:195], v[56:59]
	v_mfma_f32_16x16x32_bf16 v[44:47], v[164:167], v[200:203], v[44:47]
	v_mfma_f32_16x16x32_bf16 v[52:55], v[156:159], v[200:203], v[52:55]
	v_mfma_f32_16x16x32_bf16 v[36:39], v[156:159], v[208:211], v[36:39]
	v_mfma_f32_16x16x32_bf16 v[28:31], v[164:167], v[208:211], v[28:31]
	v_mfma_f32_16x16x32_bf16 v[12:15], v[164:167], v[216:219], v[12:15]
	v_mfma_f32_16x16x32_bf16 v[20:23], v[156:159], v[216:219], v[20:23]
	s_setprio 0
	s_setprio 1
	v_mfma_f32_16x16x32_bf16 v[48:51], v[168:171], v[188:191], v[48:51]
	v_mfma_f32_16x16x32_bf16 v[40:43], v[176:179], v[188:191], v[40:43]
	v_mfma_f32_16x16x32_bf16 v[24:27], v[176:179], v[196:199], v[24:27]
	v_mfma_f32_16x16x32_bf16 v[32:35], v[168:171], v[196:199], v[32:35]
	v_mfma_f32_16x16x32_bf16 v[16:19], v[168:171], v[204:207], v[16:19]
	v_mfma_f32_16x16x32_bf16 v[8:11], v[176:179], v[204:207], v[8:11]
	v_mfma_f32_16x16x32_bf16 v[0:3], v[176:179], v[212:215], v[0:3]
	v_mfma_f32_16x16x32_bf16 v[4:7], v[168:171], v[212:215], v[4:7]
	v_mfma_f32_16x16x32_bf16 v[48:51], v[172:175], v[192:195], v[48:51]
	v_mfma_f32_16x16x32_bf16 v[40:43], v[184:187], v[192:195], v[40:43]
	v_mfma_f32_16x16x32_bf16 v[24:27], v[184:187], v[200:203], v[24:27]
	v_mfma_f32_16x16x32_bf16 v[32:35], v[172:175], v[200:203], v[32:35]
	v_mfma_f32_16x16x32_bf16 v[16:19], v[172:175], v[208:211], v[16:19]
	v_mfma_f32_16x16x32_bf16 v[8:11], v[184:187], v[208:211], v[8:11]
	v_mfma_f32_16x16x32_bf16 v[0:3], v[184:187], v[216:219], v[0:3]
	v_mfma_f32_16x16x32_bf16 v[4:7], v[172:175], v[216:219], v[4:7]
	s_setprio 0
	s_barrier
	s_add_i32 s88, s88, 2
	s_add_u32 s86, s86, 0x100
	s_addc_u32 s87, s87, 0
	s_cmp_gt_u32 s88, 41
	s_mov_b64 s[54:55], s[56:57]
	s_cbranch_scc0 .LBB0_1031
	s_and_b64 vcc, exec, s[18:19]
	s_cbranch_vccz .LBB0_1034
	s_barrier

.LBB0_1162:
	ds_read_b128 v[152:155], v148
	ds_read_b128 v[156:159], v148 offset:1024
	ds_read_b128 v[160:163], v148 offset:2048
	ds_read_b128 v[164:167], v148 offset:3072
	ds_read_b128 v[168:171], v149
	ds_read_b128 v[172:175], v149 offset:1024
	ds_read_b128 v[176:179], v149 offset:2048
	ds_read_b128 v[184:187], v149 offset:3072
	s_add_u32 s62, s60, 0xfffc0080
	s_addc_u32 s63, s61, -1
	s_cmp_eq_u32 s87, 12
	s_cselect_b32 s65, s53, s63
	s_cselect_b32 s64, s83, s62
	s_cselect_b32 s63, s49, s86
	s_cselect_b32 s62, s84, s85
	v_lshl_add_u64 v[220:221], s[60:61], 0, v[138:139]
	s_add_i32 m0, s69, 0xc000
	ds_read_b128 v[188:191], v150
	ds_read_b128 v[192:195], v150 offset:1024
	ds_read_b128 v[196:199], v150 offset:2048
	ds_read_b128 v[200:203], v150 offset:3072
	ds_read_b128 v[204:207], v150 offset:4096
	ds_read_b128 v[208:211], v150 offset:5120
	ds_read_b128 v[212:215], v150 offset:6144
	ds_read_b128 v[216:219], v150 offset:7168
	global_load_lds_dwordx4 v[220:221], off
	v_lshl_add_u64 v[220:221], s[60:61], 0, v[140:141]
	s_add_i32 m0, s69, 0xe000
	s_nop 0
	global_load_lds_dwordx4 v[220:221], off
	s_waitcnt vmcnt(8)
	s_waitcnt lgkmcnt(0)
	s_barrier
	s_setprio 1
	s_waitcnt lgkmcnt(0)
	v_mfma_f32_16x16x32_bf16 v[124:127], v[152:155], v[188:191], v[124:127]
	v_mfma_f32_16x16x32_bf16 v[120:123], v[160:163], v[188:191], v[120:123]
	v_mfma_f32_16x16x32_bf16 v[112:115], v[160:163], v[196:199], v[112:115]
	v_mfma_f32_16x16x32_bf16 v[116:119], v[152:155], v[196:199], v[116:119]
	v_mfma_f32_16x16x32_bf16 v[108:111], v[152:155], v[204:207], v[108:111]
	v_mfma_f32_16x16x32_bf16 v[104:107], v[160:163], v[204:207], v[104:107]
	v_mfma_f32_16x16x32_bf16 v[96:99], v[160:163], v[212:215], v[96:99]
	v_mfma_f32_16x16x32_bf16 v[100:103], v[152:155], v[212:215], v[100:103]
	v_mfma_f32_16x16x32_bf16 v[124:127], v[156:159], v[192:195], v[124:127]
	v_mfma_f32_16x16x32_bf16 v[120:123], v[164:167], v[192:195], v[120:123]
	v_mfma_f32_16x16x32_bf16 v[112:115], v[164:167], v[200:203], v[112:115]
	v_mfma_f32_16x16x32_bf16 v[116:119], v[156:159], v[200:203], v[116:119]
	v_mfma_f32_16x16x32_bf16 v[108:111], v[156:159], v[208:211], v[108:111]
	v_mfma_f32_16x16x32_bf16 v[104:107], v[164:167], v[208:211], v[104:107]
	v_mfma_f32_16x16x32_bf16 v[96:99], v[164:167], v[216:219], v[96:99]
	v_mfma_f32_16x16x32_bf16 v[100:103], v[156:159], v[216:219], v[100:103]
	s_setprio 0
	s_setprio 1
	v_mfma_f32_16x16x32_bf16 v[68:71], v[168:171], v[188:191], v[68:71]
	v_mfma_f32_16x16x32_bf16 v[64:67], v[176:179], v[188:191], v[64:67]
	v_mfma_f32_16x16x32_bf16 v[48:51], v[176:179], v[196:199], v[48:51]
	v_mfma_f32_16x16x32_bf16 v[52:55], v[168:171], v[196:199], v[52:55]
	v_mfma_f32_16x16x32_bf16 v[44:47], v[168:171], v[204:207], v[44:47]
	v_mfma_f32_16x16x32_bf16 v[40:43], v[176:179], v[204:207], v[40:43]
	v_mfma_f32_16x16x32_bf16 v[32:35], v[176:179], v[212:215], v[32:35]
	v_mfma_f32_16x16x32_bf16 v[36:39], v[168:171], v[212:215], v[36:39]
	v_mfma_f32_16x16x32_bf16 v[68:71], v[172:175], v[192:195], v[68:71]
	v_mfma_f32_16x16x32_bf16 v[64:67], v[184:187], v[192:195], v[64:67]
	v_mfma_f32_16x16x32_bf16 v[48:51], v[184:187], v[200:203], v[48:51]
	v_mfma_f32_16x16x32_bf16 v[52:55], v[172:175], v[200:203], v[52:55]
	v_mfma_f32_16x16x32_bf16 v[44:47], v[172:175], v[208:211], v[44:47]
	v_mfma_f32_16x16x32_bf16 v[40:43], v[184:187], v[208:211], v[40:43]
	v_mfma_f32_16x16x32_bf16 v[32:35], v[184:187], v[216:219], v[32:35]
	v_mfma_f32_16x16x32_bf16 v[36:39], v[172:175], v[216:219], v[36:39]
	s_setprio 0
	s_barrier
	s_add_i32 s79, s77, s68
	v_lshl_add_u64 v[220:221], s[62:63], 0, v[130:131]
	s_mov_b32 m0, s79
	ds_read_b128 v[188:191], v150 offset:16384
	ds_read_b128 v[192:195], v150 offset:17408
	ds_read_b128 v[196:199], v150 offset:18432
	ds_read_b128 v[200:203], v150 offset:19456
	ds_read_b128 v[204:207], v150 offset:20480
	ds_read_b128 v[208:211], v150 offset:21504
	ds_read_b128 v[212:215], v150 offset:22528
	ds_read_b128 v[216:219], v150 offset:23552
	global_load_lds_dwordx4 v[220:221], off
	s_add_i32 m0, s79, 0x2000
	s_add_u32 s88, s62, 0x40000
	v_lshl_add_u64 v[222:223], s[62:63], 0, v[134:135]
	s_addc_u32 s89, s63, 0
	s_add_i32 s79, s82, s68
	global_load_lds_dwordx4 v[222:223], off
	v_lshl_add_u64 v[224:225], s[88:89], 0, v[130:131]
	s_mov_b32 m0, s79
	v_lshl_add_u64 v[226:227], s[64:65], 0, v[132:133]
	global_load_lds_dwordx4 v[224:225], off
	v_lshl_add_u64 v[224:225], s[88:89], 0, v[134:135]
	s_add_i32 m0, s79, 0x2000
	s_nop 0
	global_load_lds_dwordx4 v[224:225], off
	v_lshl_add_u64 v[224:225], s[64:65], 0, v[128:129]
	s_mov_b32 m0, s69
	s_nop 0
	global_load_lds_dwordx4 v[224:225], off
	s_mov_b32 m0, s70
	s_nop 0
	global_load_lds_dwordx4 v[226:227], off
	s_waitcnt vmcnt(8)
	s_waitcnt lgkmcnt(0)
	s_barrier
	s_setprio 1
	s_waitcnt lgkmcnt(0)
	v_mfma_f32_16x16x32_bf16 v[92:95], v[152:155], v[188:191], v[92:95]
	v_mfma_f32_16x16x32_bf16 v[88:91], v[160:163], v[188:191], v[88:91]
	v_mfma_f32_16x16x32_bf16 v[80:83], v[160:163], v[196:199], v[80:83]
	v_mfma_f32_16x16x32_bf16 v[84:87], v[152:155], v[196:199], v[84:87]
	v_mfma_f32_16x16x32_bf16 v[76:79], v[152:155], v[204:207], v[76:79]
	v_mfma_f32_16x16x32_bf16 v[72:75], v[160:163], v[204:207], v[72:75]
	v_mfma_f32_16x16x32_bf16 v[56:59], v[160:163], v[212:215], v[56:59]
	v_mfma_f32_16x16x32_bf16 v[60:63], v[152:155], v[212:215], v[60:63]
	v_mfma_f32_16x16x32_bf16 v[92:95], v[156:159], v[192:195], v[92:95]
	v_mfma_f32_16x16x32_bf16 v[88:91], v[164:167], v[192:195], v[88:91]
	v_mfma_f32_16x16x32_bf16 v[80:83], v[164:167], v[200:203], v[80:83]
	v_mfma_f32_16x16x32_bf16 v[84:87], v[156:159], v[200:203], v[84:87]
	v_mfma_f32_16x16x32_bf16 v[76:79], v[156:159], v[208:211], v[76:79]
	v_mfma_f32_16x16x32_bf16 v[72:75], v[164:167], v[208:211], v[72:75]
	v_mfma_f32_16x16x32_bf16 v[56:59], v[164:167], v[216:219], v[56:59]
	v_mfma_f32_16x16x32_bf16 v[60:63], v[156:159], v[216:219], v[60:63]
	s_setprio 0
	s_setprio 1
	v_mfma_f32_16x16x32_bf16 v[28:31], v[168:171], v[188:191], v[28:31]
	v_mfma_f32_16x16x32_bf16 v[24:27], v[176:179], v[188:191], v[24:27]
	v_mfma_f32_16x16x32_bf16 v[16:19], v[176:179], v[196:199], v[16:19]
	v_mfma_f32_16x16x32_bf16 v[20:23], v[168:171], v[196:199], v[20:23]
	v_mfma_f32_16x16x32_bf16 v[12:15], v[168:171], v[204:207], v[12:15]
	v_mfma_f32_16x16x32_bf16 v[8:11], v[176:179], v[204:207], v[8:11]
	v_mfma_f32_16x16x32_bf16 v[0:3], v[176:179], v[212:215], v[0:3]
	v_mfma_f32_16x16x32_bf16 v[4:7], v[168:171], v[212:215], v[4:7]
	v_mfma_f32_16x16x32_bf16 v[28:31], v[172:175], v[192:195], v[28:31]
	v_mfma_f32_16x16x32_bf16 v[24:27], v[184:187], v[192:195], v[24:27]
	v_mfma_f32_16x16x32_bf16 v[16:19], v[184:187], v[200:203], v[16:19]
	v_mfma_f32_16x16x32_bf16 v[20:23], v[172:175], v[200:203], v[20:23]
	v_mfma_f32_16x16x32_bf16 v[12:15], v[172:175], v[208:211], v[12:15]
	v_mfma_f32_16x16x32_bf16 v[8:11], v[184:187], v[208:211], v[8:11]
	v_mfma_f32_16x16x32_bf16 v[0:3], v[184:187], v[216:219], v[0:3]
	v_mfma_f32_16x16x32_bf16 v[4:7], v[172:175], v[216:219], v[4:7]
	s_setprio 0
	s_barrier
	s_add_i32 s79, 0, 0x18000
	s_add_i32 s88, 0, 0x1c000
	v_add_u32_e32 v164, s79, v147
	v_add_u32_e32 v181, s88, v147
	ds_read_b128 v[152:155], v164
	ds_read_b128 v[156:159], v164 offset:1024
	ds_read_b128 v[160:163], v164 offset:2048
	ds_read_b128 v[164:167], v164 offset:3072
	ds_read_b128 v[168:171], v181
	ds_read_b128 v[172:175], v181 offset:1024
	ds_read_b128 v[176:179], v181 offset:2048
	ds_read_b128 v[184:187], v181 offset:3072
	s_add_u32 s64, s64, 0x40000
	s_addc_u32 s65, s65, 0
	s_mov_b32 m0, s71
	v_lshl_add_u64 v[228:229], s[64:65], 0, v[128:129]
	ds_read_b128 v[188:191], v150 offset:32768
	ds_read_b128 v[192:195], v150 offset:33792
	ds_read_b128 v[196:199], v150 offset:34816
	ds_read_b128 v[200:203], v150 offset:35840
	ds_read_b128 v[204:207], v150 offset:36864
	ds_read_b128 v[208:211], v150 offset:37888
	ds_read_b128 v[212:215], v150 offset:38912
	ds_read_b128 v[216:219], v150 offset:39936
	global_load_lds_dwordx4 v[228:229], off
	v_lshl_add_u64 v[228:229], s[64:65], 0, v[132:133]
	s_mov_b32 m0, s72
	s_nop 0
	global_load_lds_dwordx4 v[228:229], off
	s_waitcnt vmcnt(8)
	s_waitcnt lgkmcnt(0)
	s_barrier
	s_setprio 1
	s_waitcnt lgkmcnt(0)
	v_mfma_f32_16x16x32_bf16 v[124:127], v[152:155], v[188:191], v[124:127]
	v_mfma_f32_16x16x32_bf16 v[120:123], v[160:163], v[188:191], v[120:123]
	v_mfma_f32_16x16x32_bf16 v[112:115], v[160:163], v[196:199], v[112:115]
	v_mfma_f32_16x16x32_bf16 v[116:119], v[152:155], v[196:199], v[116:119]
	v_mfma_f32_16x16x32_bf16 v[108:111], v[152:155], v[204:207], v[108:111]
	v_mfma_f32_16x16x32_bf16 v[104:107], v[160:163], v[204:207], v[104:107]
	v_mfma_f32_16x16x32_bf16 v[96:99], v[160:163], v[212:215], v[96:99]
	v_mfma_f32_16x16x32_bf16 v[100:103], v[152:155], v[212:215], v[100:103]
	v_mfma_f32_16x16x32_bf16 v[124:127], v[156:159], v[192:195], v[124:127]
	v_mfma_f32_16x16x32_bf16 v[120:123], v[164:167], v[192:195], v[120:123]
	v_mfma_f32_16x16x32_bf16 v[112:115], v[164:167], v[200:203], v[112:115]
	v_mfma_f32_16x16x32_bf16 v[116:119], v[156:159], v[200:203], v[116:119]
	v_mfma_f32_16x16x32_bf16 v[108:111], v[156:159], v[208:211], v[108:111]
	v_mfma_f32_16x16x32_bf16 v[104:107], v[164:167], v[208:211], v[104:107]
	v_mfma_f32_16x16x32_bf16 v[96:99], v[164:167], v[216:219], v[96:99]
	v_mfma_f32_16x16x32_bf16 v[100:103], v[156:159], v[216:219], v[100:103]
	s_setprio 0
	s_setprio 1
	v_mfma_f32_16x16x32_bf16 v[68:71], v[168:171], v[188:191], v[68:71]
	v_mfma_f32_16x16x32_bf16 v[64:67], v[176:179], v[188:191], v[64:67]
	v_mfma_f32_16x16x32_bf16 v[48:51], v[176:179], v[196:199], v[48:51]
	v_mfma_f32_16x16x32_bf16 v[52:55], v[168:171], v[196:199], v[52:55]
	v_mfma_f32_16x16x32_bf16 v[44:47], v[168:171], v[204:207], v[44:47]
	v_mfma_f32_16x16x32_bf16 v[40:43], v[176:179], v[204:207], v[40:43]
	v_mfma_f32_16x16x32_bf16 v[32:35], v[176:179], v[212:215], v[32:35]
	v_mfma_f32_16x16x32_bf16 v[36:39], v[168:171], v[212:215], v[36:39]
	v_mfma_f32_16x16x32_bf16 v[68:71], v[172:175], v[192:195], v[68:71]
	v_mfma_f32_16x16x32_bf16 v[64:67], v[184:187], v[192:195], v[64:67]
	v_mfma_f32_16x16x32_bf16 v[48:51], v[184:187], v[200:203], v[48:51]
	v_mfma_f32_16x16x32_bf16 v[52:55], v[172:175], v[200:203], v[52:55]
	v_mfma_f32_16x16x32_bf16 v[44:47], v[172:175], v[208:211], v[44:47]
	v_mfma_f32_16x16x32_bf16 v[40:43], v[184:187], v[208:211], v[40:43]
	v_mfma_f32_16x16x32_bf16 v[32:35], v[184:187], v[216:219], v[32:35]
	v_mfma_f32_16x16x32_bf16 v[36:39], v[172:175], v[216:219], v[36:39]
	s_setprio 0
	s_barrier
	s_add_i32 s64, s79, s68
	v_lshl_add_u64 v[220:221], v[220:221], 0, s[12:13]
	s_mov_b32 m0, s64
	ds_read_b128 v[188:191], v150 offset:49152
	ds_read_b128 v[192:195], v150 offset:50176
	ds_read_b128 v[196:199], v150 offset:51200
	ds_read_b128 v[200:203], v150 offset:52224
	ds_read_b128 v[204:207], v150 offset:53248
	ds_read_b128 v[208:211], v150 offset:54272
	ds_read_b128 v[212:215], v150 offset:55296
	ds_read_b128 v[216:219], v150 offset:56320
	global_load_lds_dwordx4 v[220:221], off
	s_add_i32 m0, s64, 0x2000
	s_add_u32 s62, s62, 0x40080
	v_lshl_add_u64 v[220:221], v[222:223], 0, s[12:13]
	s_addc_u32 s63, s63, 0
	s_add_i32 s64, s88, s68
	global_load_lds_dwordx4 v[220:221], off
	v_lshl_add_u64 v[220:221], s[62:63], 0, v[130:131]
	s_mov_b32 m0, s64
	s_nop 0
	global_load_lds_dwordx4 v[220:221], off
	v_lshl_add_u64 v[220:221], s[62:63], 0, v[134:135]
	s_add_i32 m0, s64, 0x2000
	s_nop 0
	global_load_lds_dwordx4 v[220:221], off
	v_lshl_add_u64 v[220:221], v[224:225], 0, s[12:13]
	s_mov_b32 m0, s75
	s_nop 0
	global_load_lds_dwordx4 v[220:221], off
	v_lshl_add_u64 v[220:221], v[226:227], 0, s[12:13]
	s_mov_b32 m0, s76
	s_nop 0
	global_load_lds_dwordx4 v[220:221], off
	s_waitcnt vmcnt(8)
	s_waitcnt lgkmcnt(0)
	s_barrier
	s_setprio 1
	s_waitcnt lgkmcnt(0)
	v_mfma_f32_16x16x32_bf16 v[92:95], v[152:155], v[188:191], v[92:95]
	v_mfma_f32_16x16x32_bf16 v[88:91], v[160:163], v[188:191], v[88:91]
	v_mfma_f32_16x16x32_bf16 v[80:83], v[160:163], v[196:199], v[80:83]
	v_mfma_f32_16x16x32_bf16 v[84:87], v[152:155], v[196:199], v[84:87]
	v_mfma_f32_16x16x32_bf16 v[76:79], v[152:155], v[204:207], v[76:79]
	v_mfma_f32_16x16x32_bf16 v[72:75], v[160:163], v[204:207], v[72:75]
	v_mfma_f32_16x16x32_bf16 v[56:59], v[160:163], v[212:215], v[56:59]
	v_mfma_f32_16x16x32_bf16 v[60:63], v[152:155], v[212:215], v[60:63]
	v_mfma_f32_16x16x32_bf16 v[92:95], v[156:159], v[192:195], v[92:95]
	v_mfma_f32_16x16x32_bf16 v[88:91], v[164:167], v[192:195], v[88:91]
	v_mfma_f32_16x16x32_bf16 v[80:83], v[164:167], v[200:203], v[80:83]
	v_mfma_f32_16x16x32_bf16 v[84:87], v[156:159], v[200:203], v[84:87]
	v_mfma_f32_16x16x32_bf16 v[76:79], v[156:159], v[208:211], v[76:79]
	v_mfma_f32_16x16x32_bf16 v[72:75], v[164:167], v[208:211], v[72:75]
	v_mfma_f32_16x16x32_bf16 v[56:59], v[164:167], v[216:219], v[56:59]
	v_mfma_f32_16x16x32_bf16 v[60:63], v[156:159], v[216:219], v[60:63]
	s_setprio 0
	s_setprio 1
	v_mfma_f32_16x16x32_bf16 v[28:31], v[168:171], v[188:191], v[28:31]
	v_mfma_f32_16x16x32_bf16 v[24:27], v[176:179], v[188:191], v[24:27]
	v_mfma_f32_16x16x32_bf16 v[16:19], v[176:179], v[196:199], v[16:19]
	v_mfma_f32_16x16x32_bf16 v[20:23], v[168:171], v[196:199], v[20:23]
	v_mfma_f32_16x16x32_bf16 v[12:15], v[168:171], v[204:207], v[12:15]
	v_mfma_f32_16x16x32_bf16 v[8:11], v[176:179], v[204:207], v[8:11]
	v_mfma_f32_16x16x32_bf16 v[0:3], v[176:179], v[212:215], v[0:3]
	v_mfma_f32_16x16x32_bf16 v[4:7], v[168:171], v[212:215], v[4:7]
	v_mfma_f32_16x16x32_bf16 v[28:31], v[172:175], v[192:195], v[28:31]
	v_mfma_f32_16x16x32_bf16 v[24:27], v[184:187], v[192:195], v[24:27]
	v_mfma_f32_16x16x32_bf16 v[16:19], v[184:187], v[200:203], v[16:19]
	v_mfma_f32_16x16x32_bf16 v[20:23], v[172:175], v[200:203], v[20:23]
	v_mfma_f32_16x16x32_bf16 v[12:15], v[172:175], v[208:211], v[12:15]
	v_mfma_f32_16x16x32_bf16 v[8:11], v[184:187], v[208:211], v[8:11]
	v_mfma_f32_16x16x32_bf16 v[0:3], v[184:187], v[216:219], v[0:3]
	v_mfma_f32_16x16x32_bf16 v[4:7], v[172:175], v[216:219], v[4:7]
	s_setprio 0
	s_barrier
	s_add_i32 s87, s87, 2
	s_add_u32 s60, s60, 0x100
	s_addc_u32 s61, s61, 0
	s_add_u32 s85, s85, 0x100
	s_addc_u32 s86, s86, 0
	s_cmp_gt_u32 s87, 13
	s_cbranch_scc0 .LBB0_1162
	s_and_b64 vcc, exec, s[16:17]
	s_cbranch_vccz .LBB0_1165
	s_barrier

.LBB0_1311:
	ds_read_b128 v[152:155], v149
	ds_read_b128 v[156:159], v149 offset:1024
	ds_read_b128 v[160:163], v149 offset:2048
	ds_read_b128 v[164:167], v149 offset:3072
	ds_read_b128 v[168:171], v150
	ds_read_b128 v[172:175], v150 offset:1024
	ds_read_b128 v[176:179], v150 offset:2048
	ds_read_b128 v[184:187], v150 offset:3072
	s_add_u32 s58, s56, 0xfffc0080
	s_addc_u32 s59, s57, -1
	s_cmp_eq_u32 s86, 12
	s_cselect_b32 s61, s49, s59
	s_cselect_b32 s60, s82, s58
	s_cselect_b32 s59, s47, s85
	s_cselect_b32 s58, s83, s84
	v_lshl_add_u64 v[144:145], s[56:57], 0, v[136:137]
	s_add_i32 m0, s55, 0xc000
	ds_read_b128 v[188:191], v151
	ds_read_b128 v[192:195], v151 offset:1024
	ds_read_b128 v[196:199], v151 offset:2048
	ds_read_b128 v[200:203], v151 offset:3072
	ds_read_b128 v[204:207], v151 offset:4096
	ds_read_b128 v[208:211], v151 offset:5120
	ds_read_b128 v[212:215], v151 offset:6144
	ds_read_b128 v[216:219], v151 offset:7168
	global_load_lds_dwordx4 v[144:145], off
	v_lshl_add_u64 v[144:145], s[56:57], 0, v[138:139]
	s_add_i32 m0, s55, 0xe000
	s_nop 0
	global_load_lds_dwordx4 v[144:145], off
	s_waitcnt vmcnt(8)
	s_waitcnt lgkmcnt(0)
	s_barrier
	s_setprio 1
	s_waitcnt lgkmcnt(0)
	v_mfma_f32_16x16x32_bf16 v[124:127], v[152:155], v[188:191], v[124:127]
	v_mfma_f32_16x16x32_bf16 v[120:123], v[160:163], v[188:191], v[120:123]
	v_mfma_f32_16x16x32_bf16 v[108:111], v[160:163], v[196:199], v[108:111]
	v_mfma_f32_16x16x32_bf16 v[116:119], v[152:155], v[196:199], v[116:119]
	v_mfma_f32_16x16x32_bf16 v[100:103], v[152:155], v[204:207], v[100:103]
	v_mfma_f32_16x16x32_bf16 v[92:95], v[160:163], v[204:207], v[92:95]
	v_mfma_f32_16x16x32_bf16 v[76:79], v[160:163], v[212:215], v[76:79]
	v_mfma_f32_16x16x32_bf16 v[84:87], v[152:155], v[212:215], v[84:87]
	v_mfma_f32_16x16x32_bf16 v[124:127], v[156:159], v[192:195], v[124:127]
	v_mfma_f32_16x16x32_bf16 v[120:123], v[164:167], v[192:195], v[120:123]
	v_mfma_f32_16x16x32_bf16 v[108:111], v[164:167], v[200:203], v[108:111]
	v_mfma_f32_16x16x32_bf16 v[116:119], v[156:159], v[200:203], v[116:119]
	v_mfma_f32_16x16x32_bf16 v[100:103], v[156:159], v[208:211], v[100:103]
	v_mfma_f32_16x16x32_bf16 v[92:95], v[164:167], v[208:211], v[92:95]
	v_mfma_f32_16x16x32_bf16 v[76:79], v[164:167], v[216:219], v[76:79]
	v_mfma_f32_16x16x32_bf16 v[84:87], v[156:159], v[216:219], v[84:87]
	s_setprio 0
	s_setprio 1
	v_mfma_f32_16x16x32_bf16 v[112:115], v[168:171], v[188:191], v[112:115]
	v_mfma_f32_16x16x32_bf16 v[104:107], v[176:179], v[188:191], v[104:107]
	v_mfma_f32_16x16x32_bf16 v[88:91], v[176:179], v[196:199], v[88:91]
	v_mfma_f32_16x16x32_bf16 v[96:99], v[168:171], v[196:199], v[96:99]
	v_mfma_f32_16x16x32_bf16 v[80:83], v[168:171], v[204:207], v[80:83]
	v_mfma_f32_16x16x32_bf16 v[72:75], v[176:179], v[204:207], v[72:75]
	v_mfma_f32_16x16x32_bf16 v[64:67], v[176:179], v[212:215], v[64:67]
	v_mfma_f32_16x16x32_bf16 v[68:71], v[168:171], v[212:215], v[68:71]
	v_mfma_f32_16x16x32_bf16 v[112:115], v[172:175], v[192:195], v[112:115]
	v_mfma_f32_16x16x32_bf16 v[104:107], v[184:187], v[192:195], v[104:107]
	v_mfma_f32_16x16x32_bf16 v[88:91], v[184:187], v[200:203], v[88:91]
	v_mfma_f32_16x16x32_bf16 v[96:99], v[172:175], v[200:203], v[96:99]
	v_mfma_f32_16x16x32_bf16 v[80:83], v[172:175], v[208:211], v[80:83]
	v_mfma_f32_16x16x32_bf16 v[72:75], v[184:187], v[208:211], v[72:75]
	v_mfma_f32_16x16x32_bf16 v[64:67], v[184:187], v[216:219], v[64:67]
	v_mfma_f32_16x16x32_bf16 v[68:71], v[172:175], v[216:219], v[68:71]
	s_setprio 0
	s_barrier
	s_add_i32 s79, s71, s64
	v_lshl_add_u64 v[144:145], s[58:59], 0, v[130:131]
	s_mov_b32 m0, s79
	ds_read_b128 v[188:191], v151 offset:16384
	ds_read_b128 v[192:195], v151 offset:17408
	ds_read_b128 v[196:199], v151 offset:18432
	ds_read_b128 v[200:203], v151 offset:19456
	ds_read_b128 v[204:207], v151 offset:20480
	ds_read_b128 v[208:211], v151 offset:21504
	ds_read_b128 v[212:215], v151 offset:22528
	ds_read_b128 v[216:219], v151 offset:23552
	global_load_lds_dwordx4 v[144:145], off
	s_add_i32 m0, s79, 0x2000
	s_add_u32 s88, s58, 0x40000
	v_lshl_add_u64 v[220:221], s[58:59], 0, v[134:135]
	s_addc_u32 s89, s59, 0
	s_add_i32 s79, s72, s64
	global_load_lds_dwordx4 v[220:221], off
	v_lshl_add_u64 v[222:223], s[88:89], 0, v[130:131]
	s_mov_b32 m0, s79
	v_lshl_add_u64 v[224:225], s[60:61], 0, v[132:133]
	global_load_lds_dwordx4 v[222:223], off
	v_lshl_add_u64 v[222:223], s[88:89], 0, v[134:135]
	s_add_i32 m0, s79, 0x2000
	s_nop 0
	global_load_lds_dwordx4 v[222:223], off
	v_lshl_add_u64 v[222:223], s[60:61], 0, v[128:129]
	s_mov_b32 m0, s55
	s_nop 0
	global_load_lds_dwordx4 v[222:223], off
	s_mov_b32 m0, s65
	s_nop 0
	global_load_lds_dwordx4 v[224:225], off
	s_waitcnt vmcnt(8)
	s_waitcnt lgkmcnt(0)
	s_barrier
	s_setprio 1
	s_waitcnt lgkmcnt(0)
	v_mfma_f32_16x16x32_bf16 v[60:63], v[152:155], v[188:191], v[60:63]
	v_mfma_f32_16x16x32_bf16 v[56:59], v[160:163], v[188:191], v[56:59]
	v_mfma_f32_16x16x32_bf16 v[44:47], v[160:163], v[196:199], v[44:47]
	v_mfma_f32_16x16x32_bf16 v[52:55], v[152:155], v[196:199], v[52:55]
	v_mfma_f32_16x16x32_bf16 v[36:39], v[152:155], v[204:207], v[36:39]
	v_mfma_f32_16x16x32_bf16 v[28:31], v[160:163], v[204:207], v[28:31]
	v_mfma_f32_16x16x32_bf16 v[12:15], v[160:163], v[212:215], v[12:15]
	v_mfma_f32_16x16x32_bf16 v[20:23], v[152:155], v[212:215], v[20:23]
	v_mfma_f32_16x16x32_bf16 v[60:63], v[156:159], v[192:195], v[60:63]
	v_mfma_f32_16x16x32_bf16 v[56:59], v[164:167], v[192:195], v[56:59]
	v_mfma_f32_16x16x32_bf16 v[44:47], v[164:167], v[200:203], v[44:47]
	v_mfma_f32_16x16x32_bf16 v[52:55], v[156:159], v[200:203], v[52:55]
	v_mfma_f32_16x16x32_bf16 v[36:39], v[156:159], v[208:211], v[36:39]
	v_mfma_f32_16x16x32_bf16 v[28:31], v[164:167], v[208:211], v[28:31]
	v_mfma_f32_16x16x32_bf16 v[12:15], v[164:167], v[216:219], v[12:15]
	v_mfma_f32_16x16x32_bf16 v[20:23], v[156:159], v[216:219], v[20:23]
	s_setprio 0
	s_setprio 1
	v_mfma_f32_16x16x32_bf16 v[48:51], v[168:171], v[188:191], v[48:51]
	v_mfma_f32_16x16x32_bf16 v[40:43], v[176:179], v[188:191], v[40:43]
	v_mfma_f32_16x16x32_bf16 v[24:27], v[176:179], v[196:199], v[24:27]
	v_mfma_f32_16x16x32_bf16 v[32:35], v[168:171], v[196:199], v[32:35]
	v_mfma_f32_16x16x32_bf16 v[16:19], v[168:171], v[204:207], v[16:19]
	v_mfma_f32_16x16x32_bf16 v[8:11], v[176:179], v[204:207], v[8:11]
	v_mfma_f32_16x16x32_bf16 v[0:3], v[176:179], v[212:215], v[0:3]
	v_mfma_f32_16x16x32_bf16 v[4:7], v[168:171], v[212:215], v[4:7]
	v_mfma_f32_16x16x32_bf16 v[48:51], v[172:175], v[192:195], v[48:51]
	v_mfma_f32_16x16x32_bf16 v[40:43], v[184:187], v[192:195], v[40:43]
	v_mfma_f32_16x16x32_bf16 v[24:27], v[184:187], v[200:203], v[24:27]
	v_mfma_f32_16x16x32_bf16 v[32:35], v[172:175], v[200:203], v[32:35]
	v_mfma_f32_16x16x32_bf16 v[16:19], v[172:175], v[208:211], v[16:19]
	v_mfma_f32_16x16x32_bf16 v[8:11], v[184:187], v[208:211], v[8:11]
	v_mfma_f32_16x16x32_bf16 v[0:3], v[184:187], v[216:219], v[0:3]
	v_mfma_f32_16x16x32_bf16 v[4:7], v[172:175], v[216:219], v[4:7]
	s_setprio 0
	s_barrier
	s_add_i32 s79, 0, 0x18000
	s_add_i32 s87, 0, 0x1c000
	v_add_u32_e32 v164, s79, v147
	v_add_u32_e32 v181, s87, v147
	ds_read_b128 v[152:155], v164
	ds_read_b128 v[156:159], v164 offset:1024
	ds_read_b128 v[160:163], v164 offset:2048
	ds_read_b128 v[164:167], v164 offset:3072
	ds_read_b128 v[168:171], v181
	ds_read_b128 v[172:175], v181 offset:1024
	ds_read_b128 v[176:179], v181 offset:2048
	ds_read_b128 v[184:187], v181 offset:3072
	s_add_u32 s60, s60, 0x40000
	s_addc_u32 s61, s61, 0
	s_mov_b32 m0, s66
	v_lshl_add_u64 v[226:227], s[60:61], 0, v[128:129]
	ds_read_b128 v[188:191], v151 offset:32768
	ds_read_b128 v[192:195], v151 offset:33792
	ds_read_b128 v[196:199], v151 offset:34816
	ds_read_b128 v[200:203], v151 offset:35840
	ds_read_b128 v[204:207], v151 offset:36864
	ds_read_b128 v[208:211], v151 offset:37888
	ds_read_b128 v[212:215], v151 offset:38912
	ds_read_b128 v[216:219], v151 offset:39936
	global_load_lds_dwordx4 v[226:227], off
	v_lshl_add_u64 v[226:227], s[60:61], 0, v[132:133]
	s_mov_b32 m0, s67
	s_nop 0
	global_load_lds_dwordx4 v[226:227], off
	s_waitcnt vmcnt(8)
	s_waitcnt lgkmcnt(0)
	s_barrier
	s_setprio 1
	s_waitcnt lgkmcnt(0)
	v_mfma_f32_16x16x32_bf16 v[124:127], v[152:155], v[188:191], v[124:127]
	v_mfma_f32_16x16x32_bf16 v[120:123], v[160:163], v[188:191], v[120:123]
	v_mfma_f32_16x16x32_bf16 v[108:111], v[160:163], v[196:199], v[108:111]
	v_mfma_f32_16x16x32_bf16 v[116:119], v[152:155], v[196:199], v[116:119]
	v_mfma_f32_16x16x32_bf16 v[100:103], v[152:155], v[204:207], v[100:103]
	v_mfma_f32_16x16x32_bf16 v[92:95], v[160:163], v[204:207], v[92:95]
	v_mfma_f32_16x16x32_bf16 v[76:79], v[160:163], v[212:215], v[76:79]
	v_mfma_f32_16x16x32_bf16 v[84:87], v[152:155], v[212:215], v[84:87]
	v_mfma_f32_16x16x32_bf16 v[124:127], v[156:159], v[192:195], v[124:127]
	v_mfma_f32_16x16x32_bf16 v[120:123], v[164:167], v[192:195], v[120:123]
	v_mfma_f32_16x16x32_bf16 v[108:111], v[164:167], v[200:203], v[108:111]
	v_mfma_f32_16x16x32_bf16 v[116:119], v[156:159], v[200:203], v[116:119]
	v_mfma_f32_16x16x32_bf16 v[100:103], v[156:159], v[208:211], v[100:103]
	v_mfma_f32_16x16x32_bf16 v[92:95], v[164:167], v[208:211], v[92:95]
	v_mfma_f32_16x16x32_bf16 v[76:79], v[164:167], v[216:219], v[76:79]
	v_mfma_f32_16x16x32_bf16 v[84:87], v[156:159], v[216:219], v[84:87]
	s_setprio 0
	s_setprio 1
	v_mfma_f32_16x16x32_bf16 v[112:115], v[168:171], v[188:191], v[112:115]
	v_mfma_f32_16x16x32_bf16 v[104:107], v[176:179], v[188:191], v[104:107]
	v_mfma_f32_16x16x32_bf16 v[88:91], v[176:179], v[196:199], v[88:91]
	v_mfma_f32_16x16x32_bf16 v[96:99], v[168:171], v[196:199], v[96:99]
	v_mfma_f32_16x16x32_bf16 v[80:83], v[168:171], v[204:207], v[80:83]
	v_mfma_f32_16x16x32_bf16 v[72:75], v[176:179], v[204:207], v[72:75]
	v_mfma_f32_16x16x32_bf16 v[64:67], v[176:179], v[212:215], v[64:67]
	v_mfma_f32_16x16x32_bf16 v[68:71], v[168:171], v[212:215], v[68:71]
	v_mfma_f32_16x16x32_bf16 v[112:115], v[172:175], v[192:195], v[112:115]
	v_mfma_f32_16x16x32_bf16 v[104:107], v[184:187], v[192:195], v[104:107]
	v_mfma_f32_16x16x32_bf16 v[88:91], v[184:187], v[200:203], v[88:91]
	v_mfma_f32_16x16x32_bf16 v[96:99], v[172:175], v[200:203], v[96:99]
	v_mfma_f32_16x16x32_bf16 v[80:83], v[172:175], v[208:211], v[80:83]
	v_mfma_f32_16x16x32_bf16 v[72:75], v[184:187], v[208:211], v[72:75]
	v_mfma_f32_16x16x32_bf16 v[64:67], v[184:187], v[216:219], v[64:67]
	v_mfma_f32_16x16x32_bf16 v[68:71], v[172:175], v[216:219], v[68:71]
	s_setprio 0
	s_barrier
	s_add_i32 s60, s79, s64
	v_lshl_add_u64 v[144:145], v[144:145], 0, s[16:17]
	s_mov_b32 m0, s60
	ds_read_b128 v[188:191], v151 offset:49152
	ds_read_b128 v[192:195], v151 offset:50176
	ds_read_b128 v[196:199], v151 offset:51200
	ds_read_b128 v[200:203], v151 offset:52224
	ds_read_b128 v[204:207], v151 offset:53248
	ds_read_b128 v[208:211], v151 offset:54272
	ds_read_b128 v[212:215], v151 offset:55296
	ds_read_b128 v[216:219], v151 offset:56320
	global_load_lds_dwordx4 v[144:145], off
	s_add_i32 m0, s60, 0x2000
	s_add_u32 s58, s58, 0x40080
	v_lshl_add_u64 v[144:145], v[220:221], 0, s[16:17]
	s_addc_u32 s59, s59, 0
	s_add_i32 s60, s87, s64
	global_load_lds_dwordx4 v[144:145], off
	v_lshl_add_u64 v[144:145], s[58:59], 0, v[130:131]
	s_mov_b32 m0, s60
	s_nop 0
	global_load_lds_dwordx4 v[144:145], off
	v_lshl_add_u64 v[144:145], s[58:59], 0, v[134:135]
	s_add_i32 m0, s60, 0x2000
	s_nop 0
	global_load_lds_dwordx4 v[144:145], off
	v_lshl_add_u64 v[144:145], v[222:223], 0, s[16:17]
	s_mov_b32 m0, s69
	s_nop 0
	global_load_lds_dwordx4 v[144:145], off
	v_lshl_add_u64 v[144:145], v[224:225], 0, s[16:17]
	s_mov_b32 m0, s70
	s_nop 0
	global_load_lds_dwordx4 v[144:145], off
	s_waitcnt vmcnt(8)
	s_waitcnt lgkmcnt(0)
	s_barrier
	s_setprio 1
	s_waitcnt lgkmcnt(0)
	v_mfma_f32_16x16x32_bf16 v[60:63], v[152:155], v[188:191], v[60:63]
	v_mfma_f32_16x16x32_bf16 v[56:59], v[160:163], v[188:191], v[56:59]
	v_mfma_f32_16x16x32_bf16 v[44:47], v[160:163], v[196:199], v[44:47]
	v_mfma_f32_16x16x32_bf16 v[52:55], v[152:155], v[196:199], v[52:55]
	v_mfma_f32_16x16x32_bf16 v[36:39], v[152:155], v[204:207], v[36:39]
	v_mfma_f32_16x16x32_bf16 v[28:31], v[160:163], v[204:207], v[28:31]
	v_mfma_f32_16x16x32_bf16 v[12:15], v[160:163], v[212:215], v[12:15]
	v_mfma_f32_16x16x32_bf16 v[20:23], v[152:155], v[212:215], v[20:23]
	v_mfma_f32_16x16x32_bf16 v[60:63], v[156:159], v[192:195], v[60:63]
	v_mfma_f32_16x16x32_bf16 v[56:59], v[164:167], v[192:195], v[56:59]
	v_mfma_f32_16x16x32_bf16 v[44:47], v[164:167], v[200:203], v[44:47]
	v_mfma_f32_16x16x32_bf16 v[52:55], v[156:159], v[200:203], v[52:55]
	v_mfma_f32_16x16x32_bf16 v[36:39], v[156:159], v[208:211], v[36:39]
	v_mfma_f32_16x16x32_bf16 v[28:31], v[164:167], v[208:211], v[28:31]
	v_mfma_f32_16x16x32_bf16 v[12:15], v[164:167], v[216:219], v[12:15]
	v_mfma_f32_16x16x32_bf16 v[20:23], v[156:159], v[216:219], v[20:23]
	s_setprio 0
	s_setprio 1
	v_mfma_f32_16x16x32_bf16 v[48:51], v[168:171], v[188:191], v[48:51]
	v_mfma_f32_16x16x32_bf16 v[40:43], v[176:179], v[188:191], v[40:43]
	v_mfma_f32_16x16x32_bf16 v[24:27], v[176:179], v[196:199], v[24:27]
	v_mfma_f32_16x16x32_bf16 v[32:35], v[168:171], v[196:199], v[32:35]
	v_mfma_f32_16x16x32_bf16 v[16:19], v[168:171], v[204:207], v[16:19]
	v_mfma_f32_16x16x32_bf16 v[8:11], v[176:179], v[204:207], v[8:11]
	v_mfma_f32_16x16x32_bf16 v[0:3], v[176:179], v[212:215], v[0:3]
	v_mfma_f32_16x16x32_bf16 v[4:7], v[168:171], v[212:215], v[4:7]
	v_mfma_f32_16x16x32_bf16 v[48:51], v[172:175], v[192:195], v[48:51]
	v_mfma_f32_16x16x32_bf16 v[40:43], v[184:187], v[192:195], v[40:43]
	v_mfma_f32_16x16x32_bf16 v[24:27], v[184:187], v[200:203], v[24:27]
	v_mfma_f32_16x16x32_bf16 v[32:35], v[172:175], v[200:203], v[32:35]
	v_mfma_f32_16x16x32_bf16 v[16:19], v[172:175], v[208:211], v[16:19]
	v_mfma_f32_16x16x32_bf16 v[8:11], v[184:187], v[208:211], v[8:11]
	v_mfma_f32_16x16x32_bf16 v[0:3], v[184:187], v[216:219], v[0:3]
	v_mfma_f32_16x16x32_bf16 v[4:7], v[172:175], v[216:219], v[4:7]
	s_setprio 0
	s_barrier
	s_add_i32 s86, s86, 2
	s_add_u32 s56, s56, 0x100
	s_addc_u32 s57, s57, 0
	s_add_u32 s84, s84, 0x100
	s_addc_u32 s85, s85, 0
	s_cmp_gt_u32 s86, 13
	s_cbranch_scc0 .LBB0_1311
	s_and_b64 vcc, exec, s[18:19]
	s_cbranch_vccz .LBB0_1314
	s_barrier

.LBB0_1434:
	ds_read_b128 v[140:143], v147
	ds_read_b128 v[150:153], v147 offset:1024
	ds_read_b128 v[154:157], v147 offset:2048
	ds_read_b128 v[158:161], v147 offset:3072
	ds_read_b128 v[162:165], v148
	ds_read_b128 v[166:169], v148 offset:1024
	ds_read_b128 v[170:173], v148 offset:2048
	ds_read_b128 v[174:177], v148 offset:3072
	s_add_u32 s48, s46, 0xfffc0080
	s_addc_u32 s49, s47, -1
	s_cmp_eq_u32 s70, 12
	s_cselect_b32 s51, s19, s49
	s_cselect_b32 s50, s66, s48
	s_cselect_b32 s49, s17, s69
	s_cselect_b32 s48, s67, s68
	v_lshl_add_u64 v[178:179], s[46:47], 0, v[132:133]
	s_add_i32 m0, s45, 0xc000
	ds_read_b128 v[184:187], v149
	ds_read_b128 v[188:191], v149 offset:1024
	ds_read_b128 v[192:195], v149 offset:2048
	ds_read_b128 v[196:199], v149 offset:3072
	ds_read_b128 v[200:203], v149 offset:4096
	ds_read_b128 v[204:207], v149 offset:5120
	ds_read_b128 v[208:211], v149 offset:6144
	ds_read_b128 v[212:215], v149 offset:7168
	global_load_lds_dwordx4 v[178:179], off
	v_lshl_add_u64 v[178:179], s[46:47], 0, v[134:135]
	s_add_i32 m0, s45, 0xe000
	s_nop 0
	global_load_lds_dwordx4 v[178:179], off
	s_waitcnt vmcnt(8)
	s_waitcnt lgkmcnt(0)
	s_barrier
	s_setprio 1
	s_waitcnt lgkmcnt(0)
	v_mfma_f32_16x16x32_bf16 v[124:127], v[140:143], v[184:187], v[124:127]
	v_mfma_f32_16x16x32_bf16 v[120:123], v[154:157], v[184:187], v[120:123]
	v_mfma_f32_16x16x32_bf16 v[104:107], v[154:157], v[192:195], v[104:107]
	v_mfma_f32_16x16x32_bf16 v[108:111], v[140:143], v[192:195], v[108:111]
	v_mfma_f32_16x16x32_bf16 v[92:95], v[140:143], v[200:203], v[92:95]
	v_mfma_f32_16x16x32_bf16 v[88:91], v[154:157], v[200:203], v[88:91]
	v_mfma_f32_16x16x32_bf16 v[72:75], v[154:157], v[208:211], v[72:75]
	v_mfma_f32_16x16x32_bf16 v[76:79], v[140:143], v[208:211], v[76:79]
	v_mfma_f32_16x16x32_bf16 v[124:127], v[150:153], v[188:191], v[124:127]
	v_mfma_f32_16x16x32_bf16 v[120:123], v[158:161], v[188:191], v[120:123]
	v_mfma_f32_16x16x32_bf16 v[104:107], v[158:161], v[196:199], v[104:107]
	v_mfma_f32_16x16x32_bf16 v[108:111], v[150:153], v[196:199], v[108:111]
	v_mfma_f32_16x16x32_bf16 v[92:95], v[150:153], v[204:207], v[92:95]
	v_mfma_f32_16x16x32_bf16 v[88:91], v[158:161], v[204:207], v[88:91]
	v_mfma_f32_16x16x32_bf16 v[72:75], v[158:161], v[212:215], v[72:75]
	v_mfma_f32_16x16x32_bf16 v[76:79], v[150:153], v[212:215], v[76:79]
	s_setprio 0
	s_setprio 1
	v_mfma_f32_16x16x32_bf16 v[116:119], v[162:165], v[184:187], v[116:119]
	v_mfma_f32_16x16x32_bf16 v[112:115], v[170:173], v[184:187], v[112:115]
	v_mfma_f32_16x16x32_bf16 v[96:99], v[170:173], v[192:195], v[96:99]
	v_mfma_f32_16x16x32_bf16 v[100:103], v[162:165], v[192:195], v[100:103]
	v_mfma_f32_16x16x32_bf16 v[84:87], v[162:165], v[200:203], v[84:87]
	v_mfma_f32_16x16x32_bf16 v[80:83], v[170:173], v[200:203], v[80:83]
	v_mfma_f32_16x16x32_bf16 v[64:67], v[170:173], v[208:211], v[64:67]
	v_mfma_f32_16x16x32_bf16 v[68:71], v[162:165], v[208:211], v[68:71]
	v_mfma_f32_16x16x32_bf16 v[116:119], v[166:169], v[188:191], v[116:119]
	v_mfma_f32_16x16x32_bf16 v[112:115], v[174:177], v[188:191], v[112:115]
	v_mfma_f32_16x16x32_bf16 v[96:99], v[174:177], v[196:199], v[96:99]
	v_mfma_f32_16x16x32_bf16 v[100:103], v[166:169], v[196:199], v[100:103]
	v_mfma_f32_16x16x32_bf16 v[84:87], v[166:169], v[204:207], v[84:87]
	v_mfma_f32_16x16x32_bf16 v[80:83], v[174:177], v[204:207], v[80:83]
	v_mfma_f32_16x16x32_bf16 v[64:67], v[174:177], v[212:215], v[64:67]
	v_mfma_f32_16x16x32_bf16 v[68:71], v[166:169], v[212:215], v[68:71]
	s_setprio 0
	s_barrier
	s_add_i32 s71, s62, s54
	v_lshl_add_u64 v[178:179], s[48:49], 0, v[130:131]
	s_mov_b32 m0, s71
	ds_read_b128 v[184:187], v149 offset:16384
	ds_read_b128 v[188:191], v149 offset:17408
	ds_read_b128 v[192:195], v149 offset:18432
	ds_read_b128 v[196:199], v149 offset:19456
	ds_read_b128 v[200:203], v149 offset:20480
	ds_read_b128 v[204:207], v149 offset:21504
	ds_read_b128 v[208:211], v149 offset:22528
	ds_read_b128 v[212:215], v149 offset:23552
	global_load_lds_dwordx4 v[178:179], off
	s_add_i32 m0, s71, 0x2000
	s_add_u32 s72, s48, 0x40000
	v_lshl_add_u64 v[216:217], s[48:49], 0, v[128:129]
	s_addc_u32 s73, s49, 0
	s_add_i32 s71, s63, s54
	global_load_lds_dwordx4 v[216:217], off
	v_lshl_add_u64 v[218:219], s[72:73], 0, v[130:131]
	s_mov_b32 m0, s71
	v_lshl_add_u64 v[220:221], s[50:51], 0, v[128:129]
	global_load_lds_dwordx4 v[218:219], off
	v_lshl_add_u64 v[218:219], s[72:73], 0, v[128:129]
	s_add_i32 m0, s71, 0x2000
	s_nop 0
	global_load_lds_dwordx4 v[218:219], off
	v_lshl_add_u64 v[218:219], s[50:51], 0, v[130:131]
	s_mov_b32 m0, s45
	s_nop 0
	global_load_lds_dwordx4 v[218:219], off
	s_mov_b32 m0, s56
	s_nop 0
	global_load_lds_dwordx4 v[220:221], off
	s_waitcnt vmcnt(8)
	s_waitcnt lgkmcnt(0)
	s_barrier
	s_setprio 1
	s_waitcnt lgkmcnt(0)
	v_mfma_f32_16x16x32_bf16 v[60:63], v[140:143], v[184:187], v[60:63]
	v_mfma_f32_16x16x32_bf16 v[56:59], v[154:157], v[184:187], v[56:59]
	v_mfma_f32_16x16x32_bf16 v[40:43], v[154:157], v[192:195], v[40:43]
	v_mfma_f32_16x16x32_bf16 v[44:47], v[140:143], v[192:195], v[44:47]
	v_mfma_f32_16x16x32_bf16 v[28:31], v[140:143], v[200:203], v[28:31]
	v_mfma_f32_16x16x32_bf16 v[24:27], v[154:157], v[200:203], v[24:27]
	v_mfma_f32_16x16x32_bf16 v[8:11], v[154:157], v[208:211], v[8:11]
	v_mfma_f32_16x16x32_bf16 v[12:15], v[140:143], v[208:211], v[12:15]
	v_mfma_f32_16x16x32_bf16 v[60:63], v[150:153], v[188:191], v[60:63]
	v_mfma_f32_16x16x32_bf16 v[56:59], v[158:161], v[188:191], v[56:59]
	v_mfma_f32_16x16x32_bf16 v[40:43], v[158:161], v[196:199], v[40:43]
	v_mfma_f32_16x16x32_bf16 v[44:47], v[150:153], v[196:199], v[44:47]
	v_mfma_f32_16x16x32_bf16 v[28:31], v[150:153], v[204:207], v[28:31]
	v_mfma_f32_16x16x32_bf16 v[24:27], v[158:161], v[204:207], v[24:27]
	v_mfma_f32_16x16x32_bf16 v[8:11], v[158:161], v[212:215], v[8:11]
	v_mfma_f32_16x16x32_bf16 v[12:15], v[150:153], v[212:215], v[12:15]
	s_setprio 0
	s_setprio 1
	v_mfma_f32_16x16x32_bf16 v[52:55], v[162:165], v[184:187], v[52:55]
	v_mfma_f32_16x16x32_bf16 v[48:51], v[170:173], v[184:187], v[48:51]
	v_mfma_f32_16x16x32_bf16 v[32:35], v[170:173], v[192:195], v[32:35]
	v_mfma_f32_16x16x32_bf16 v[36:39], v[162:165], v[192:195], v[36:39]
	v_mfma_f32_16x16x32_bf16 v[20:23], v[162:165], v[200:203], v[20:23]
	v_mfma_f32_16x16x32_bf16 v[16:19], v[170:173], v[200:203], v[16:19]
	v_mfma_f32_16x16x32_bf16 v[0:3], v[170:173], v[208:211], v[0:3]
	v_mfma_f32_16x16x32_bf16 v[4:7], v[162:165], v[208:211], v[4:7]
	v_mfma_f32_16x16x32_bf16 v[52:55], v[166:169], v[188:191], v[52:55]
	v_mfma_f32_16x16x32_bf16 v[48:51], v[174:177], v[188:191], v[48:51]
	v_mfma_f32_16x16x32_bf16 v[32:35], v[174:177], v[196:199], v[32:35]
	v_mfma_f32_16x16x32_bf16 v[36:39], v[166:169], v[196:199], v[36:39]
	v_mfma_f32_16x16x32_bf16 v[20:23], v[166:169], v[204:207], v[20:23]
	v_mfma_f32_16x16x32_bf16 v[16:19], v[174:177], v[204:207], v[16:19]
	v_mfma_f32_16x16x32_bf16 v[0:3], v[174:177], v[212:215], v[0:3]
	v_mfma_f32_16x16x32_bf16 v[4:7], v[166:169], v[212:215], v[4:7]
	s_setprio 0
	s_barrier
	s_add_i32 s71, 0, 0x18000
	s_add_i32 s72, 0, 0x1c000
	v_add_u32_e32 v158, s71, v145
	v_add_u32_e32 v174, s72, v145
	ds_read_b128 v[140:143], v158
	ds_read_b128 v[150:153], v158 offset:1024
	ds_read_b128 v[154:157], v158 offset:2048
	ds_read_b128 v[158:161], v158 offset:3072
	ds_read_b128 v[162:165], v174
	ds_read_b128 v[166:169], v174 offset:1024
	ds_read_b128 v[170:173], v174 offset:2048
	ds_read_b128 v[174:177], v174 offset:3072
	s_add_u32 s50, s50, 0x40000
	s_addc_u32 s51, s51, 0
	s_mov_b32 m0, s57
	v_lshl_add_u64 v[222:223], s[50:51], 0, v[130:131]
	ds_read_b128 v[184:187], v149 offset:32768
	ds_read_b128 v[188:191], v149 offset:33792
	ds_read_b128 v[192:195], v149 offset:34816
	ds_read_b128 v[196:199], v149 offset:35840
	ds_read_b128 v[200:203], v149 offset:36864
	ds_read_b128 v[204:207], v149 offset:37888
	ds_read_b128 v[208:211], v149 offset:38912
	ds_read_b128 v[212:215], v149 offset:39936
	global_load_lds_dwordx4 v[222:223], off
	v_lshl_add_u64 v[222:223], s[50:51], 0, v[128:129]
	s_mov_b32 m0, s58
	s_nop 0
	global_load_lds_dwordx4 v[222:223], off
	s_waitcnt vmcnt(8)
	s_waitcnt lgkmcnt(0)
	s_barrier
	s_setprio 1
	s_waitcnt lgkmcnt(0)
	v_mfma_f32_16x16x32_bf16 v[124:127], v[140:143], v[184:187], v[124:127]
	v_mfma_f32_16x16x32_bf16 v[120:123], v[154:157], v[184:187], v[120:123]
	v_mfma_f32_16x16x32_bf16 v[104:107], v[154:157], v[192:195], v[104:107]
	v_mfma_f32_16x16x32_bf16 v[108:111], v[140:143], v[192:195], v[108:111]
	v_mfma_f32_16x16x32_bf16 v[92:95], v[140:143], v[200:203], v[92:95]
	v_mfma_f32_16x16x32_bf16 v[88:91], v[154:157], v[200:203], v[88:91]
	v_mfma_f32_16x16x32_bf16 v[72:75], v[154:157], v[208:211], v[72:75]
	v_mfma_f32_16x16x32_bf16 v[76:79], v[140:143], v[208:211], v[76:79]
	v_mfma_f32_16x16x32_bf16 v[124:127], v[150:153], v[188:191], v[124:127]
	v_mfma_f32_16x16x32_bf16 v[120:123], v[158:161], v[188:191], v[120:123]
	v_mfma_f32_16x16x32_bf16 v[104:107], v[158:161], v[196:199], v[104:107]
	v_mfma_f32_16x16x32_bf16 v[108:111], v[150:153], v[196:199], v[108:111]
	v_mfma_f32_16x16x32_bf16 v[92:95], v[150:153], v[204:207], v[92:95]
	v_mfma_f32_16x16x32_bf16 v[88:91], v[158:161], v[204:207], v[88:91]
	v_mfma_f32_16x16x32_bf16 v[72:75], v[158:161], v[212:215], v[72:75]
	v_mfma_f32_16x16x32_bf16 v[76:79], v[150:153], v[212:215], v[76:79]
	s_setprio 0
	s_setprio 1
	v_mfma_f32_16x16x32_bf16 v[116:119], v[162:165], v[184:187], v[116:119]
	v_mfma_f32_16x16x32_bf16 v[112:115], v[170:173], v[184:187], v[112:115]
	v_mfma_f32_16x16x32_bf16 v[96:99], v[170:173], v[192:195], v[96:99]
	v_mfma_f32_16x16x32_bf16 v[100:103], v[162:165], v[192:195], v[100:103]
	v_mfma_f32_16x16x32_bf16 v[84:87], v[162:165], v[200:203], v[84:87]
	v_mfma_f32_16x16x32_bf16 v[80:83], v[170:173], v[200:203], v[80:83]
	v_mfma_f32_16x16x32_bf16 v[64:67], v[170:173], v[208:211], v[64:67]
	v_mfma_f32_16x16x32_bf16 v[68:71], v[162:165], v[208:211], v[68:71]
	v_mfma_f32_16x16x32_bf16 v[116:119], v[166:169], v[188:191], v[116:119]
	v_mfma_f32_16x16x32_bf16 v[112:115], v[174:177], v[188:191], v[112:115]
	v_mfma_f32_16x16x32_bf16 v[96:99], v[174:177], v[196:199], v[96:99]
	v_mfma_f32_16x16x32_bf16 v[100:103], v[166:169], v[196:199], v[100:103]
	v_mfma_f32_16x16x32_bf16 v[84:87], v[166:169], v[204:207], v[84:87]
	v_mfma_f32_16x16x32_bf16 v[80:83], v[174:177], v[204:207], v[80:83]
	v_mfma_f32_16x16x32_bf16 v[64:67], v[174:177], v[212:215], v[64:67]
	v_mfma_f32_16x16x32_bf16 v[68:71], v[166:169], v[212:215], v[68:71]
	s_setprio 0
	s_barrier
	s_add_i32 s50, s71, s54
	v_lshl_add_u64 v[178:179], v[178:179], 0, s[10:11]
	s_mov_b32 m0, s50
	ds_read_b128 v[184:187], v149 offset:49152
	ds_read_b128 v[188:191], v149 offset:50176
	ds_read_b128 v[192:195], v149 offset:51200
	ds_read_b128 v[196:199], v149 offset:52224
	ds_read_b128 v[200:203], v149 offset:53248
	ds_read_b128 v[204:207], v149 offset:54272
	ds_read_b128 v[208:211], v149 offset:55296
	ds_read_b128 v[212:215], v149 offset:56320
	global_load_lds_dwordx4 v[178:179], off
	s_add_i32 m0, s50, 0x2000
	s_add_u32 s48, s48, 0x40080
	v_lshl_add_u64 v[178:179], v[216:217], 0, s[10:11]
	s_addc_u32 s49, s49, 0
	s_add_i32 s50, s72, s54
	global_load_lds_dwordx4 v[178:179], off
	v_lshl_add_u64 v[178:179], s[48:49], 0, v[130:131]
	s_mov_b32 m0, s50
	s_nop 0
	global_load_lds_dwordx4 v[178:179], off
	v_lshl_add_u64 v[178:179], s[48:49], 0, v[128:129]
	s_add_i32 m0, s50, 0x2000
	s_nop 0
	global_load_lds_dwordx4 v[178:179], off
	v_lshl_add_u64 v[178:179], v[218:219], 0, s[10:11]
	s_mov_b32 m0, s60
	s_nop 0
	global_load_lds_dwordx4 v[178:179], off
	v_lshl_add_u64 v[178:179], v[220:221], 0, s[10:11]
	s_mov_b32 m0, s61
	s_nop 0
	global_load_lds_dwordx4 v[178:179], off
	s_waitcnt vmcnt(8)
	s_waitcnt lgkmcnt(0)
	s_barrier
	s_setprio 1
	s_waitcnt lgkmcnt(0)
	v_mfma_f32_16x16x32_bf16 v[60:63], v[140:143], v[184:187], v[60:63]
	v_mfma_f32_16x16x32_bf16 v[56:59], v[154:157], v[184:187], v[56:59]
	v_mfma_f32_16x16x32_bf16 v[40:43], v[154:157], v[192:195], v[40:43]
	v_mfma_f32_16x16x32_bf16 v[44:47], v[140:143], v[192:195], v[44:47]
	v_mfma_f32_16x16x32_bf16 v[28:31], v[140:143], v[200:203], v[28:31]
	v_mfma_f32_16x16x32_bf16 v[24:27], v[154:157], v[200:203], v[24:27]
	v_mfma_f32_16x16x32_bf16 v[8:11], v[154:157], v[208:211], v[8:11]
	v_mfma_f32_16x16x32_bf16 v[12:15], v[140:143], v[208:211], v[12:15]
	v_mfma_f32_16x16x32_bf16 v[60:63], v[150:153], v[188:191], v[60:63]
	v_mfma_f32_16x16x32_bf16 v[56:59], v[158:161], v[188:191], v[56:59]
	v_mfma_f32_16x16x32_bf16 v[40:43], v[158:161], v[196:199], v[40:43]
	v_mfma_f32_16x16x32_bf16 v[44:47], v[150:153], v[196:199], v[44:47]
	v_mfma_f32_16x16x32_bf16 v[28:31], v[150:153], v[204:207], v[28:31]
	v_mfma_f32_16x16x32_bf16 v[24:27], v[158:161], v[204:207], v[24:27]
	v_mfma_f32_16x16x32_bf16 v[8:11], v[158:161], v[212:215], v[8:11]
	v_mfma_f32_16x16x32_bf16 v[12:15], v[150:153], v[212:215], v[12:15]
	s_setprio 0
	s_setprio 1
	v_mfma_f32_16x16x32_bf16 v[52:55], v[162:165], v[184:187], v[52:55]
	v_mfma_f32_16x16x32_bf16 v[48:51], v[170:173], v[184:187], v[48:51]
	v_mfma_f32_16x16x32_bf16 v[32:35], v[170:173], v[192:195], v[32:35]
	v_mfma_f32_16x16x32_bf16 v[36:39], v[162:165], v[192:195], v[36:39]
	v_mfma_f32_16x16x32_bf16 v[20:23], v[162:165], v[200:203], v[20:23]
	v_mfma_f32_16x16x32_bf16 v[16:19], v[170:173], v[200:203], v[16:19]
	v_mfma_f32_16x16x32_bf16 v[0:3], v[170:173], v[208:211], v[0:3]
	v_mfma_f32_16x16x32_bf16 v[4:7], v[162:165], v[208:211], v[4:7]
	v_mfma_f32_16x16x32_bf16 v[52:55], v[166:169], v[188:191], v[52:55]
	v_mfma_f32_16x16x32_bf16 v[48:51], v[174:177], v[188:191], v[48:51]
	v_mfma_f32_16x16x32_bf16 v[32:35], v[174:177], v[196:199], v[32:35]
	v_mfma_f32_16x16x32_bf16 v[36:39], v[166:169], v[196:199], v[36:39]
	v_mfma_f32_16x16x32_bf16 v[20:23], v[166:169], v[204:207], v[20:23]
	v_mfma_f32_16x16x32_bf16 v[16:19], v[174:177], v[204:207], v[16:19]
	v_mfma_f32_16x16x32_bf16 v[0:3], v[174:177], v[212:215], v[0:3]
	v_mfma_f32_16x16x32_bf16 v[4:7], v[166:169], v[212:215], v[4:7]
	s_setprio 0
	s_barrier
	s_add_i32 s70, s70, 2
	s_add_u32 s46, s46, 0x100
	s_addc_u32 s47, s47, 0
	s_add_u32 s68, s68, 0x100
	s_addc_u32 s69, s69, 0
	s_cmp_gt_u32 s70, 13
	s_cbranch_scc0 .LBB0_1434
	s_and_b64 vcc, exec, s[12:13]
	s_cbranch_vccz .LBB0_1437
	s_barrier

.LBB0_1514:
	ds_read_b128 v[152:155], v149
	ds_read_b128 v[156:159], v149 offset:1024
	ds_read_b128 v[160:163], v149 offset:2048
	ds_read_b128 v[164:167], v149 offset:3072
	ds_read_b128 v[168:171], v150
	ds_read_b128 v[172:175], v150 offset:1024
	ds_read_b128 v[176:179], v150 offset:2048
	ds_read_b128 v[184:187], v150 offset:3072
	s_add_u32 s48, s46, 0x100
	s_addc_u32 s49, s47, 0
	s_cmp_eq_u32 s76, 40
	s_cselect_b32 s53, s9, s49
	s_cselect_b32 s52, s8, s48
	s_cselect_b32 s51, s45, s75
	s_cselect_b32 s50, s44, s74
	v_lshl_add_u64 v[144:145], s[46:47], 0, v[136:137]
	s_add_i32 m0, s57, 0xc000
	ds_read_b128 v[188:191], v151
	ds_read_b128 v[192:195], v151 offset:1024
	ds_read_b128 v[196:199], v151 offset:2048
	ds_read_b128 v[200:203], v151 offset:3072
	ds_read_b128 v[204:207], v151 offset:4096
	ds_read_b128 v[208:211], v151 offset:5120
	ds_read_b128 v[212:215], v151 offset:6144
	ds_read_b128 v[216:219], v151 offset:7168
	global_load_lds_dwordx4 v[144:145], off
	v_lshl_add_u64 v[144:145], s[46:47], 0, v[138:139]
	s_add_i32 m0, s57, 0xe000
	s_nop 0
	global_load_lds_dwordx4 v[144:145], off
	s_waitcnt vmcnt(8)
	s_waitcnt lgkmcnt(0)
	s_barrier
	s_setprio 1
	s_waitcnt lgkmcnt(0)
	v_mfma_f32_16x16x32_bf16 v[124:127], v[152:155], v[188:191], v[124:127]
	v_mfma_f32_16x16x32_bf16 v[120:123], v[160:163], v[188:191], v[120:123]
	v_mfma_f32_16x16x32_bf16 v[108:111], v[160:163], v[196:199], v[108:111]
	v_mfma_f32_16x16x32_bf16 v[116:119], v[152:155], v[196:199], v[116:119]
	v_mfma_f32_16x16x32_bf16 v[100:103], v[152:155], v[204:207], v[100:103]
	v_mfma_f32_16x16x32_bf16 v[92:95], v[160:163], v[204:207], v[92:95]
	v_mfma_f32_16x16x32_bf16 v[76:79], v[160:163], v[212:215], v[76:79]
	v_mfma_f32_16x16x32_bf16 v[84:87], v[152:155], v[212:215], v[84:87]
	v_mfma_f32_16x16x32_bf16 v[124:127], v[156:159], v[192:195], v[124:127]
	v_mfma_f32_16x16x32_bf16 v[120:123], v[164:167], v[192:195], v[120:123]
	v_mfma_f32_16x16x32_bf16 v[108:111], v[164:167], v[200:203], v[108:111]
	v_mfma_f32_16x16x32_bf16 v[116:119], v[156:159], v[200:203], v[116:119]
	v_mfma_f32_16x16x32_bf16 v[100:103], v[156:159], v[208:211], v[100:103]
	v_mfma_f32_16x16x32_bf16 v[92:95], v[164:167], v[208:211], v[92:95]
	v_mfma_f32_16x16x32_bf16 v[76:79], v[164:167], v[216:219], v[76:79]
	v_mfma_f32_16x16x32_bf16 v[84:87], v[156:159], v[216:219], v[84:87]
	s_setprio 0
	s_setprio 1
	v_mfma_f32_16x16x32_bf16 v[112:115], v[168:171], v[188:191], v[112:115]
	v_mfma_f32_16x16x32_bf16 v[104:107], v[176:179], v[188:191], v[104:107]
	v_mfma_f32_16x16x32_bf16 v[88:91], v[176:179], v[196:199], v[88:91]
	v_mfma_f32_16x16x32_bf16 v[96:99], v[168:171], v[196:199], v[96:99]
	v_mfma_f32_16x16x32_bf16 v[80:83], v[168:171], v[204:207], v[80:83]
	v_mfma_f32_16x16x32_bf16 v[72:75], v[176:179], v[204:207], v[72:75]
	v_mfma_f32_16x16x32_bf16 v[64:67], v[176:179], v[212:215], v[64:67]
	v_mfma_f32_16x16x32_bf16 v[68:71], v[168:171], v[212:215], v[68:71]
	v_mfma_f32_16x16x32_bf16 v[112:115], v[172:175], v[192:195], v[112:115]
	v_mfma_f32_16x16x32_bf16 v[104:107], v[184:187], v[192:195], v[104:107]
	v_mfma_f32_16x16x32_bf16 v[88:91], v[184:187], v[200:203], v[88:91]
	v_mfma_f32_16x16x32_bf16 v[96:99], v[172:175], v[200:203], v[96:99]
	v_mfma_f32_16x16x32_bf16 v[80:83], v[172:175], v[208:211], v[80:83]
	v_mfma_f32_16x16x32_bf16 v[72:75], v[184:187], v[208:211], v[72:75]
	v_mfma_f32_16x16x32_bf16 v[64:67], v[184:187], v[216:219], v[64:67]
	v_mfma_f32_16x16x32_bf16 v[68:71], v[172:175], v[216:219], v[68:71]
	s_setprio 0
	s_barrier
	s_add_i32 s46, s64, s56
	v_lshl_add_u64 v[144:145], s[50:51], 0, v[130:131]
	s_mov_b32 m0, s46
	ds_read_b128 v[188:191], v151 offset:16384
	ds_read_b128 v[192:195], v151 offset:17408
	ds_read_b128 v[196:199], v151 offset:18432
	ds_read_b128 v[200:203], v151 offset:19456
	ds_read_b128 v[204:207], v151 offset:20480
	ds_read_b128 v[208:211], v151 offset:21504
	ds_read_b128 v[212:215], v151 offset:22528
	ds_read_b128 v[216:219], v151 offset:23552
	global_load_lds_dwordx4 v[144:145], off
	s_add_i32 m0, s46, 0x2000
	s_add_u32 s46, s50, 0xb0000
	v_lshl_add_u64 v[220:221], s[50:51], 0, v[134:135]
	s_addc_u32 s47, s51, 0
	s_add_i32 s77, s65, s56
	global_load_lds_dwordx4 v[220:221], off
	v_lshl_add_u64 v[222:223], s[46:47], 0, v[130:131]
	s_mov_b32 m0, s77
	v_lshl_add_u64 v[224:225], s[52:53], 0, v[132:133]
	global_load_lds_dwordx4 v[222:223], off
	v_lshl_add_u64 v[222:223], s[46:47], 0, v[134:135]
	s_add_i32 m0, s77, 0x2000
	s_nop 0
	global_load_lds_dwordx4 v[222:223], off
	v_lshl_add_u64 v[222:223], s[52:53], 0, v[128:129]
	s_mov_b32 m0, s57
	s_nop 0
	global_load_lds_dwordx4 v[222:223], off
	s_mov_b32 m0, s58
	s_nop 0
	global_load_lds_dwordx4 v[224:225], off
	s_waitcnt vmcnt(8)
	s_waitcnt lgkmcnt(0)
	s_barrier
	s_setprio 1
	s_waitcnt lgkmcnt(0)
	v_mfma_f32_16x16x32_bf16 v[60:63], v[152:155], v[188:191], v[60:63]
	v_mfma_f32_16x16x32_bf16 v[56:59], v[160:163], v[188:191], v[56:59]
	v_mfma_f32_16x16x32_bf16 v[44:47], v[160:163], v[196:199], v[44:47]
	v_mfma_f32_16x16x32_bf16 v[52:55], v[152:155], v[196:199], v[52:55]
	v_mfma_f32_16x16x32_bf16 v[36:39], v[152:155], v[204:207], v[36:39]
	v_mfma_f32_16x16x32_bf16 v[28:31], v[160:163], v[204:207], v[28:31]
	v_mfma_f32_16x16x32_bf16 v[12:15], v[160:163], v[212:215], v[12:15]
	v_mfma_f32_16x16x32_bf16 v[20:23], v[152:155], v[212:215], v[20:23]
	v_mfma_f32_16x16x32_bf16 v[60:63], v[156:159], v[192:195], v[60:63]
	v_mfma_f32_16x16x32_bf16 v[56:59], v[164:167], v[192:195], v[56:59]
	v_mfma_f32_16x16x32_bf16 v[44:47], v[164:167], v[200:203], v[44:47]
	v_mfma_f32_16x16x32_bf16 v[52:55], v[156:159], v[200:203], v[52:55]
	v_mfma_f32_16x16x32_bf16 v[36:39], v[156:159], v[208:211], v[36:39]
	v_mfma_f32_16x16x32_bf16 v[28:31], v[164:167], v[208:211], v[28:31]
	v_mfma_f32_16x16x32_bf16 v[12:15], v[164:167], v[216:219], v[12:15]
	v_mfma_f32_16x16x32_bf16 v[20:23], v[156:159], v[216:219], v[20:23]
	s_setprio 0
	s_setprio 1
	v_mfma_f32_16x16x32_bf16 v[48:51], v[168:171], v[188:191], v[48:51]
	v_mfma_f32_16x16x32_bf16 v[40:43], v[176:179], v[188:191], v[40:43]
	v_mfma_f32_16x16x32_bf16 v[24:27], v[176:179], v[196:199], v[24:27]
	v_mfma_f32_16x16x32_bf16 v[32:35], v[168:171], v[196:199], v[32:35]
	v_mfma_f32_16x16x32_bf16 v[16:19], v[168:171], v[204:207], v[16:19]
	v_mfma_f32_16x16x32_bf16 v[8:11], v[176:179], v[204:207], v[8:11]
	v_mfma_f32_16x16x32_bf16 v[0:3], v[176:179], v[212:215], v[0:3]
	v_mfma_f32_16x16x32_bf16 v[4:7], v[168:171], v[212:215], v[4:7]
	v_mfma_f32_16x16x32_bf16 v[48:51], v[172:175], v[192:195], v[48:51]
	v_mfma_f32_16x16x32_bf16 v[40:43], v[184:187], v[192:195], v[40:43]
	v_mfma_f32_16x16x32_bf16 v[24:27], v[184:187], v[200:203], v[24:27]
	v_mfma_f32_16x16x32_bf16 v[32:35], v[172:175], v[200:203], v[32:35]
	v_mfma_f32_16x16x32_bf16 v[16:19], v[172:175], v[208:211], v[16:19]
	v_mfma_f32_16x16x32_bf16 v[8:11], v[184:187], v[208:211], v[8:11]
	v_mfma_f32_16x16x32_bf16 v[0:3], v[184:187], v[216:219], v[0:3]
	v_mfma_f32_16x16x32_bf16 v[4:7], v[172:175], v[216:219], v[4:7]
	s_setprio 0
	s_barrier
	s_add_i32 s77, 0, 0x18000
	s_add_i32 s79, 0, 0x1c000
	v_add_u32_e32 v164, s77, v147
	v_add_u32_e32 v181, s79, v147
	ds_read_b128 v[152:155], v164
	ds_read_b128 v[156:159], v164 offset:1024
	ds_read_b128 v[160:163], v164 offset:2048
	ds_read_b128 v[164:167], v164 offset:3072
	ds_read_b128 v[168:171], v181
	ds_read_b128 v[172:175], v181 offset:1024
	ds_read_b128 v[176:179], v181 offset:2048
	ds_read_b128 v[184:187], v181 offset:3072
	s_add_u32 s46, s52, 0xb0000
	s_addc_u32 s47, s53, 0
	s_mov_b32 m0, s59
	v_lshl_add_u64 v[226:227], s[46:47], 0, v[128:129]
	ds_read_b128 v[188:191], v151 offset:32768
	ds_read_b128 v[192:195], v151 offset:33792
	ds_read_b128 v[196:199], v151 offset:34816
	ds_read_b128 v[200:203], v151 offset:35840
	ds_read_b128 v[204:207], v151 offset:36864
	ds_read_b128 v[208:211], v151 offset:37888
	ds_read_b128 v[212:215], v151 offset:38912
	ds_read_b128 v[216:219], v151 offset:39936
	global_load_lds_dwordx4 v[226:227], off
	v_lshl_add_u64 v[226:227], s[46:47], 0, v[132:133]
	s_mov_b32 m0, s60
	s_nop 0
	global_load_lds_dwordx4 v[226:227], off
	s_waitcnt vmcnt(8)
	s_waitcnt lgkmcnt(0)
	s_barrier
	s_setprio 1
	s_waitcnt lgkmcnt(0)
	v_mfma_f32_16x16x32_bf16 v[124:127], v[152:155], v[188:191], v[124:127]
	v_mfma_f32_16x16x32_bf16 v[120:123], v[160:163], v[188:191], v[120:123]
	v_mfma_f32_16x16x32_bf16 v[108:111], v[160:163], v[196:199], v[108:111]
	v_mfma_f32_16x16x32_bf16 v[116:119], v[152:155], v[196:199], v[116:119]
	v_mfma_f32_16x16x32_bf16 v[100:103], v[152:155], v[204:207], v[100:103]
	v_mfma_f32_16x16x32_bf16 v[92:95], v[160:163], v[204:207], v[92:95]
	v_mfma_f32_16x16x32_bf16 v[76:79], v[160:163], v[212:215], v[76:79]
	v_mfma_f32_16x16x32_bf16 v[84:87], v[152:155], v[212:215], v[84:87]
	v_mfma_f32_16x16x32_bf16 v[124:127], v[156:159], v[192:195], v[124:127]
	v_mfma_f32_16x16x32_bf16 v[120:123], v[164:167], v[192:195], v[120:123]
	v_mfma_f32_16x16x32_bf16 v[108:111], v[164:167], v[200:203], v[108:111]
	v_mfma_f32_16x16x32_bf16 v[116:119], v[156:159], v[200:203], v[116:119]
	v_mfma_f32_16x16x32_bf16 v[100:103], v[156:159], v[208:211], v[100:103]
	v_mfma_f32_16x16x32_bf16 v[92:95], v[164:167], v[208:211], v[92:95]
	v_mfma_f32_16x16x32_bf16 v[76:79], v[164:167], v[216:219], v[76:79]
	v_mfma_f32_16x16x32_bf16 v[84:87], v[156:159], v[216:219], v[84:87]
	s_setprio 0
	s_setprio 1
	v_mfma_f32_16x16x32_bf16 v[112:115], v[168:171], v[188:191], v[112:115]
	v_mfma_f32_16x16x32_bf16 v[104:107], v[176:179], v[188:191], v[104:107]
	v_mfma_f32_16x16x32_bf16 v[88:91], v[176:179], v[196:199], v[88:91]
	v_mfma_f32_16x16x32_bf16 v[96:99], v[168:171], v[196:199], v[96:99]
	v_mfma_f32_16x16x32_bf16 v[80:83], v[168:171], v[204:207], v[80:83]
	v_mfma_f32_16x16x32_bf16 v[72:75], v[176:179], v[204:207], v[72:75]
	v_mfma_f32_16x16x32_bf16 v[64:67], v[176:179], v[212:215], v[64:67]
	v_mfma_f32_16x16x32_bf16 v[68:71], v[168:171], v[212:215], v[68:71]
	v_mfma_f32_16x16x32_bf16 v[112:115], v[172:175], v[192:195], v[112:115]
	v_mfma_f32_16x16x32_bf16 v[104:107], v[184:187], v[192:195], v[104:107]
	v_mfma_f32_16x16x32_bf16 v[88:91], v[184:187], v[200:203], v[88:91]
	v_mfma_f32_16x16x32_bf16 v[96:99], v[172:175], v[200:203], v[96:99]
	v_mfma_f32_16x16x32_bf16 v[80:83], v[172:175], v[208:211], v[80:83]
	v_mfma_f32_16x16x32_bf16 v[72:75], v[184:187], v[208:211], v[72:75]
	v_mfma_f32_16x16x32_bf16 v[64:67], v[184:187], v[216:219], v[64:67]
	v_mfma_f32_16x16x32_bf16 v[68:71], v[172:175], v[216:219], v[68:71]
	s_setprio 0
	s_barrier
	s_add_i32 s46, s77, s56
	v_lshl_add_u64 v[144:145], v[144:145], 0, s[10:11]
	s_mov_b32 m0, s46
	ds_read_b128 v[188:191], v151 offset:49152
	ds_read_b128 v[192:195], v151 offset:50176
	ds_read_b128 v[196:199], v151 offset:51200
	ds_read_b128 v[200:203], v151 offset:52224
	ds_read_b128 v[204:207], v151 offset:53248
	ds_read_b128 v[208:211], v151 offset:54272
	ds_read_b128 v[212:215], v151 offset:55296
	ds_read_b128 v[216:219], v151 offset:56320
	global_load_lds_dwordx4 v[144:145], off
	s_add_i32 m0, s46, 0x2000
	s_add_u32 s46, s50, 0xb0080
	v_lshl_add_u64 v[144:145], v[220:221], 0, s[10:11]
	s_addc_u32 s47, s51, 0
	s_add_i32 s50, s79, s56
	global_load_lds_dwordx4 v[144:145], off
	v_lshl_add_u64 v[144:145], s[46:47], 0, v[130:131]
	s_mov_b32 m0, s50
	s_nop 0
	global_load_lds_dwordx4 v[144:145], off
	v_lshl_add_u64 v[144:145], s[46:47], 0, v[134:135]
	s_add_i32 m0, s50, 0x2000
	s_nop 0
	global_load_lds_dwordx4 v[144:145], off
	v_lshl_add_u64 v[144:145], v[222:223], 0, s[10:11]
	s_mov_b32 m0, s62
	s_nop 0
	global_load_lds_dwordx4 v[144:145], off
	v_lshl_add_u64 v[144:145], v[224:225], 0, s[10:11]
	s_mov_b32 m0, s63
	s_nop 0
	global_load_lds_dwordx4 v[144:145], off
	s_waitcnt vmcnt(8)
	s_waitcnt lgkmcnt(0)
	s_barrier
	s_setprio 1
	s_waitcnt lgkmcnt(0)
	v_mfma_f32_16x16x32_bf16 v[60:63], v[152:155], v[188:191], v[60:63]
	v_mfma_f32_16x16x32_bf16 v[56:59], v[160:163], v[188:191], v[56:59]
	v_mfma_f32_16x16x32_bf16 v[44:47], v[160:163], v[196:199], v[44:47]
	v_mfma_f32_16x16x32_bf16 v[52:55], v[152:155], v[196:199], v[52:55]
	v_mfma_f32_16x16x32_bf16 v[36:39], v[152:155], v[204:207], v[36:39]
	v_mfma_f32_16x16x32_bf16 v[28:31], v[160:163], v[204:207], v[28:31]
	v_mfma_f32_16x16x32_bf16 v[12:15], v[160:163], v[212:215], v[12:15]
	v_mfma_f32_16x16x32_bf16 v[20:23], v[152:155], v[212:215], v[20:23]
	v_mfma_f32_16x16x32_bf16 v[60:63], v[156:159], v[192:195], v[60:63]
	v_mfma_f32_16x16x32_bf16 v[56:59], v[164:167], v[192:195], v[56:59]
	v_mfma_f32_16x16x32_bf16 v[44:47], v[164:167], v[200:203], v[44:47]
	v_mfma_f32_16x16x32_bf16 v[52:55], v[156:159], v[200:203], v[52:55]
	v_mfma_f32_16x16x32_bf16 v[36:39], v[156:159], v[208:211], v[36:39]
	v_mfma_f32_16x16x32_bf16 v[28:31], v[164:167], v[208:211], v[28:31]
	v_mfma_f32_16x16x32_bf16 v[12:15], v[164:167], v[216:219], v[12:15]
	v_mfma_f32_16x16x32_bf16 v[20:23], v[156:159], v[216:219], v[20:23]
	s_setprio 0
	s_setprio 1
	v_mfma_f32_16x16x32_bf16 v[48:51], v[168:171], v[188:191], v[48:51]
	v_mfma_f32_16x16x32_bf16 v[40:43], v[176:179], v[188:191], v[40:43]
	v_mfma_f32_16x16x32_bf16 v[24:27], v[176:179], v[196:199], v[24:27]
	v_mfma_f32_16x16x32_bf16 v[32:35], v[168:171], v[196:199], v[32:35]
	v_mfma_f32_16x16x32_bf16 v[16:19], v[168:171], v[204:207], v[16:19]
	v_mfma_f32_16x16x32_bf16 v[8:11], v[176:179], v[204:207], v[8:11]
	v_mfma_f32_16x16x32_bf16 v[0:3], v[176:179], v[212:215], v[0:3]
	v_mfma_f32_16x16x32_bf16 v[4:7], v[168:171], v[212:215], v[4:7]
	v_mfma_f32_16x16x32_bf16 v[48:51], v[172:175], v[192:195], v[48:51]
	v_mfma_f32_16x16x32_bf16 v[40:43], v[184:187], v[192:195], v[40:43]
	v_mfma_f32_16x16x32_bf16 v[24:27], v[184:187], v[200:203], v[24:27]
	v_mfma_f32_16x16x32_bf16 v[32:35], v[172:175], v[200:203], v[32:35]
	v_mfma_f32_16x16x32_bf16 v[16:19], v[172:175], v[208:211], v[16:19]
	v_mfma_f32_16x16x32_bf16 v[8:11], v[184:187], v[208:211], v[8:11]
	v_mfma_f32_16x16x32_bf16 v[0:3], v[184:187], v[216:219], v[0:3]
	v_mfma_f32_16x16x32_bf16 v[4:7], v[172:175], v[216:219], v[4:7]
	s_setprio 0
	s_barrier
	s_add_i32 s76, s76, 2
	s_add_u32 s74, s74, 0x100
	s_addc_u32 s75, s75, 0
	s_cmp_gt_u32 s76, 41
	s_mov_b64 s[46:47], s[48:49]
	s_cbranch_scc0 .LBB0_1514
	s_and_b64 vcc, exec, s[12:13]
	s_cbranch_vccz .LBB0_1517
	s_barrier
